# phase 8 down-proj GEMM: third (partial) round split into 128x128 quarter tiles over all 256 CUs (K-loop copy skipping 3 of 4 MFMA blocks + quarter epilogues), on top of batched EpiRes epilogues
# speedup vs baseline: 1.0003x; 1.0003x over previous
; __device__ __forceinline__ unsigned cvt_pk_bf16(float lo, float hi) { unsigned r; asm volatile("v_cvt_pk_bf16_f32 %0, %1, %2" : "=v"(r) : "v"(lo), "v"(hi)); return r; }
;     __device__ __forceinline__ void operator()(const gacc_t (&acc)[2][2][4][2], const Unit& u, int wr, int wc, int fr, int fq) const {
;     ...
;             for (int m = 0; m < 4; ++m) { const int row = u.pm * 256 + ai * 128 + wr * 64 + m * 16 + fr;
;                 const float* bp = row < ML ? baseL + (size_t)row * D : baseC + (size_t)(row - ML) * D;
;                 const int mb = row < ML ? (row >> 11) : 8; const float* gp = mod + mb * MODW + chunk * D; float* op = out + (size_t)row * D;
;                 float sq = 0.f;
; #pragma unroll
;                 for (int bj = 0; bj < 2; ++bj)
; #pragma unroll
;                     for (int n = 0; n < 2; ++n) { const int col = u.pn * 256 + bj * 128 + wc * 32 + n * 16 + 4 * fq;
;                         const f32x4 b = *(const f32x4*)(bp + col), g = *(const f32x4*)(gp + col); const gacc_t a = acc[ai][bj][m][n];
;                         f32x4 o; o.x = b.x + g.x * a[0]; o.y = b.y + g.y * a[1]; o.z = b.z + g.z * a[2]; o.w = b.w + g.w * a[3];
;                         *(f32x4*)(op + col) = o;
;                         if (hu) { const f32x4 gg = *(const f32x4*)(gn + col), sc = *(const f32x4*)(scl + mb * MODW + col);
;                             sq += (o.x * o.x + o.y * o.y) + (o.z * o.z + o.w * o.w);
;                             u32x2 w; w.x = pg8::cvt_pk_bf16(o.x * gg.x * (1.f + sc.x), o.y * gg.y * (1.f + sc.y)); w.y = pg8::cvt_pk_bf16(o.z * gg.z * (1.f + sc.z), o.w * gg.w * (1.f + sc.w));
;                             *(u32x2*)(hu + (size_t)row * D + col) = w; } }
.LBB0_635:
	s_lshl_b32 s31, s46, 8
	s_add_i32 s31, s31, s70
	s_lshr_b32 s35, s31, 11
	s_mul_i32 s35, s35, 0xc000
	s_cmpk_gt_i32 s31, 0x3fff
	s_cselect_b32 s35, 0x60000, s35
	s_cselect_b32 s48, s68, s64
	s_cselect_b32 s49, s69, s65
	v_lshl_or_b32 v132, s44, 8, v152
	v_lshlrev_b32_e32 v132, 2, v132
	v_add_u32_e32 v222, s35, v132
	v_add_u32_e32 v223, s28, v222
	v_add_u32_e32 v220, s31, v150
	v_lshl_add_u32 v219, v220, 13, v132
	s_cselect_b32 s35, 0x8000000, 0
	s_sub_u32 s48, s48, s35
	s_subb_u32 s49, s49, 0
	v_mov_b32_e32 v218, v219
	global_load_dwordx4 v[142:145], v222, s[14:15] offset:0
	global_load_dwordx4 v[146:149], v222, s[14:15] offset:64
	global_load_dwordx4 v[176:179], v222, s[14:15] offset:512
	global_load_dwordx4 v[180:183], v222, s[14:15] offset:576
	global_load_dwordx4 v[186:189], v132, s[78:79] offset:0
	global_load_dwordx4 v[190:193], v132, s[78:79] offset:64
	global_load_dwordx4 v[194:197], v132, s[78:79] offset:512
	global_load_dwordx4 v[198:201], v132, s[78:79] offset:576
	global_load_dwordx4 v[160:163], v223, s[6:7] offset:0
	global_load_dwordx4 v[164:167], v223, s[6:7] offset:64
	global_load_dwordx4 v[168:171], v223, s[6:7] offset:512
	global_load_dwordx4 v[172:175], v223, s[6:7] offset:576
	global_load_dwordx4 v[202:205], v218, s[48:49] offset:0
	global_load_dwordx4 v[206:209], v218, s[48:49] offset:64
	global_load_dwordx4 v[210:213], v218, s[48:49] offset:512
	global_load_dwordx4 v[214:217], v218, s[48:49] offset:576
	v_add_u32_e32 v218, 0x20000, v218
	s_waitcnt vmcnt(8)
	v_add_f32_e32 v142, 1.0, v142
	v_add_f32_e32 v143, 1.0, v143
	v_add_f32_e32 v144, 1.0, v144
	v_add_f32_e32 v145, 1.0, v145
	v_add_f32_e32 v146, 1.0, v146
	v_add_f32_e32 v147, 1.0, v147
	v_add_f32_e32 v148, 1.0, v148
	v_add_f32_e32 v149, 1.0, v149
	v_add_f32_e32 v176, 1.0, v176
	v_add_f32_e32 v177, 1.0, v177
	v_add_f32_e32 v178, 1.0, v178
	v_add_f32_e32 v179, 1.0, v179
	v_add_f32_e32 v180, 1.0, v180
	v_add_f32_e32 v181, 1.0, v181
	v_add_f32_e32 v182, 1.0, v182
	v_add_f32_e32 v183, 1.0, v183
	v_mul_f32_e32 v186, v186, v142
	v_mul_f32_e32 v187, v187, v143
	v_mul_f32_e32 v188, v188, v144
	v_mul_f32_e32 v189, v189, v145
	v_mul_f32_e32 v190, v190, v146
	v_mul_f32_e32 v191, v191, v147
	v_mul_f32_e32 v192, v192, v148
	v_mul_f32_e32 v193, v193, v149
	v_mul_f32_e32 v194, v194, v176
	v_mul_f32_e32 v195, v195, v177
	v_mul_f32_e32 v196, v196, v178
	v_mul_f32_e32 v197, v197, v179
	v_mul_f32_e32 v198, v198, v180
	v_mul_f32_e32 v199, v199, v181
	v_mul_f32_e32 v200, v200, v182
	v_mul_f32_e32 v201, v201, v183
	global_load_dwordx4 v[142:145], v218, s[48:49] offset:0
	global_load_dwordx4 v[146:149], v218, s[48:49] offset:64
	global_load_dwordx4 v[176:179], v218, s[48:49] offset:512
	global_load_dwordx4 v[180:183], v218, s[48:49] offset:576
	v_add_u32_e32 v218, 0x20000, v218
	s_waitcnt vmcnt(4)
	v_pk_fma_f32 v[126:127], v[126:127], v[162:163], v[204:205]
	v_pk_fma_f32 v[124:125], v[124:125], v[160:161], v[202:203]
	global_store_dwordx4 v219, v[124:127], s[8:9] offset:0
	v_pk_fma_f32 v[122:123], v[122:123], v[166:167], v[208:209]
	v_pk_fma_f32 v[120:121], v[120:121], v[164:165], v[206:207]
	global_store_dwordx4 v219, v[120:123], s[8:9] offset:64
	v_pk_fma_f32 v[118:119], v[118:119], v[170:171], v[212:213]
	v_pk_fma_f32 v[116:117], v[116:117], v[168:169], v[210:211]
	global_store_dwordx4 v219, v[116:119], s[8:9] offset:512
	v_pk_fma_f32 v[114:115], v[114:115], v[174:175], v[216:217]
	v_pk_fma_f32 v[112:113], v[112:113], v[172:173], v[214:215]
	global_store_dwordx4 v219, v[112:115], s[8:9] offset:576
	v_lshrrev_b32_e32 v220, 1, v219
	v_mul_f32_e32 v202, v124, v186
	v_mul_f32_e32 v203, v125, v187
	v_mul_f32_e32 v204, v126, v188
	v_mul_f32_e32 v205, v127, v189
	v_mul_f32_e32 v221, v124, v124
	v_fmac_f32_e32 v221, v125, v125
	v_fmac_f32_e32 v221, v126, v126
	v_fmac_f32_e32 v221, v127, v127
	v_cvt_pk_bf16_f32 v202, v202, v203
	v_cvt_pk_bf16_f32 v203, v204, v205
	global_store_dwordx2 v220, v[202:203], s[10:11] offset:0
	v_mul_f32_e32 v206, v120, v190
	v_mul_f32_e32 v207, v121, v191
	v_mul_f32_e32 v208, v122, v192
	v_mul_f32_e32 v209, v123, v193
	v_fmac_f32_e32 v221, v120, v120
	v_fmac_f32_e32 v221, v121, v121
	v_fmac_f32_e32 v221, v122, v122
	v_fmac_f32_e32 v221, v123, v123
	v_cvt_pk_bf16_f32 v206, v206, v207
	v_cvt_pk_bf16_f32 v207, v208, v209
	global_store_dwordx2 v220, v[206:207], s[10:11] offset:32
	v_mul_f32_e32 v210, v116, v194
	v_mul_f32_e32 v211, v117, v195
	v_mul_f32_e32 v212, v118, v196
	v_mul_f32_e32 v213, v119, v197
	v_fmac_f32_e32 v221, v116, v116
	v_fmac_f32_e32 v221, v117, v117
	v_fmac_f32_e32 v221, v118, v118
	v_fmac_f32_e32 v221, v119, v119
	v_cvt_pk_bf16_f32 v210, v210, v211
	v_cvt_pk_bf16_f32 v211, v212, v213
	global_store_dwordx2 v220, v[210:211], s[10:11] offset:256
	v_mul_f32_e32 v214, v112, v198
	v_mul_f32_e32 v215, v113, v199
	v_mul_f32_e32 v216, v114, v200
	v_mul_f32_e32 v217, v115, v201
	v_fmac_f32_e32 v221, v112, v112
	v_fmac_f32_e32 v221, v113, v113
	v_fmac_f32_e32 v221, v114, v114
	v_fmac_f32_e32 v221, v115, v115
	v_cvt_pk_bf16_f32 v214, v214, v215
	v_cvt_pk_bf16_f32 v215, v216, v217
	global_store_dwordx2 v220, v[214:215], s[10:11] offset:288
	v_mov_b32_e32 v124, v221
	global_load_dwordx4 v[202:205], v218, s[48:49] offset:0
	global_load_dwordx4 v[206:209], v218, s[48:49] offset:64
	global_load_dwordx4 v[210:213], v218, s[48:49] offset:512
	global_load_dwordx4 v[214:217], v218, s[48:49] offset:576
	v_add_u32_e32 v218, 0x20000, v218
	v_add_u32_e32 v219, 0x20000, v219
	s_waitcnt vmcnt(12)
; __device__ __forceinline__ unsigned cvt_pk_bf16(float lo, float hi) { unsigned r; asm volatile("v_cvt_pk_bf16_f32 %0, %1, %2" : "=v"(r) : "v"(lo), "v"(hi)); return r; }
;     __device__ __forceinline__ void operator()(const gacc_t (&acc)[2][2][4][2], const Unit& u, int wr, int wc, int fr, int fq) const {
;     ...
;                 for (int bj = 0; bj < 2; ++bj)
; #pragma unroll
;                     for (int n = 0; n < 2; ++n) { const int col = u.pn * 256 + bj * 128 + wc * 32 + n * 16 + 4 * fq;
;                         const f32x4 b = *(const f32x4*)(bp + col), g = *(const f32x4*)(gp + col); const gacc_t a = acc[ai][bj][m][n];
;                         f32x4 o; o.x = b.x + g.x * a[0]; o.y = b.y + g.y * a[1]; o.z = b.z + g.z * a[2]; o.w = b.w + g.w * a[3];
;                         *(f32x4*)(op + col) = o;
;                         if (hu) { const f32x4 gg = *(const f32x4*)(gn + col), sc = *(const f32x4*)(scl + mb * MODW + col);
;                             sq += (o.x * o.x + o.y * o.y) + (o.z * o.z + o.w * o.w);
;                             u32x2 w; w.x = pg8::cvt_pk_bf16(o.x * gg.x * (1.f + sc.x), o.y * gg.y * (1.f + sc.y)); w.y = pg8::cvt_pk_bf16(o.z * gg.z * (1.f + sc.z), o.w * gg.w * (1.f + sc.w));
;                             *(u32x2*)(hu + (size_t)row * D + col) = w; } }
	v_pk_fma_f32 v[110:111], v[110:111], v[162:163], v[144:145]
	v_pk_fma_f32 v[108:109], v[108:109], v[160:161], v[142:143]
	global_store_dwordx4 v219, v[108:111], s[8:9] offset:0
	v_pk_fma_f32 v[106:107], v[106:107], v[166:167], v[148:149]
	v_pk_fma_f32 v[104:105], v[104:105], v[164:165], v[146:147]
	global_store_dwordx4 v219, v[104:107], s[8:9] offset:64
	v_pk_fma_f32 v[102:103], v[102:103], v[170:171], v[178:179]
	v_pk_fma_f32 v[100:101], v[100:101], v[168:169], v[176:177]
	global_store_dwordx4 v219, v[100:103], s[8:9] offset:512
	v_pk_fma_f32 v[98:99], v[98:99], v[174:175], v[182:183]
	v_pk_fma_f32 v[96:97], v[96:97], v[172:173], v[180:181]
	global_store_dwordx4 v219, v[96:99], s[8:9] offset:576
	v_lshrrev_b32_e32 v220, 1, v219
	v_mul_f32_e32 v142, v108, v186
	v_mul_f32_e32 v143, v109, v187
	v_mul_f32_e32 v144, v110, v188
	v_mul_f32_e32 v145, v111, v189
	v_mul_f32_e32 v221, v108, v108
	v_fmac_f32_e32 v221, v109, v109
	v_fmac_f32_e32 v221, v110, v110
	v_fmac_f32_e32 v221, v111, v111
	v_cvt_pk_bf16_f32 v142, v142, v143
	v_cvt_pk_bf16_f32 v143, v144, v145
	global_store_dwordx2 v220, v[142:143], s[10:11] offset:0
	v_mul_f32_e32 v146, v104, v190
	v_mul_f32_e32 v147, v105, v191
	v_mul_f32_e32 v148, v106, v192
	v_mul_f32_e32 v149, v107, v193
	v_fmac_f32_e32 v221, v104, v104
	v_fmac_f32_e32 v221, v105, v105
	v_fmac_f32_e32 v221, v106, v106
	v_fmac_f32_e32 v221, v107, v107
	v_cvt_pk_bf16_f32 v146, v146, v147
	v_cvt_pk_bf16_f32 v147, v148, v149
	global_store_dwordx2 v220, v[146:147], s[10:11] offset:32
	v_mul_f32_e32 v176, v100, v194
	v_mul_f32_e32 v177, v101, v195
	v_mul_f32_e32 v178, v102, v196
	v_mul_f32_e32 v179, v103, v197
	v_fmac_f32_e32 v221, v100, v100
	v_fmac_f32_e32 v221, v101, v101
	v_fmac_f32_e32 v221, v102, v102
	v_fmac_f32_e32 v221, v103, v103
	v_cvt_pk_bf16_f32 v176, v176, v177
	v_cvt_pk_bf16_f32 v177, v178, v179
	global_store_dwordx2 v220, v[176:177], s[10:11] offset:256
	v_mul_f32_e32 v180, v96, v198
	v_mul_f32_e32 v181, v97, v199
	v_mul_f32_e32 v182, v98, v200
	v_mul_f32_e32 v183, v99, v201
	v_fmac_f32_e32 v221, v96, v96
	v_fmac_f32_e32 v221, v97, v97
	v_fmac_f32_e32 v221, v98, v98
	v_fmac_f32_e32 v221, v99, v99
	v_cvt_pk_bf16_f32 v180, v180, v181
	v_cvt_pk_bf16_f32 v181, v182, v183
	global_store_dwordx2 v220, v[180:181], s[10:11] offset:288
	v_mov_b32_e32 v108, v221
	global_load_dwordx4 v[142:145], v218, s[48:49] offset:0
	global_load_dwordx4 v[146:149], v218, s[48:49] offset:64
	global_load_dwordx4 v[176:179], v218, s[48:49] offset:512
	global_load_dwordx4 v[180:183], v218, s[48:49] offset:576
	v_add_u32_e32 v218, 0xa0000, v218
	v_add_u32_e32 v219, 0x20000, v219
	s_waitcnt vmcnt(12)
	v_pk_fma_f32 v[94:95], v[94:95], v[162:163], v[204:205]
	v_pk_fma_f32 v[92:93], v[92:93], v[160:161], v[202:203]
	global_store_dwordx4 v219, v[92:95], s[8:9] offset:0
	v_pk_fma_f32 v[90:91], v[90:91], v[166:167], v[208:209]
	v_pk_fma_f32 v[88:89], v[88:89], v[164:165], v[206:207]
	global_store_dwordx4 v219, v[88:91], s[8:9] offset:64
	v_pk_fma_f32 v[86:87], v[86:87], v[170:171], v[212:213]
	v_pk_fma_f32 v[84:85], v[84:85], v[168:169], v[210:211]
	global_store_dwordx4 v219, v[84:87], s[8:9] offset:512
	v_pk_fma_f32 v[82:83], v[82:83], v[174:175], v[216:217]
	v_pk_fma_f32 v[80:81], v[80:81], v[172:173], v[214:215]
	global_store_dwordx4 v219, v[80:83], s[8:9] offset:576
	v_lshrrev_b32_e32 v220, 1, v219
	v_mul_f32_e32 v202, v92, v186
	v_mul_f32_e32 v203, v93, v187
	v_mul_f32_e32 v204, v94, v188
	v_mul_f32_e32 v205, v95, v189
	v_mul_f32_e32 v221, v92, v92
	v_fmac_f32_e32 v221, v93, v93
	v_fmac_f32_e32 v221, v94, v94
	v_fmac_f32_e32 v221, v95, v95
	v_cvt_pk_bf16_f32 v202, v202, v203
	v_cvt_pk_bf16_f32 v203, v204, v205
	global_store_dwordx2 v220, v[202:203], s[10:11] offset:0
	v_mul_f32_e32 v206, v88, v190
	v_mul_f32_e32 v207, v89, v191
	v_mul_f32_e32 v208, v90, v192
	v_mul_f32_e32 v209, v91, v193
	v_fmac_f32_e32 v221, v88, v88
	v_fmac_f32_e32 v221, v89, v89
	v_fmac_f32_e32 v221, v90, v90
	v_fmac_f32_e32 v221, v91, v91
	v_cvt_pk_bf16_f32 v206, v206, v207
	v_cvt_pk_bf16_f32 v207, v208, v209
	global_store_dwordx2 v220, v[206:207], s[10:11] offset:32
	v_mul_f32_e32 v210, v84, v194
	v_mul_f32_e32 v211, v85, v195
	v_mul_f32_e32 v212, v86, v196
	v_mul_f32_e32 v213, v87, v197
	v_fmac_f32_e32 v221, v84, v84
	v_fmac_f32_e32 v221, v85, v85
	v_fmac_f32_e32 v221, v86, v86
	v_fmac_f32_e32 v221, v87, v87
	v_cvt_pk_bf16_f32 v210, v210, v211
	v_cvt_pk_bf16_f32 v211, v212, v213
	global_store_dwordx2 v220, v[210:211], s[10:11] offset:256
	v_mul_f32_e32 v214, v80, v198
	v_mul_f32_e32 v215, v81, v199
	v_mul_f32_e32 v216, v82, v200
	v_mul_f32_e32 v217, v83, v201
	v_fmac_f32_e32 v221, v80, v80
	v_fmac_f32_e32 v221, v81, v81
	v_fmac_f32_e32 v221, v82, v82
	v_fmac_f32_e32 v221, v83, v83
	v_cvt_pk_bf16_f32 v214, v214, v215
	v_cvt_pk_bf16_f32 v215, v216, v217
	global_store_dwordx2 v220, v[214:215], s[10:11] offset:288
	v_mov_b32_e32 v92, v221
	global_load_dwordx4 v[202:205], v218, s[48:49] offset:0
	global_load_dwordx4 v[206:209], v218, s[48:49] offset:64
	global_load_dwordx4 v[210:213], v218, s[48:49] offset:512
	global_load_dwordx4 v[214:217], v218, s[48:49] offset:576
	v_add_u32_e32 v218, 0x20000, v218
	v_add_u32_e32 v219, 0x20000, v219
	s_waitcnt vmcnt(12)
; __device__ __forceinline__ unsigned cvt_pk_bf16(float lo, float hi) { unsigned r; asm volatile("v_cvt_pk_bf16_f32 %0, %1, %2" : "=v"(r) : "v"(lo), "v"(hi)); return r; }
;     __device__ __forceinline__ void operator()(const gacc_t (&acc)[2][2][4][2], const Unit& u, int wr, int wc, int fr, int fq) const {
;     ...
;                 for (int bj = 0; bj < 2; ++bj)
; #pragma unroll
;                     for (int n = 0; n < 2; ++n) { const int col = u.pn * 256 + bj * 128 + wc * 32 + n * 16 + 4 * fq;
;                         const f32x4 b = *(const f32x4*)(bp + col), g = *(const f32x4*)(gp + col); const gacc_t a = acc[ai][bj][m][n];
;                         f32x4 o; o.x = b.x + g.x * a[0]; o.y = b.y + g.y * a[1]; o.z = b.z + g.z * a[2]; o.w = b.w + g.w * a[3];
;                         *(f32x4*)(op + col) = o;
;                         if (hu) { const f32x4 gg = *(const f32x4*)(gn + col), sc = *(const f32x4*)(scl + mb * MODW + col);
;                             sq += (o.x * o.x + o.y * o.y) + (o.z * o.z + o.w * o.w);
;                             u32x2 w; w.x = pg8::cvt_pk_bf16(o.x * gg.x * (1.f + sc.x), o.y * gg.y * (1.f + sc.y)); w.y = pg8::cvt_pk_bf16(o.z * gg.z * (1.f + sc.z), o.w * gg.w * (1.f + sc.w));
;                             *(u32x2*)(hu + (size_t)row * D + col) = w; } }
	v_pk_fma_f32 v[78:79], v[78:79], v[162:163], v[144:145]
	v_pk_fma_f32 v[76:77], v[76:77], v[160:161], v[142:143]
	global_store_dwordx4 v219, v[76:79], s[8:9] offset:0
	v_pk_fma_f32 v[74:75], v[74:75], v[166:167], v[148:149]
	v_pk_fma_f32 v[72:73], v[72:73], v[164:165], v[146:147]
	global_store_dwordx4 v219, v[72:75], s[8:9] offset:64
	v_pk_fma_f32 v[70:71], v[70:71], v[170:171], v[178:179]
	v_pk_fma_f32 v[68:69], v[68:69], v[168:169], v[176:177]
	global_store_dwordx4 v219, v[68:71], s[8:9] offset:512
	v_pk_fma_f32 v[66:67], v[66:67], v[174:175], v[182:183]
	v_pk_fma_f32 v[64:65], v[64:65], v[172:173], v[180:181]
	global_store_dwordx4 v219, v[64:67], s[8:9] offset:576
	v_lshrrev_b32_e32 v220, 1, v219
	v_mul_f32_e32 v142, v76, v186
	v_mul_f32_e32 v143, v77, v187
	v_mul_f32_e32 v144, v78, v188
	v_mul_f32_e32 v145, v79, v189
	v_mul_f32_e32 v221, v76, v76
	v_fmac_f32_e32 v221, v77, v77
	v_fmac_f32_e32 v221, v78, v78
	v_fmac_f32_e32 v221, v79, v79
	v_cvt_pk_bf16_f32 v142, v142, v143
	v_cvt_pk_bf16_f32 v143, v144, v145
	global_store_dwordx2 v220, v[142:143], s[10:11] offset:0
	v_mul_f32_e32 v146, v72, v190
	v_mul_f32_e32 v147, v73, v191
	v_mul_f32_e32 v148, v74, v192
	v_mul_f32_e32 v149, v75, v193
	v_fmac_f32_e32 v221, v72, v72
	v_fmac_f32_e32 v221, v73, v73
	v_fmac_f32_e32 v221, v74, v74
	v_fmac_f32_e32 v221, v75, v75
	v_cvt_pk_bf16_f32 v146, v146, v147
	v_cvt_pk_bf16_f32 v147, v148, v149
	global_store_dwordx2 v220, v[146:147], s[10:11] offset:32
	v_mul_f32_e32 v176, v68, v194
	v_mul_f32_e32 v177, v69, v195
	v_mul_f32_e32 v178, v70, v196
	v_mul_f32_e32 v179, v71, v197
	v_fmac_f32_e32 v221, v68, v68
	v_fmac_f32_e32 v221, v69, v69
	v_fmac_f32_e32 v221, v70, v70
	v_fmac_f32_e32 v221, v71, v71
	v_cvt_pk_bf16_f32 v176, v176, v177
	v_cvt_pk_bf16_f32 v177, v178, v179
	global_store_dwordx2 v220, v[176:177], s[10:11] offset:256
	v_mul_f32_e32 v180, v64, v198
	v_mul_f32_e32 v181, v65, v199
	v_mul_f32_e32 v182, v66, v200
	v_mul_f32_e32 v183, v67, v201
	v_fmac_f32_e32 v221, v64, v64
	v_fmac_f32_e32 v221, v65, v65
	v_fmac_f32_e32 v221, v66, v66
	v_fmac_f32_e32 v221, v67, v67
	v_cvt_pk_bf16_f32 v180, v180, v181
	v_cvt_pk_bf16_f32 v181, v182, v183
	global_store_dwordx2 v220, v[180:181], s[10:11] offset:288
	v_mov_b32_e32 v76, v221
	global_load_dwordx4 v[142:145], v218, s[48:49] offset:0
	global_load_dwordx4 v[146:149], v218, s[48:49] offset:64
	global_load_dwordx4 v[176:179], v218, s[48:49] offset:512
	global_load_dwordx4 v[180:183], v218, s[48:49] offset:576
	v_add_u32_e32 v218, 0x20000, v218
	v_add_u32_e32 v219, 0xa0000, v219
	s_waitcnt vmcnt(12)
	v_pk_fma_f32 v[62:63], v[62:63], v[162:163], v[204:205]
	v_pk_fma_f32 v[60:61], v[60:61], v[160:161], v[202:203]
	global_store_dwordx4 v219, v[60:63], s[8:9] offset:0
	v_pk_fma_f32 v[58:59], v[58:59], v[166:167], v[208:209]
	v_pk_fma_f32 v[56:57], v[56:57], v[164:165], v[206:207]
	global_store_dwordx4 v219, v[56:59], s[8:9] offset:64
	v_pk_fma_f32 v[54:55], v[54:55], v[170:171], v[212:213]
	v_pk_fma_f32 v[52:53], v[52:53], v[168:169], v[210:211]
	global_store_dwordx4 v219, v[52:55], s[8:9] offset:512
	v_pk_fma_f32 v[50:51], v[50:51], v[174:175], v[216:217]
	v_pk_fma_f32 v[48:49], v[48:49], v[172:173], v[214:215]
	global_store_dwordx4 v219, v[48:51], s[8:9] offset:576
	v_lshrrev_b32_e32 v220, 1, v219
	v_mul_f32_e32 v202, v60, v186
	v_mul_f32_e32 v203, v61, v187
	v_mul_f32_e32 v204, v62, v188
	v_mul_f32_e32 v205, v63, v189
	v_mul_f32_e32 v221, v60, v60
	v_fmac_f32_e32 v221, v61, v61
	v_fmac_f32_e32 v221, v62, v62
	v_fmac_f32_e32 v221, v63, v63
	v_cvt_pk_bf16_f32 v202, v202, v203
	v_cvt_pk_bf16_f32 v203, v204, v205
	global_store_dwordx2 v220, v[202:203], s[10:11] offset:0
	v_mul_f32_e32 v206, v56, v190
	v_mul_f32_e32 v207, v57, v191
	v_mul_f32_e32 v208, v58, v192
	v_mul_f32_e32 v209, v59, v193
	v_fmac_f32_e32 v221, v56, v56
	v_fmac_f32_e32 v221, v57, v57
	v_fmac_f32_e32 v221, v58, v58
	v_fmac_f32_e32 v221, v59, v59
	v_cvt_pk_bf16_f32 v206, v206, v207
	v_cvt_pk_bf16_f32 v207, v208, v209
	global_store_dwordx2 v220, v[206:207], s[10:11] offset:32
	v_mul_f32_e32 v210, v52, v194
	v_mul_f32_e32 v211, v53, v195
	v_mul_f32_e32 v212, v54, v196
	v_mul_f32_e32 v213, v55, v197
	v_fmac_f32_e32 v221, v52, v52
	v_fmac_f32_e32 v221, v53, v53
	v_fmac_f32_e32 v221, v54, v54
	v_fmac_f32_e32 v221, v55, v55
	v_cvt_pk_bf16_f32 v210, v210, v211
	v_cvt_pk_bf16_f32 v211, v212, v213
	global_store_dwordx2 v220, v[210:211], s[10:11] offset:256
	v_mul_f32_e32 v214, v48, v198
	v_mul_f32_e32 v215, v49, v199
	v_mul_f32_e32 v216, v50, v200
	v_mul_f32_e32 v217, v51, v201
	v_fmac_f32_e32 v221, v48, v48
	v_fmac_f32_e32 v221, v49, v49
	v_fmac_f32_e32 v221, v50, v50
	v_fmac_f32_e32 v221, v51, v51
	v_cvt_pk_bf16_f32 v214, v214, v215
	v_cvt_pk_bf16_f32 v215, v216, v217
	global_store_dwordx2 v220, v[214:215], s[10:11] offset:288
	v_mov_b32_e32 v60, v221
	global_load_dwordx4 v[202:205], v218, s[48:49] offset:0
	global_load_dwordx4 v[206:209], v218, s[48:49] offset:64
	global_load_dwordx4 v[210:213], v218, s[48:49] offset:512
	global_load_dwordx4 v[214:217], v218, s[48:49] offset:576
	v_add_u32_e32 v218, 0x20000, v218
	v_add_u32_e32 v219, 0x20000, v219
	s_waitcnt vmcnt(12)
; __device__ __forceinline__ unsigned cvt_pk_bf16(float lo, float hi) { unsigned r; asm volatile("v_cvt_pk_bf16_f32 %0, %1, %2" : "=v"(r) : "v"(lo), "v"(hi)); return r; }
;     __device__ __forceinline__ void operator()(const gacc_t (&acc)[2][2][4][2], const Unit& u, int wr, int wc, int fr, int fq) const {
;     ...
;                 for (int bj = 0; bj < 2; ++bj)
; #pragma unroll
;                     for (int n = 0; n < 2; ++n) { const int col = u.pn * 256 + bj * 128 + wc * 32 + n * 16 + 4 * fq;
;                         const f32x4 b = *(const f32x4*)(bp + col), g = *(const f32x4*)(gp + col); const gacc_t a = acc[ai][bj][m][n];
;                         f32x4 o; o.x = b.x + g.x * a[0]; o.y = b.y + g.y * a[1]; o.z = b.z + g.z * a[2]; o.w = b.w + g.w * a[3];
;                         *(f32x4*)(op + col) = o;
;                         if (hu) { const f32x4 gg = *(const f32x4*)(gn + col), sc = *(const f32x4*)(scl + mb * MODW + col);
;                             sq += (o.x * o.x + o.y * o.y) + (o.z * o.z + o.w * o.w);
;                             u32x2 w; w.x = pg8::cvt_pk_bf16(o.x * gg.x * (1.f + sc.x), o.y * gg.y * (1.f + sc.y)); w.y = pg8::cvt_pk_bf16(o.z * gg.z * (1.f + sc.z), o.w * gg.w * (1.f + sc.w));
;                             *(u32x2*)(hu + (size_t)row * D + col) = w; } }
	v_pk_fma_f32 v[46:47], v[46:47], v[162:163], v[144:145]
	v_pk_fma_f32 v[44:45], v[44:45], v[160:161], v[142:143]
	global_store_dwordx4 v219, v[44:47], s[8:9] offset:0
	v_pk_fma_f32 v[42:43], v[42:43], v[166:167], v[148:149]
	v_pk_fma_f32 v[40:41], v[40:41], v[164:165], v[146:147]
	global_store_dwordx4 v219, v[40:43], s[8:9] offset:64
	v_pk_fma_f32 v[38:39], v[38:39], v[170:171], v[178:179]
	v_pk_fma_f32 v[36:37], v[36:37], v[168:169], v[176:177]
	global_store_dwordx4 v219, v[36:39], s[8:9] offset:512
	v_pk_fma_f32 v[34:35], v[34:35], v[174:175], v[182:183]
	v_pk_fma_f32 v[32:33], v[32:33], v[172:173], v[180:181]
	global_store_dwordx4 v219, v[32:35], s[8:9] offset:576
	v_lshrrev_b32_e32 v220, 1, v219
	v_mul_f32_e32 v142, v44, v186
	v_mul_f32_e32 v143, v45, v187
	v_mul_f32_e32 v144, v46, v188
	v_mul_f32_e32 v145, v47, v189
	v_mul_f32_e32 v221, v44, v44
	v_fmac_f32_e32 v221, v45, v45
	v_fmac_f32_e32 v221, v46, v46
	v_fmac_f32_e32 v221, v47, v47
	v_cvt_pk_bf16_f32 v142, v142, v143
	v_cvt_pk_bf16_f32 v143, v144, v145
	global_store_dwordx2 v220, v[142:143], s[10:11] offset:0
	v_mul_f32_e32 v146, v40, v190
	v_mul_f32_e32 v147, v41, v191
	v_mul_f32_e32 v148, v42, v192
	v_mul_f32_e32 v149, v43, v193
	v_fmac_f32_e32 v221, v40, v40
	v_fmac_f32_e32 v221, v41, v41
	v_fmac_f32_e32 v221, v42, v42
	v_fmac_f32_e32 v221, v43, v43
	v_cvt_pk_bf16_f32 v146, v146, v147
	v_cvt_pk_bf16_f32 v147, v148, v149
	global_store_dwordx2 v220, v[146:147], s[10:11] offset:32
	v_mul_f32_e32 v176, v36, v194
	v_mul_f32_e32 v177, v37, v195
	v_mul_f32_e32 v178, v38, v196
	v_mul_f32_e32 v179, v39, v197
	v_fmac_f32_e32 v221, v36, v36
	v_fmac_f32_e32 v221, v37, v37
	v_fmac_f32_e32 v221, v38, v38
	v_fmac_f32_e32 v221, v39, v39
	v_cvt_pk_bf16_f32 v176, v176, v177
	v_cvt_pk_bf16_f32 v177, v178, v179
	global_store_dwordx2 v220, v[176:177], s[10:11] offset:256
	v_mul_f32_e32 v180, v32, v198
	v_mul_f32_e32 v181, v33, v199
	v_mul_f32_e32 v182, v34, v200
	v_mul_f32_e32 v183, v35, v201
	v_fmac_f32_e32 v221, v32, v32
	v_fmac_f32_e32 v221, v33, v33
	v_fmac_f32_e32 v221, v34, v34
	v_fmac_f32_e32 v221, v35, v35
	v_cvt_pk_bf16_f32 v180, v180, v181
	v_cvt_pk_bf16_f32 v181, v182, v183
	global_store_dwordx2 v220, v[180:181], s[10:11] offset:288
	v_mov_b32_e32 v44, v221
	global_load_dwordx4 v[142:145], v218, s[48:49] offset:0
	global_load_dwordx4 v[146:149], v218, s[48:49] offset:64
	global_load_dwordx4 v[176:179], v218, s[48:49] offset:512
	global_load_dwordx4 v[180:183], v218, s[48:49] offset:576
	v_add_u32_e32 v219, 0x20000, v219
	s_waitcnt vmcnt(12)
	v_pk_fma_f32 v[30:31], v[30:31], v[162:163], v[204:205]
	v_pk_fma_f32 v[28:29], v[28:29], v[160:161], v[202:203]
	global_store_dwordx4 v219, v[28:31], s[8:9] offset:0
	v_pk_fma_f32 v[26:27], v[26:27], v[166:167], v[208:209]
	v_pk_fma_f32 v[24:25], v[24:25], v[164:165], v[206:207]
	global_store_dwordx4 v219, v[24:27], s[8:9] offset:64
	v_pk_fma_f32 v[22:23], v[22:23], v[170:171], v[212:213]
	v_pk_fma_f32 v[20:21], v[20:21], v[168:169], v[210:211]
	global_store_dwordx4 v219, v[20:23], s[8:9] offset:512
	v_pk_fma_f32 v[18:19], v[18:19], v[174:175], v[216:217]
	v_pk_fma_f32 v[16:17], v[16:17], v[172:173], v[214:215]
	global_store_dwordx4 v219, v[16:19], s[8:9] offset:576
	v_lshrrev_b32_e32 v220, 1, v219
	v_mul_f32_e32 v202, v28, v186
	v_mul_f32_e32 v203, v29, v187
	v_mul_f32_e32 v204, v30, v188
	v_mul_f32_e32 v205, v31, v189
	v_mul_f32_e32 v221, v28, v28
	v_fmac_f32_e32 v221, v29, v29
	v_fmac_f32_e32 v221, v30, v30
	v_fmac_f32_e32 v221, v31, v31
	v_cvt_pk_bf16_f32 v202, v202, v203
	v_cvt_pk_bf16_f32 v203, v204, v205
	global_store_dwordx2 v220, v[202:203], s[10:11] offset:0
	v_mul_f32_e32 v206, v24, v190
	v_mul_f32_e32 v207, v25, v191
	v_mul_f32_e32 v208, v26, v192
	v_mul_f32_e32 v209, v27, v193
	v_fmac_f32_e32 v221, v24, v24
	v_fmac_f32_e32 v221, v25, v25
	v_fmac_f32_e32 v221, v26, v26
	v_fmac_f32_e32 v221, v27, v27
	v_cvt_pk_bf16_f32 v206, v206, v207
	v_cvt_pk_bf16_f32 v207, v208, v209
	global_store_dwordx2 v220, v[206:207], s[10:11] offset:32
	v_mul_f32_e32 v210, v20, v194
	v_mul_f32_e32 v211, v21, v195
	v_mul_f32_e32 v212, v22, v196
	v_mul_f32_e32 v213, v23, v197
	v_fmac_f32_e32 v221, v20, v20
	v_fmac_f32_e32 v221, v21, v21
	v_fmac_f32_e32 v221, v22, v22
	v_fmac_f32_e32 v221, v23, v23
	v_cvt_pk_bf16_f32 v210, v210, v211
	v_cvt_pk_bf16_f32 v211, v212, v213
	global_store_dwordx2 v220, v[210:211], s[10:11] offset:256
	v_mul_f32_e32 v214, v16, v198
	v_mul_f32_e32 v215, v17, v199
	v_mul_f32_e32 v216, v18, v200
	v_mul_f32_e32 v217, v19, v201
	v_fmac_f32_e32 v221, v16, v16
	v_fmac_f32_e32 v221, v17, v17
	v_fmac_f32_e32 v221, v18, v18
	v_fmac_f32_e32 v221, v19, v19
	v_cvt_pk_bf16_f32 v214, v214, v215
	v_cvt_pk_bf16_f32 v215, v216, v217
	global_store_dwordx2 v220, v[214:215], s[10:11] offset:288
	v_mov_b32_e32 v28, v221
	v_add_u32_e32 v219, 0x20000, v219
	s_waitcnt vmcnt(8)
; __device__ __forceinline__ unsigned cvt_pk_bf16(float lo, float hi) { unsigned r; asm volatile("v_cvt_pk_bf16_f32 %0, %1, %2" : "=v"(r) : "v"(lo), "v"(hi)); return r; }
;     __device__ __forceinline__ void operator()(const gacc_t (&acc)[2][2][4][2], const Unit& u, int wr, int wc, int fr, int fq) const {
;     ...
;                 for (int bj = 0; bj < 2; ++bj)
; #pragma unroll
;                     for (int n = 0; n < 2; ++n) { const int col = u.pn * 256 + bj * 128 + wc * 32 + n * 16 + 4 * fq;
;                         const f32x4 b = *(const f32x4*)(bp + col), g = *(const f32x4*)(gp + col); const gacc_t a = acc[ai][bj][m][n];
;                         f32x4 o; o.x = b.x + g.x * a[0]; o.y = b.y + g.y * a[1]; o.z = b.z + g.z * a[2]; o.w = b.w + g.w * a[3];
;                         *(f32x4*)(op + col) = o;
;                         if (hu) { const f32x4 gg = *(const f32x4*)(gn + col), sc = *(const f32x4*)(scl + mb * MODW + col);
;                             sq += (o.x * o.x + o.y * o.y) + (o.z * o.z + o.w * o.w);
;                             u32x2 w; w.x = pg8::cvt_pk_bf16(o.x * gg.x * (1.f + sc.x), o.y * gg.y * (1.f + sc.y)); w.y = pg8::cvt_pk_bf16(o.z * gg.z * (1.f + sc.z), o.w * gg.w * (1.f + sc.w));
;                             *(u32x2*)(hu + (size_t)row * D + col) = w; } }
;                 if (hu) { sq += __shfl_xor(sq, 16); sq += __shfl_xor(sq, 32); if (fq == 0) __hip_atomic_fetch_add(ss + row, sq, __ATOMIC_RELAXED, __HIP_MEMORY_SCOPE_AGENT); } }
	v_pk_fma_f32 v[14:15], v[14:15], v[162:163], v[144:145]
	v_pk_fma_f32 v[12:13], v[12:13], v[160:161], v[142:143]
	global_store_dwordx4 v219, v[12:15], s[8:9] offset:0
	v_pk_fma_f32 v[10:11], v[10:11], v[166:167], v[148:149]
	v_pk_fma_f32 v[8:9], v[8:9], v[164:165], v[146:147]
	global_store_dwordx4 v219, v[8:11], s[8:9] offset:64
	v_pk_fma_f32 v[6:7], v[6:7], v[170:171], v[178:179]
	v_pk_fma_f32 v[4:5], v[4:5], v[168:169], v[176:177]
	global_store_dwordx4 v219, v[4:7], s[8:9] offset:512
	v_pk_fma_f32 v[2:3], v[2:3], v[174:175], v[182:183]
	v_pk_fma_f32 v[0:1], v[0:1], v[172:173], v[180:181]
	global_store_dwordx4 v219, v[0:3], s[8:9] offset:576
	v_lshrrev_b32_e32 v220, 1, v219
	v_mul_f32_e32 v142, v12, v186
	v_mul_f32_e32 v143, v13, v187
	v_mul_f32_e32 v144, v14, v188
	v_mul_f32_e32 v145, v15, v189
	v_mul_f32_e32 v221, v12, v12
	v_fmac_f32_e32 v221, v13, v13
	v_fmac_f32_e32 v221, v14, v14
	v_fmac_f32_e32 v221, v15, v15
	v_cvt_pk_bf16_f32 v142, v142, v143
	v_cvt_pk_bf16_f32 v143, v144, v145
	global_store_dwordx2 v220, v[142:143], s[10:11] offset:0
	v_mul_f32_e32 v146, v8, v190
	v_mul_f32_e32 v147, v9, v191
	v_mul_f32_e32 v148, v10, v192
	v_mul_f32_e32 v149, v11, v193
	v_fmac_f32_e32 v221, v8, v8
	v_fmac_f32_e32 v221, v9, v9
	v_fmac_f32_e32 v221, v10, v10
	v_fmac_f32_e32 v221, v11, v11
	v_cvt_pk_bf16_f32 v146, v146, v147
	v_cvt_pk_bf16_f32 v147, v148, v149
	global_store_dwordx2 v220, v[146:147], s[10:11] offset:32
	v_mul_f32_e32 v176, v4, v194
	v_mul_f32_e32 v177, v5, v195
	v_mul_f32_e32 v178, v6, v196
	v_mul_f32_e32 v179, v7, v197
	v_fmac_f32_e32 v221, v4, v4
	v_fmac_f32_e32 v221, v5, v5
	v_fmac_f32_e32 v221, v6, v6
	v_fmac_f32_e32 v221, v7, v7
	v_cvt_pk_bf16_f32 v176, v176, v177
	v_cvt_pk_bf16_f32 v177, v178, v179
	global_store_dwordx2 v220, v[176:177], s[10:11] offset:256
	v_mul_f32_e32 v180, v0, v198
	v_mul_f32_e32 v181, v1, v199
	v_mul_f32_e32 v182, v2, v200
	v_mul_f32_e32 v183, v3, v201
	v_fmac_f32_e32 v221, v0, v0
	v_fmac_f32_e32 v221, v1, v1
	v_fmac_f32_e32 v221, v2, v2
	v_fmac_f32_e32 v221, v3, v3
	v_cvt_pk_bf16_f32 v180, v180, v181
	v_cvt_pk_bf16_f32 v181, v182, v183
	global_store_dwordx2 v220, v[180:181], s[10:11] offset:288
	v_mov_b32_e32 v12, v221
	v_xor_b32_e32 v220, 16, v156
	v_lshlrev_b32_e32 v220, 2, v220
	v_xor_b32_e32 v221, 32, v156
	v_lshlrev_b32_e32 v221, 2, v221
	ds_bpermute_b32 v202, v220, v124
	ds_bpermute_b32 v203, v220, v108
	ds_bpermute_b32 v204, v220, v92
	ds_bpermute_b32 v205, v220, v76
	ds_bpermute_b32 v206, v220, v60
	ds_bpermute_b32 v207, v220, v44
	ds_bpermute_b32 v208, v220, v28
	ds_bpermute_b32 v209, v220, v12
	s_waitcnt lgkmcnt(0)
	v_add_f32_e32 v124, v124, v202
	v_add_f32_e32 v108, v108, v203
	v_add_f32_e32 v92, v92, v204
	v_add_f32_e32 v76, v76, v205
	v_add_f32_e32 v60, v60, v206
	v_add_f32_e32 v44, v44, v207
	v_add_f32_e32 v28, v28, v208
	v_add_f32_e32 v12, v12, v209
	ds_bpermute_b32 v202, v221, v124
	ds_bpermute_b32 v203, v221, v108
	ds_bpermute_b32 v204, v221, v92
	ds_bpermute_b32 v205, v221, v76
	ds_bpermute_b32 v206, v221, v60
	ds_bpermute_b32 v207, v221, v44
	ds_bpermute_b32 v208, v221, v28
	ds_bpermute_b32 v209, v221, v12
	v_add_u32_e32 v220, s31, v150
	v_lshlrev_b32_e32 v220, 2, v220
	s_waitcnt lgkmcnt(0)
	v_add_f32_e32 v124, v124, v202
	v_add_f32_e32 v108, v108, v203
	v_add_f32_e32 v92, v92, v204
	v_add_f32_e32 v76, v76, v205
	v_add_f32_e32 v60, v60, v206
	v_add_f32_e32 v44, v44, v207
	v_add_f32_e32 v28, v28, v208
	v_add_f32_e32 v12, v12, v209
	s_and_saveexec_b64 s[46:47], s[2:3]
	global_atomic_add_f32 v220, v124, s[22:23] offset:0
	global_atomic_add_f32 v220, v108, s[22:23] offset:64
	global_atomic_add_f32 v220, v92, s[22:23] offset:128
	global_atomic_add_f32 v220, v76, s[22:23] offset:192
	global_atomic_add_f32 v220, v60, s[22:23] offset:512
	global_atomic_add_f32 v220, v44, s[22:23] offset:576
	global_atomic_add_f32 v220, v28, s[22:23] offset:640
	global_atomic_add_f32 v220, v12, s[22:23] offset:704
	s_mov_b64 exec, s[46:47]
	s_andn2_b64 vcc, exec, s[4:5]
	s_mov_b64 s[4:5], -1
	s_cbranch_vccnz .LBB0_628
	s_andn2_b64 vcc, exec, s[0:1]
	s_cbranch_vccnz .LBB0_627
	s_barrier
	s_branch .LBB0_627

;     __host__ __device__ bool next(int i, Unit& u) const {
;         const long L = (long)i * G + c; if (L >= nwg) return false;
;         int wgid = (int)L; { const int q = nwg / NXCD, r = nwg % NXCD, xcd = wgid % NXCD, off = wgid / NXCD; wgid = (xcd < r ? xcd * (q + 1) : r * (q + 1) + (xcd - r) * q) + off; }
;         const int nig = WGM * nN, gid = wgid / nig, fm = gid * WGM, gsz = (nM - fm) < WGM ? (nM - fm) : WGM;
;         u.pm = fm + ((wgid % nig) % gsz); u.pn = (wgid % nig) / gsz; return true;
;     }
.LBB0_821:
	s_add_i32 s59, s59, 1
	s_mul_i32 s4, s59, s65
	s_mul_hi_u32 s5, s59, s66
	s_add_i32 s5, s5, s4
	s_mul_i32 s4, s59, s66
	s_add_u32 s4, s4, s33
	s_addc_u32 s5, s5, s67
	s_cmp_eq_u32 s59, 2
	s_cbranch_scc0 .Lp8_sched_std
	s_cmp_eq_u32 s88, 0x100
	s_cbranch_scc0 .Lp8_sched_std
	s_lshr_b32 s5, s33, 5
	s_lshl_b32 s5, s5, 3
	s_and_b32 s4, s33, 7
	s_add_i32 s4, s4, s5
	s_add_i32 s4, s4, 512
	s_mov_b32 s5, 0
.Lp8_sched_std:
	v_cmp_gt_i64_e32 vcc, s[4:5], v[140:141]
	v_cmp_lt_i64_e64 s[6:7], s[4:5], v[138:139]
	s_cbranch_vccnz .LBB0_823
	s_ashr_i32 s5, s4, 31
	s_lshr_b32 s5, s5, 29
	s_add_i32 s5, s4, s5
	s_ashr_i32 s38, s5, 3
	s_and_b32 s5, s5, -8
	s_sub_i32 s4, s4, s5
	s_cmp_lt_i32 s4, 0
	s_cselect_b32 s5, s68, 0x48
	s_mul_i32 s4, s5, s4
	s_add_i32 s4, s4, s38
	s_ashr_i32 s5, s4, 31
	s_lshr_b32 s5, s5, 27
	s_add_i32 s5, s4, s5
	s_ashr_i32 s38, s5, 5
	s_lshl_b32 s38, s38, 2
	s_sub_i32 s39, 0x48, s38
	s_min_i32 s39, s39, 4
	s_abs_i32 s48, s39
	v_cvt_f32_u32_e32 v0, s48
	s_sub_i32 s62, 0, s48
	s_andn2_b32 s5, s5, 31
	s_sub_i32 s4, s4, s5
	v_rcp_iflag_f32_e32 v0, v0
	s_abs_i32 s5, s4
	s_xor_b32 s49, s4, s39
	s_ashr_i32 s49, s49, 31
	v_mul_f32_e32 v0, 0x4f7ffffe, v0
	v_cvt_u32_f32_e32 v0, v0
	s_nop 0
	v_readfirstlane_b32 s63, v0
	s_mul_i32 s62, s62, s63
	s_mul_hi_u32 s62, s63, s62
	s_add_i32 s63, s63, s62
	s_mul_hi_u32 s62, s5, s63
	s_mul_i32 s63, s62, s48
	s_sub_i32 s5, s5, s63
	s_add_i32 s72, s62, 1
	s_sub_i32 s63, s5, s48
	s_cmp_ge_u32 s5, s48
	s_cselect_b32 s62, s72, s62
	s_cselect_b32 s5, s63, s5
	s_add_i32 s63, s62, 1
	s_cmp_ge_u32 s5, s48
	s_cselect_b32 s5, s63, s62
	s_xor_b32 s5, s5, s49
	s_sub_i32 s72, s5, s49
	s_mul_i32 s5, s72, s39
	s_sub_i32 s4, s4, s5
	s_add_i32 s73, s4, s38

; #define PG8_STAGE(bufoff, gbase, voff) do { _Pragma("unroll") for (int _i = 0; _i < 2; ++_i) \
;         __builtin_amdgcn_global_load_lds((const unsigned*)((const char*)(gbase) + (voff)[_i]), (PG8_LAS unsigned*)(lds + (bufoff) + ldsw + _i * 8192), 16, 0, 0); } while (0)
; #define PG8_LDA(dst, b, h) do { _Pragma("unroll") for (int m = 0; m < 4; ++m) _Pragma("unroll") for (int k = 0; k < 2; ++k) dst[m][k] = *(const PG8_LAS bf16x8*)(lds + PG8_SA(b, h) + aoff + m * 2048 + k * 1024); } while (0)
; #define PG8_LDB(dst, b, h) do { _Pragma("unroll") for (int n = 0; n < 2; ++n) _Pragma("unroll") for (int k = 0; k < 2; ++k) dst[n][k] = *(const PG8_LAS bf16x8*)(lds + PG8_SB(b, h) + boff + n * 2048 + k * 1024); } while (0)
; #define PG8_WAIT_V(n) asm volatile("s_waitcnt vmcnt(" #n ")" ::: "memory")
; #define PG8_WAIT_L(n) asm volatile("s_waitcnt lgkmcnt(" #n ")" ::: "memory")
; #define PG8_BAR __builtin_amdgcn_s_barrier()
; #define PG8_SCHED __builtin_amdgcn_sched_barrier(0)
; template <class Epi, class Sched, bool ALIGN_EPI = false, bool SP2 = false>
; __device__ __forceinline__ void gemm_phase(PG8_LAS unsigned char* lds, const Gemm g, const Sched& S, const Epi& E) {
;     ...
;     for (;;) {
;         const bool has_next = S.next(ui + 1, nxt);
;         const char* nA = has_next ? (const char*)g.A + (size_t)nxt.pm * tstep : cA; const char* nB = has_next ? (const char*)g.Bt + (size_t)nxt.pn * tstep : cB;
;         for (int t = 0; t < nt; t += 2) {
;             const bool last = (t == nt - 2);
;             const char* a1 = cA + (size_t)(t + 1) * kstep;
;             const char* a2 = last ? nA : cA + (size_t)(t + 2) * kstep; const char* b2 = last ? nB : cB + (size_t)(t + 2) * kstep;
;             const char* a3 = a2 + kstep; const char* b3 = b2 + kstep;
;             if (last && has_next) S.a_ready(nxt);
;             if constexpr (SP2) {
;             PG8_LDB(B0, 0, 0); PG8_LDB(B1, 0, 1); PG8_SCHED; PG8_LDA(At, 0, 0); PG8_STAGE(PG8_SA(1, 1), a1 + hstep, voffA);
;             PG8_WAIT_V(8); PG8_WAIT_L(0); PG8_BAR; PG8_MMA(0, 0, At, B0); PG8_MMA(0, 1, At, B1); PG8_BAR; PG8_SCHED;
;     ...
; #pragma unroll
;         for (int a = 0; a < 2; ++a)
; #pragma unroll
;             for (int b = 0; b < 2; ++b)
; #pragma unroll
;                 for (int m = 0; m < 4; ++m)
; #pragma unroll
;                     for (int n = 0; n < 2; ++n) acc[a][b][m][n] = (f32x4){0.f, 0.f, 0.f, 0.f};
.LBB0_827:
	s_mov_b32 s32, 15
	s_cmp_eq_u32 s59, 3
	s_cbranch_scc0 .Lp8_mode_done
	s_cmp_eq_u32 s88, 0x100
	s_cbranch_scc0 .Lp8_mode_done
	s_bfe_u32 s32, s33, 0x20003
	s_lshl_b32 s32, 1, s32
.Lp8_mode_done:
	s_add_u32 s44, s44, 0x160080
	s_addc_u32 s45, s45, 0
	s_add_u32 s76, s46, 0x100
	v_mov_b32_e32 v0, 0
	s_addc_u32 s77, s47, 0
	s_mov_b32 s92, -2
	s_waitcnt lgkmcnt(0)
	v_mov_b32_e32 v1, v0
	v_mov_b32_e32 v2, v0
	v_mov_b32_e32 v3, v0
	v_mov_b32_e32 v4, v0
	v_mov_b32_e32 v5, v0
	v_mov_b32_e32 v6, v0
	v_mov_b32_e32 v7, v0
	v_mov_b32_e32 v16, v0
	v_mov_b32_e32 v17, v0
	v_mov_b32_e32 v18, v0
	v_mov_b32_e32 v19, v0
	v_mov_b32_e32 v20, v0
	v_mov_b32_e32 v21, v0
	v_mov_b32_e32 v22, v0
	v_mov_b32_e32 v23, v0
	v_mov_b32_e32 v32, v0
	v_mov_b32_e32 v33, v0
	v_mov_b32_e32 v34, v0
	v_mov_b32_e32 v35, v0
	v_mov_b32_e32 v36, v0
	v_mov_b32_e32 v37, v0
	v_mov_b32_e32 v38, v0
	v_mov_b32_e32 v39, v0
	v_mov_b32_e32 v48, v0
	v_mov_b32_e32 v49, v0
	v_mov_b32_e32 v50, v0
	v_mov_b32_e32 v51, v0
	v_mov_b32_e32 v52, v0
	v_mov_b32_e32 v53, v0
	v_mov_b32_e32 v54, v0
	v_mov_b32_e32 v55, v0
	v_mov_b32_e32 v8, v0
	v_mov_b32_e32 v9, v0
	v_mov_b32_e32 v10, v0
	v_mov_b32_e32 v11, v0
	v_mov_b32_e32 v12, v0
	v_mov_b32_e32 v13, v0
	v_mov_b32_e32 v14, v0
	v_mov_b32_e32 v15, v0
	v_mov_b32_e32 v24, v0
	v_mov_b32_e32 v25, v0
	v_mov_b32_e32 v26, v0
	v_mov_b32_e32 v27, v0
	v_mov_b32_e32 v28, v0
	v_mov_b32_e32 v29, v0
	v_mov_b32_e32 v30, v0
	v_mov_b32_e32 v31, v0
	v_mov_b32_e32 v40, v0
	v_mov_b32_e32 v41, v0
	v_mov_b32_e32 v42, v0
	v_mov_b32_e32 v43, v0
	v_mov_b32_e32 v44, v0
	v_mov_b32_e32 v45, v0
	v_mov_b32_e32 v46, v0
	v_mov_b32_e32 v47, v0
	v_mov_b32_e32 v56, v0
	v_mov_b32_e32 v57, v0
	v_mov_b32_e32 v58, v0
	v_mov_b32_e32 v59, v0
	v_mov_b32_e32 v60, v0
	v_mov_b32_e32 v61, v0
	v_mov_b32_e32 v62, v0
	v_mov_b32_e32 v63, v0
	v_mov_b32_e32 v64, v0
	v_mov_b32_e32 v65, v0
	v_mov_b32_e32 v66, v0
	v_mov_b32_e32 v67, v0
	v_mov_b32_e32 v68, v0
	v_mov_b32_e32 v69, v0
	v_mov_b32_e32 v70, v0
	v_mov_b32_e32 v71, v0
	v_mov_b32_e32 v80, v0
	v_mov_b32_e32 v81, v0
	v_mov_b32_e32 v82, v0
	v_mov_b32_e32 v83, v0
	v_mov_b32_e32 v84, v0
	v_mov_b32_e32 v85, v0
	v_mov_b32_e32 v86, v0
	v_mov_b32_e32 v87, v0
	v_mov_b32_e32 v96, v0
	v_mov_b32_e32 v97, v0
	v_mov_b32_e32 v98, v0
	v_mov_b32_e32 v99, v0
	v_mov_b32_e32 v100, v0
	v_mov_b32_e32 v101, v0
	v_mov_b32_e32 v102, v0
	v_mov_b32_e32 v103, v0
	v_mov_b32_e32 v112, v0
	v_mov_b32_e32 v113, v0
	v_mov_b32_e32 v114, v0
	v_mov_b32_e32 v115, v0
	v_mov_b32_e32 v116, v0
	v_mov_b32_e32 v117, v0
	v_mov_b32_e32 v118, v0
	v_mov_b32_e32 v119, v0
	v_mov_b32_e32 v72, v0
	v_mov_b32_e32 v73, v0
	v_mov_b32_e32 v74, v0
	v_mov_b32_e32 v75, v0
	v_mov_b32_e32 v76, v0
	v_mov_b32_e32 v77, v0
	v_mov_b32_e32 v78, v0
	v_mov_b32_e32 v79, v0
	v_mov_b32_e32 v88, v0
	v_mov_b32_e32 v89, v0
	v_mov_b32_e32 v90, v0
	v_mov_b32_e32 v91, v0
	v_mov_b32_e32 v92, v0
	v_mov_b32_e32 v93, v0
	v_mov_b32_e32 v94, v0
	v_mov_b32_e32 v95, v0
	v_mov_b32_e32 v104, v0
	v_mov_b32_e32 v105, v0
	v_mov_b32_e32 v106, v0
	v_mov_b32_e32 v107, v0
	v_mov_b32_e32 v108, v0
	v_mov_b32_e32 v109, v0
	v_mov_b32_e32 v110, v0
	v_mov_b32_e32 v111, v0
	v_mov_b32_e32 v120, v0
	v_mov_b32_e32 v121, v0
	v_mov_b32_e32 v122, v0
	v_mov_b32_e32 v123, v0
	v_mov_b32_e32 v124, v0
	v_mov_b32_e32 v125, v0
	v_mov_b32_e32 v126, v0
	v_mov_b32_e32 v127, v0
	s_cmp_lg_u32 s32, 15
	s_cbranch_scc1 .Lp8_qloop
.LBB0_828:
	ds_read_b128 v[142:145], v155
	ds_read_b128 v[146:149], v155 offset:1024
	ds_read_b128 v[160:163], v155 offset:2048
	ds_read_b128 v[164:167], v155 offset:3072
	ds_read_b128 v[168:171], v156
	ds_read_b128 v[172:175], v156 offset:1024
	ds_read_b128 v[176:179], v156 offset:2048
	ds_read_b128 v[180:183], v156 offset:3072
	s_add_u32 s46, s44, 0xffea0080
	s_addc_u32 s47, s45, -1
	s_cmpk_eq_i32 s92, 0x54
	s_cselect_b32 s49, s7, s47
	s_cselect_b32 s48, s6, s46
	s_cselect_b32 s47, s39, s77
	s_cselect_b32 s46, s38, s76
	v_lshl_add_u64 v[150:151], s[44:45], 0, v[134:135]
	s_add_i32 m0, s55, 0xc000
	ds_read_b128 v[186:189], v157
	ds_read_b128 v[190:193], v157 offset:1024
	ds_read_b128 v[194:197], v157 offset:2048
	ds_read_b128 v[198:201], v157 offset:3072
	ds_read_b128 v[202:205], v157 offset:4096
	ds_read_b128 v[206:209], v157 offset:5120
	ds_read_b128 v[210:213], v157 offset:6144
	ds_read_b128 v[214:217], v157 offset:7168
	global_load_lds_dwordx4 v[150:151], off
	v_lshl_add_u64 v[150:151], s[44:45], 0, v[136:137]
	s_add_i32 m0, s55, 0xe000
	s_nop 0
	global_load_lds_dwordx4 v[150:151], off
	s_waitcnt vmcnt(8)
	s_waitcnt lgkmcnt(0)
	s_barrier
; #define PG8_STAGE(bufoff, gbase, voff) do { _Pragma("unroll") for (int _i = 0; _i < 2; ++_i) \
;         __builtin_amdgcn_global_load_lds((const unsigned*)((const char*)(gbase) + (voff)[_i]), (PG8_LAS unsigned*)(lds + (bufoff) + ldsw + _i * 8192), 16, 0, 0); } while (0)
; #define PG8_LDA(dst, b, h) do { _Pragma("unroll") for (int m = 0; m < 4; ++m) _Pragma("unroll") for (int k = 0; k < 2; ++k) dst[m][k] = *(const PG8_LAS bf16x8*)(lds + PG8_SA(b, h) + aoff + m * 2048 + k * 1024); } while (0)
; #define PG8_MMA(ai, bj, At, Bt) do { __builtin_amdgcn_s_setprio(1); _Pragma("unroll") for (int m = 0; m < 4; ++m) _Pragma("unroll") for (int n = 0; n < 2; ++n) _Pragma("unroll") for (int k = 0; k < 2; ++k) \
;         acc[ai][bj][m][n] = __builtin_amdgcn_mfma_f32_16x16x32_bf16(Bt[n][k], At[m][k], acc[ai][bj][m][n], 0, 0, 0); __builtin_amdgcn_s_setprio(0); } while (0)
; #define PG8_WAIT_V(n) asm volatile("s_waitcnt vmcnt(" #n ")" ::: "memory")
; #define PG8_WAIT_L(n) asm volatile("s_waitcnt lgkmcnt(" #n ")" ::: "memory")
; #define PG8_BAR __builtin_amdgcn_s_barrier()
; #define PG8_SCHED __builtin_amdgcn_sched_barrier(0)
; template <class Epi, class Sched, bool ALIGN_EPI = false, bool SP2 = false>
; __device__ __forceinline__ void gemm_phase(PG8_LAS unsigned char* lds, const Gemm g, const Sched& S, const Epi& E) {
;     ...
;             PG8_WAIT_V(8); PG8_WAIT_L(0); PG8_BAR; PG8_MMA(0, 0, At, B0); PG8_MMA(0, 1, At, B1); PG8_BAR; PG8_SCHED;
;             PG8_LDA(At, 0, 1); PG8_STAGE(PG8_SB(0, 0), b2, voffB); PG8_STAGE(PG8_SB(0, 1), b2 + hstep, voffB); PG8_STAGE(PG8_SA(0, 0), a2, voffA);
;             PG8_WAIT_V(8); PG8_WAIT_L(0); PG8_BAR; PG8_MMA(1, 0, At, B0); PG8_MMA(1, 1, At, B1); PG8_BAR; PG8_SCHED;
	s_setprio 1
	s_waitcnt lgkmcnt(0)
	v_mfma_f32_16x16x32_bf16 v[124:127], v[142:145], v[186:189], v[124:127]
	v_mfma_f32_16x16x32_bf16 v[120:123], v[160:163], v[186:189], v[120:123]
	v_mfma_f32_16x16x32_bf16 v[108:111], v[142:145], v[194:197], v[108:111]
	v_mfma_f32_16x16x32_bf16 v[104:107], v[160:163], v[194:197], v[104:107]
	v_mfma_f32_16x16x32_bf16 v[92:95], v[142:145], v[202:205], v[92:95]
	v_mfma_f32_16x16x32_bf16 v[88:91], v[160:163], v[202:205], v[88:91]
	v_mfma_f32_16x16x32_bf16 v[76:79], v[142:145], v[210:213], v[76:79]
	v_mfma_f32_16x16x32_bf16 v[72:75], v[160:163], v[210:213], v[72:75]
	v_mfma_f32_16x16x32_bf16 v[124:127], v[146:149], v[190:193], v[124:127]
	v_mfma_f32_16x16x32_bf16 v[120:123], v[164:167], v[190:193], v[120:123]
	v_mfma_f32_16x16x32_bf16 v[108:111], v[146:149], v[198:201], v[108:111]
	v_mfma_f32_16x16x32_bf16 v[104:107], v[164:167], v[198:201], v[104:107]
	v_mfma_f32_16x16x32_bf16 v[92:95], v[146:149], v[206:209], v[92:95]
	v_mfma_f32_16x16x32_bf16 v[88:91], v[164:167], v[206:209], v[88:91]
	v_mfma_f32_16x16x32_bf16 v[76:79], v[146:149], v[214:217], v[76:79]
	v_mfma_f32_16x16x32_bf16 v[72:75], v[164:167], v[214:217], v[72:75]
	s_setprio 0
	s_setprio 1
	v_mfma_f32_16x16x32_bf16 v[116:119], v[168:171], v[186:189], v[116:119]
	v_mfma_f32_16x16x32_bf16 v[112:115], v[176:179], v[186:189], v[112:115]
	v_mfma_f32_16x16x32_bf16 v[100:103], v[168:171], v[194:197], v[100:103]
	v_mfma_f32_16x16x32_bf16 v[96:99], v[176:179], v[194:197], v[96:99]
	v_mfma_f32_16x16x32_bf16 v[84:87], v[168:171], v[202:205], v[84:87]
	v_mfma_f32_16x16x32_bf16 v[80:83], v[176:179], v[202:205], v[80:83]
	v_mfma_f32_16x16x32_bf16 v[68:71], v[168:171], v[210:213], v[68:71]
	v_mfma_f32_16x16x32_bf16 v[64:67], v[176:179], v[210:213], v[64:67]
	v_mfma_f32_16x16x32_bf16 v[116:119], v[172:175], v[190:193], v[116:119]
	v_mfma_f32_16x16x32_bf16 v[112:115], v[180:183], v[190:193], v[112:115]
	v_mfma_f32_16x16x32_bf16 v[100:103], v[172:175], v[198:201], v[100:103]
	v_mfma_f32_16x16x32_bf16 v[96:99], v[180:183], v[198:201], v[96:99]
	v_mfma_f32_16x16x32_bf16 v[84:87], v[172:175], v[206:209], v[84:87]
	v_mfma_f32_16x16x32_bf16 v[80:83], v[180:183], v[206:209], v[80:83]
	v_mfma_f32_16x16x32_bf16 v[68:71], v[172:175], v[214:217], v[68:71]
	v_mfma_f32_16x16x32_bf16 v[64:67], v[180:183], v[214:217], v[64:67]
	s_setprio 0
	s_barrier
	s_add_i32 s62, s69, s54
	v_lshl_add_u64 v[150:151], s[46:47], 0, v[128:129]
	s_mov_b32 m0, s62
	ds_read_b128 v[186:189], v157 offset:16384
	ds_read_b128 v[190:193], v157 offset:17408
	ds_read_b128 v[194:197], v157 offset:18432
	ds_read_b128 v[198:201], v157 offset:19456
	ds_read_b128 v[202:205], v157 offset:20480
	ds_read_b128 v[206:209], v157 offset:21504
	ds_read_b128 v[210:213], v157 offset:22528
	ds_read_b128 v[214:217], v157 offset:23552
	global_load_lds_dwordx4 v[150:151], off
	s_add_i32 m0, s62, 0x2000
	s_add_u32 s62, s46, 0x160000
	v_lshl_add_u64 v[218:219], s[46:47], 0, v[130:131]
	s_addc_u32 s63, s47, 0
	s_add_i32 s93, s70, s54
	global_load_lds_dwordx4 v[218:219], off
	v_lshl_add_u64 v[220:221], s[62:63], 0, v[128:129]
	s_mov_b32 m0, s93
	v_lshl_add_u64 v[222:223], s[48:49], 0, v[130:131]
	global_load_lds_dwordx4 v[220:221], off
	v_lshl_add_u64 v[220:221], s[62:63], 0, v[130:131]
	s_add_i32 m0, s93, 0x2000
	s_nop 0
	global_load_lds_dwordx4 v[220:221], off
	v_lshl_add_u64 v[220:221], s[48:49], 0, v[128:129]
	s_mov_b32 m0, s55
	s_nop 0
	global_load_lds_dwordx4 v[220:221], off
	s_mov_b32 m0, s56
	s_nop 0
	global_load_lds_dwordx4 v[222:223], off
	s_waitcnt vmcnt(8)
	s_waitcnt lgkmcnt(0)
	s_barrier
	s_setprio 1
	s_waitcnt lgkmcnt(0)
	v_mfma_f32_16x16x32_bf16 v[60:63], v[142:145], v[186:189], v[60:63]
	v_mfma_f32_16x16x32_bf16 v[56:59], v[160:163], v[186:189], v[56:59]
	v_mfma_f32_16x16x32_bf16 v[44:47], v[142:145], v[194:197], v[44:47]
	v_mfma_f32_16x16x32_bf16 v[40:43], v[160:163], v[194:197], v[40:43]
	v_mfma_f32_16x16x32_bf16 v[28:31], v[142:145], v[202:205], v[28:31]
	v_mfma_f32_16x16x32_bf16 v[24:27], v[160:163], v[202:205], v[24:27]
	v_mfma_f32_16x16x32_bf16 v[12:15], v[142:145], v[210:213], v[12:15]
	v_mfma_f32_16x16x32_bf16 v[8:11], v[160:163], v[210:213], v[8:11]
	v_mfma_f32_16x16x32_bf16 v[60:63], v[146:149], v[190:193], v[60:63]
	v_mfma_f32_16x16x32_bf16 v[56:59], v[164:167], v[190:193], v[56:59]
	v_mfma_f32_16x16x32_bf16 v[44:47], v[146:149], v[198:201], v[44:47]
	v_mfma_f32_16x16x32_bf16 v[40:43], v[164:167], v[198:201], v[40:43]
	v_mfma_f32_16x16x32_bf16 v[28:31], v[146:149], v[206:209], v[28:31]
	v_mfma_f32_16x16x32_bf16 v[24:27], v[164:167], v[206:209], v[24:27]
	v_mfma_f32_16x16x32_bf16 v[12:15], v[146:149], v[214:217], v[12:15]
	v_mfma_f32_16x16x32_bf16 v[8:11], v[164:167], v[214:217], v[8:11]
	s_setprio 0
	s_setprio 1
	v_mfma_f32_16x16x32_bf16 v[52:55], v[168:171], v[186:189], v[52:55]
	v_mfma_f32_16x16x32_bf16 v[48:51], v[176:179], v[186:189], v[48:51]
	v_mfma_f32_16x16x32_bf16 v[36:39], v[168:171], v[194:197], v[36:39]
	v_mfma_f32_16x16x32_bf16 v[32:35], v[176:179], v[194:197], v[32:35]
	v_mfma_f32_16x16x32_bf16 v[20:23], v[168:171], v[202:205], v[20:23]
	v_mfma_f32_16x16x32_bf16 v[16:19], v[176:179], v[202:205], v[16:19]
	v_mfma_f32_16x16x32_bf16 v[4:7], v[168:171], v[210:213], v[4:7]
	v_mfma_f32_16x16x32_bf16 v[0:3], v[176:179], v[210:213], v[0:3]
	v_mfma_f32_16x16x32_bf16 v[52:55], v[172:175], v[190:193], v[52:55]
	v_mfma_f32_16x16x32_bf16 v[48:51], v[180:183], v[190:193], v[48:51]
	v_mfma_f32_16x16x32_bf16 v[36:39], v[172:175], v[198:201], v[36:39]
	v_mfma_f32_16x16x32_bf16 v[32:35], v[180:183], v[198:201], v[32:35]
	v_mfma_f32_16x16x32_bf16 v[20:23], v[172:175], v[206:209], v[20:23]
	v_mfma_f32_16x16x32_bf16 v[16:19], v[180:183], v[206:209], v[16:19]
	v_mfma_f32_16x16x32_bf16 v[4:7], v[172:175], v[214:217], v[4:7]
	v_mfma_f32_16x16x32_bf16 v[0:3], v[180:183], v[214:217], v[0:3]
	s_setprio 0
	s_barrier
; #define PG8_STAGE(bufoff, gbase, voff) do { _Pragma("unroll") for (int _i = 0; _i < 2; ++_i) \
;         __builtin_amdgcn_global_load_lds((const unsigned*)((const char*)(gbase) + (voff)[_i]), (PG8_LAS unsigned*)(lds + (bufoff) + ldsw + _i * 8192), 16, 0, 0); } while (0)
; #define PG8_LDA(dst, b, h) do { _Pragma("unroll") for (int m = 0; m < 4; ++m) _Pragma("unroll") for (int k = 0; k < 2; ++k) dst[m][k] = *(const PG8_LAS bf16x8*)(lds + PG8_SA(b, h) + aoff + m * 2048 + k * 1024); } while (0)
; #define PG8_LDB(dst, b, h) do { _Pragma("unroll") for (int n = 0; n < 2; ++n) _Pragma("unroll") for (int k = 0; k < 2; ++k) dst[n][k] = *(const PG8_LAS bf16x8*)(lds + PG8_SB(b, h) + boff + n * 2048 + k * 1024); } while (0)
; #define PG8_MMA(ai, bj, At, Bt) do { __builtin_amdgcn_s_setprio(1); _Pragma("unroll") for (int m = 0; m < 4; ++m) _Pragma("unroll") for (int n = 0; n < 2; ++n) _Pragma("unroll") for (int k = 0; k < 2; ++k) \
;         acc[ai][bj][m][n] = __builtin_amdgcn_mfma_f32_16x16x32_bf16(Bt[n][k], At[m][k], acc[ai][bj][m][n], 0, 0, 0); __builtin_amdgcn_s_setprio(0); } while (0)
; #define PG8_WAIT_V(n) asm volatile("s_waitcnt vmcnt(" #n ")" ::: "memory")
; #define PG8_WAIT_L(n) asm volatile("s_waitcnt lgkmcnt(" #n ")" ::: "memory")
; #define PG8_BAR __builtin_amdgcn_s_barrier()
; #define PG8_SCHED __builtin_amdgcn_sched_barrier(0)
; template <class Epi, class Sched, bool ALIGN_EPI = false, bool SP2 = false>
; __device__ __forceinline__ void gemm_phase(PG8_LAS unsigned char* lds, const Gemm g, const Sched& S, const Epi& E) {
;     ...
;             PG8_LDB(B0, 1, 0); PG8_LDB(B1, 1, 1); PG8_SCHED; PG8_LDA(At, 1, 0); PG8_STAGE(PG8_SA(0, 1), a2 + hstep, voffA);
;             PG8_WAIT_V(8); PG8_WAIT_L(0); PG8_BAR; PG8_MMA(0, 0, At, B0); PG8_MMA(0, 1, At, B1); PG8_BAR; PG8_SCHED;
;             PG8_LDA(At, 1, 1); PG8_STAGE(PG8_SB(1, 0), b3, voffB); PG8_STAGE(PG8_SB(1, 1), b3 + hstep, voffB); PG8_STAGE(PG8_SA(1, 0), a3, voffA);
	s_add_i32 s62, 0, 0x18000
	v_add_u32_e32 v132, s62, v153
	s_add_i32 s63, 0, 0x1c000
	ds_read_b128 v[142:145], v132
	ds_read_b128 v[146:149], v132 offset:1024
	ds_read_b128 v[160:163], v132 offset:2048
	ds_read_b128 v[164:167], v132 offset:3072
	v_add_u32_e32 v132, s63, v153
	ds_read_b128 v[168:171], v132
	ds_read_b128 v[172:175], v132 offset:1024
	ds_read_b128 v[176:179], v132 offset:2048
	ds_read_b128 v[180:183], v132 offset:3072
	s_add_u32 s48, s48, 0x160000
	s_addc_u32 s49, s49, 0
	s_mov_b32 m0, s57
	v_lshl_add_u64 v[224:225], s[48:49], 0, v[128:129]
	ds_read_b128 v[186:189], v157 offset:32768
	ds_read_b128 v[190:193], v157 offset:33792
	ds_read_b128 v[194:197], v157 offset:34816
	ds_read_b128 v[198:201], v157 offset:35840
	ds_read_b128 v[202:205], v157 offset:36864
	ds_read_b128 v[206:209], v157 offset:37888
	ds_read_b128 v[210:213], v157 offset:38912
	ds_read_b128 v[214:217], v157 offset:39936
	global_load_lds_dwordx4 v[224:225], off
	v_lshl_add_u64 v[224:225], s[48:49], 0, v[130:131]
	s_mov_b32 m0, s58
	s_nop 0
	global_load_lds_dwordx4 v[224:225], off
	s_waitcnt vmcnt(8)
	s_waitcnt lgkmcnt(0)
	s_barrier
	s_setprio 1
	s_waitcnt lgkmcnt(0)
	v_mfma_f32_16x16x32_bf16 v[124:127], v[142:145], v[186:189], v[124:127]
	v_mfma_f32_16x16x32_bf16 v[120:123], v[160:163], v[186:189], v[120:123]
	v_mfma_f32_16x16x32_bf16 v[108:111], v[142:145], v[194:197], v[108:111]
	v_mfma_f32_16x16x32_bf16 v[104:107], v[160:163], v[194:197], v[104:107]
	v_mfma_f32_16x16x32_bf16 v[92:95], v[142:145], v[202:205], v[92:95]
	v_mfma_f32_16x16x32_bf16 v[88:91], v[160:163], v[202:205], v[88:91]
	v_mfma_f32_16x16x32_bf16 v[76:79], v[142:145], v[210:213], v[76:79]
	v_mfma_f32_16x16x32_bf16 v[72:75], v[160:163], v[210:213], v[72:75]
	v_mfma_f32_16x16x32_bf16 v[124:127], v[146:149], v[190:193], v[124:127]
	v_mfma_f32_16x16x32_bf16 v[120:123], v[164:167], v[190:193], v[120:123]
	v_mfma_f32_16x16x32_bf16 v[108:111], v[146:149], v[198:201], v[108:111]
	v_mfma_f32_16x16x32_bf16 v[104:107], v[164:167], v[198:201], v[104:107]
	v_mfma_f32_16x16x32_bf16 v[92:95], v[146:149], v[206:209], v[92:95]
	v_mfma_f32_16x16x32_bf16 v[88:91], v[164:167], v[206:209], v[88:91]
	v_mfma_f32_16x16x32_bf16 v[76:79], v[146:149], v[214:217], v[76:79]
	v_mfma_f32_16x16x32_bf16 v[72:75], v[164:167], v[214:217], v[72:75]
	s_setprio 0
	s_setprio 1
	v_mfma_f32_16x16x32_bf16 v[116:119], v[168:171], v[186:189], v[116:119]
	v_mfma_f32_16x16x32_bf16 v[112:115], v[176:179], v[186:189], v[112:115]
	v_mfma_f32_16x16x32_bf16 v[100:103], v[168:171], v[194:197], v[100:103]
	v_mfma_f32_16x16x32_bf16 v[96:99], v[176:179], v[194:197], v[96:99]
	v_mfma_f32_16x16x32_bf16 v[84:87], v[168:171], v[202:205], v[84:87]
	v_mfma_f32_16x16x32_bf16 v[80:83], v[176:179], v[202:205], v[80:83]
	v_mfma_f32_16x16x32_bf16 v[68:71], v[168:171], v[210:213], v[68:71]
	v_mfma_f32_16x16x32_bf16 v[64:67], v[176:179], v[210:213], v[64:67]
	v_mfma_f32_16x16x32_bf16 v[116:119], v[172:175], v[190:193], v[116:119]
	v_mfma_f32_16x16x32_bf16 v[112:115], v[180:183], v[190:193], v[112:115]
	v_mfma_f32_16x16x32_bf16 v[100:103], v[172:175], v[198:201], v[100:103]
	v_mfma_f32_16x16x32_bf16 v[96:99], v[180:183], v[198:201], v[96:99]
	v_mfma_f32_16x16x32_bf16 v[84:87], v[172:175], v[206:209], v[84:87]
	v_mfma_f32_16x16x32_bf16 v[80:83], v[180:183], v[206:209], v[80:83]
	v_mfma_f32_16x16x32_bf16 v[68:71], v[172:175], v[214:217], v[68:71]
	v_mfma_f32_16x16x32_bf16 v[64:67], v[180:183], v[214:217], v[64:67]
	s_setprio 0
	s_barrier
	s_add_i32 s48, s62, s54
	v_lshl_add_u64 v[150:151], v[150:151], 0, s[30:31]
	s_mov_b32 m0, s48
	ds_read_b128 v[186:189], v157 offset:49152
	ds_read_b128 v[190:193], v157 offset:50176
	ds_read_b128 v[194:197], v157 offset:51200
	ds_read_b128 v[198:201], v157 offset:52224
	ds_read_b128 v[202:205], v157 offset:53248
	ds_read_b128 v[206:209], v157 offset:54272
	ds_read_b128 v[210:213], v157 offset:55296
	ds_read_b128 v[214:217], v157 offset:56320
	global_load_lds_dwordx4 v[150:151], off
	s_add_i32 m0, s48, 0x2000
	s_add_u32 s46, s46, 0x160080
	v_lshl_add_u64 v[150:151], v[218:219], 0, s[30:31]
	s_addc_u32 s47, s47, 0
	s_add_i32 s48, s63, s54
	global_load_lds_dwordx4 v[150:151], off
	v_lshl_add_u64 v[150:151], s[46:47], 0, v[128:129]
	s_mov_b32 m0, s48
	s_nop 0
	global_load_lds_dwordx4 v[150:151], off
	v_lshl_add_u64 v[150:151], s[46:47], 0, v[130:131]
	s_add_i32 m0, s48, 0x2000
	s_nop 0
	global_load_lds_dwordx4 v[150:151], off
	v_lshl_add_u64 v[150:151], v[220:221], 0, s[30:31]
	s_mov_b32 m0, s61
	s_nop 0
	global_load_lds_dwordx4 v[150:151], off
	v_lshl_add_u64 v[150:151], v[222:223], 0, s[30:31]
	s_mov_b32 m0, s64
	s_nop 0
	global_load_lds_dwordx4 v[150:151], off
	s_waitcnt vmcnt(8)
	s_waitcnt lgkmcnt(0)
	s_barrier
; #define PG8_STAGE(bufoff, gbase, voff) do { _Pragma("unroll") for (int _i = 0; _i < 2; ++_i) \
;         __builtin_amdgcn_global_load_lds((const unsigned*)((const char*)(gbase) + (voff)[_i]), (PG8_LAS unsigned*)(lds + (bufoff) + ldsw + _i * 8192), 16, 0, 0); } while (0)
; #define PG8_LDA(dst, b, h) do { _Pragma("unroll") for (int m = 0; m < 4; ++m) _Pragma("unroll") for (int k = 0; k < 2; ++k) dst[m][k] = *(const PG8_LAS bf16x8*)(lds + PG8_SA(b, h) + aoff + m * 2048 + k * 1024); } while (0)
; #define PG8_LDB(dst, b, h) do { _Pragma("unroll") for (int n = 0; n < 2; ++n) _Pragma("unroll") for (int k = 0; k < 2; ++k) dst[n][k] = *(const PG8_LAS bf16x8*)(lds + PG8_SB(b, h) + boff + n * 2048 + k * 1024); } while (0)
; #define PG8_MMA(ai, bj, At, Bt) do { __builtin_amdgcn_s_setprio(1); _Pragma("unroll") for (int m = 0; m < 4; ++m) _Pragma("unroll") for (int n = 0; n < 2; ++n) _Pragma("unroll") for (int k = 0; k < 2; ++k) \
;         acc[ai][bj][m][n] = __builtin_amdgcn_mfma_f32_16x16x32_bf16(Bt[n][k], At[m][k], acc[ai][bj][m][n], 0, 0, 0); __builtin_amdgcn_s_setprio(0); } while (0)
; #define PG8_WAIT_V(n) asm volatile("s_waitcnt vmcnt(" #n ")" ::: "memory")
; template <class Epi, class Sched, bool ALIGN_EPI = false, bool SP2 = false>
; __device__ __forceinline__ void gemm_phase(PG8_LAS unsigned char* lds, const Gemm g, const Sched& S, const Epi& E) {
;     ...
;             PG8_LDB(B0, 0, 0); PG8_LDB(B1, 0, 1); PG8_SCHED; PG8_LDA(At, 0, 0); PG8_STAGE(PG8_SA(1, 1), a1 + hstep, voffA);
;             PG8_WAIT_V(8); PG8_WAIT_L(0); PG8_BAR; PG8_MMA(0, 0, At, B0); PG8_MMA(0, 1, At, B1); PG8_BAR; PG8_SCHED;
;             PG8_LDA(At, 0, 1); PG8_STAGE(PG8_SB(0, 0), b2, voffB); PG8_STAGE(PG8_SB(0, 1), b2 + hstep, voffB); PG8_STAGE(PG8_SA(0, 0), a2, voffA);
;             PG8_WAIT_V(8); PG8_WAIT_L(0); PG8_BAR; PG8_MMA(1, 0, At, B0); PG8_MMA(1, 1, At, B1); PG8_BAR; PG8_SCHED;
;             PG8_LDB(B0, 1, 0); PG8_LDB(B1, 1, 1); PG8_SCHED; PG8_LDA(At, 1, 0); PG8_STAGE(PG8_SA(0, 1), a2 + hstep, voffA);
;             PG8_WAIT_V(8); PG8_WAIT_L(0); PG8_BAR; PG8_MMA(0, 0, At, B0); PG8_MMA(0, 1, At, B1); PG8_BAR; PG8_SCHED;
;             PG8_LDA(At, 1, 1); PG8_STAGE(PG8_SB(1, 0), b3, voffB); PG8_STAGE(PG8_SB(1, 1), b3 + hstep, voffB); PG8_STAGE(PG8_SA(1, 0), a3, voffA);
;             PG8_WAIT_V(8); PG8_WAIT_L(0); PG8_BAR; PG8_MMA(1, 0, At, B0); PG8_MMA(1, 1, At, B1); PG8_BAR; PG8_SCHED;
	s_setprio 1
	s_waitcnt lgkmcnt(0)
	v_mfma_f32_16x16x32_bf16 v[60:63], v[142:145], v[186:189], v[60:63]
	v_mfma_f32_16x16x32_bf16 v[56:59], v[160:163], v[186:189], v[56:59]
	v_mfma_f32_16x16x32_bf16 v[44:47], v[142:145], v[194:197], v[44:47]
	v_mfma_f32_16x16x32_bf16 v[40:43], v[160:163], v[194:197], v[40:43]
	v_mfma_f32_16x16x32_bf16 v[28:31], v[142:145], v[202:205], v[28:31]
	v_mfma_f32_16x16x32_bf16 v[24:27], v[160:163], v[202:205], v[24:27]
	v_mfma_f32_16x16x32_bf16 v[12:15], v[142:145], v[210:213], v[12:15]
	v_mfma_f32_16x16x32_bf16 v[8:11], v[160:163], v[210:213], v[8:11]
	v_mfma_f32_16x16x32_bf16 v[60:63], v[146:149], v[190:193], v[60:63]
	v_mfma_f32_16x16x32_bf16 v[56:59], v[164:167], v[190:193], v[56:59]
	v_mfma_f32_16x16x32_bf16 v[44:47], v[146:149], v[198:201], v[44:47]
	v_mfma_f32_16x16x32_bf16 v[40:43], v[164:167], v[198:201], v[40:43]
	v_mfma_f32_16x16x32_bf16 v[28:31], v[146:149], v[206:209], v[28:31]
	v_mfma_f32_16x16x32_bf16 v[24:27], v[164:167], v[206:209], v[24:27]
	v_mfma_f32_16x16x32_bf16 v[12:15], v[146:149], v[214:217], v[12:15]
	v_mfma_f32_16x16x32_bf16 v[8:11], v[164:167], v[214:217], v[8:11]
	s_setprio 0
	s_setprio 1
	v_mfma_f32_16x16x32_bf16 v[52:55], v[168:171], v[186:189], v[52:55]
	v_mfma_f32_16x16x32_bf16 v[48:51], v[176:179], v[186:189], v[48:51]
	v_mfma_f32_16x16x32_bf16 v[36:39], v[168:171], v[194:197], v[36:39]
	v_mfma_f32_16x16x32_bf16 v[32:35], v[176:179], v[194:197], v[32:35]
	v_mfma_f32_16x16x32_bf16 v[20:23], v[168:171], v[202:205], v[20:23]
	v_mfma_f32_16x16x32_bf16 v[16:19], v[176:179], v[202:205], v[16:19]
	v_mfma_f32_16x16x32_bf16 v[4:7], v[168:171], v[210:213], v[4:7]
	v_mfma_f32_16x16x32_bf16 v[0:3], v[176:179], v[210:213], v[0:3]
	v_mfma_f32_16x16x32_bf16 v[52:55], v[172:175], v[190:193], v[52:55]
	v_mfma_f32_16x16x32_bf16 v[48:51], v[180:183], v[190:193], v[48:51]
	v_mfma_f32_16x16x32_bf16 v[36:39], v[172:175], v[198:201], v[36:39]
	v_mfma_f32_16x16x32_bf16 v[32:35], v[180:183], v[198:201], v[32:35]
	v_mfma_f32_16x16x32_bf16 v[20:23], v[172:175], v[206:209], v[20:23]
	v_mfma_f32_16x16x32_bf16 v[16:19], v[180:183], v[206:209], v[16:19]
	v_mfma_f32_16x16x32_bf16 v[4:7], v[172:175], v[214:217], v[4:7]
	v_mfma_f32_16x16x32_bf16 v[0:3], v[180:183], v[214:217], v[0:3]
	s_setprio 0
	s_barrier
	s_add_i32 s92, s92, 2
	s_add_u32 s44, s44, 0x100
	s_addc_u32 s45, s45, 0
	s_add_u32 s76, s76, 0x100
	s_addc_u32 s77, s77, 0
	s_cmpk_gt_u32 s92, 0x55
	s_cbranch_scc0 .LBB0_828
	s_branch .Lp8_kdone
.Lp8_qloop:
	ds_read_b128 v[142:145], v155
	ds_read_b128 v[146:149], v155 offset:1024
	ds_read_b128 v[160:163], v155 offset:2048
	ds_read_b128 v[164:167], v155 offset:3072
	ds_read_b128 v[168:171], v156
	ds_read_b128 v[172:175], v156 offset:1024
	ds_read_b128 v[176:179], v156 offset:2048
	ds_read_b128 v[180:183], v156 offset:3072
	s_add_u32 s46, s44, 0xffea0080
	s_addc_u32 s47, s45, -1
	s_cmpk_eq_i32 s92, 0x54
	s_cselect_b32 s49, s7, s47
	s_cselect_b32 s48, s6, s46
	s_cselect_b32 s47, s39, s77
	s_cselect_b32 s46, s38, s76
	v_lshl_add_u64 v[150:151], s[44:45], 0, v[134:135]
	s_add_i32 m0, s55, 0xc000
	ds_read_b128 v[186:189], v157
	ds_read_b128 v[190:193], v157 offset:1024
	ds_read_b128 v[194:197], v157 offset:2048
	ds_read_b128 v[198:201], v157 offset:3072
	ds_read_b128 v[202:205], v157 offset:4096
	ds_read_b128 v[206:209], v157 offset:5120
	ds_read_b128 v[210:213], v157 offset:6144
	ds_read_b128 v[214:217], v157 offset:7168
	global_load_lds_dwordx4 v[150:151], off
	v_lshl_add_u64 v[150:151], s[44:45], 0, v[136:137]
	s_add_i32 m0, s55, 0xe000
	s_nop 0
	global_load_lds_dwordx4 v[150:151], off
	s_waitcnt vmcnt(8)
	s_waitcnt lgkmcnt(0)
	s_barrier
	s_setprio 1
	s_waitcnt lgkmcnt(0)
	s_bitcmp1_b32 s32, 0
	s_cbranch_scc0 .Lp8_qskip0
	v_mfma_f32_16x16x32_bf16 v[124:127], v[142:145], v[186:189], v[124:127]
	v_mfma_f32_16x16x32_bf16 v[120:123], v[160:163], v[186:189], v[120:123]
	v_mfma_f32_16x16x32_bf16 v[108:111], v[142:145], v[194:197], v[108:111]
	v_mfma_f32_16x16x32_bf16 v[104:107], v[160:163], v[194:197], v[104:107]
	v_mfma_f32_16x16x32_bf16 v[92:95], v[142:145], v[202:205], v[92:95]
	v_mfma_f32_16x16x32_bf16 v[88:91], v[160:163], v[202:205], v[88:91]
	v_mfma_f32_16x16x32_bf16 v[76:79], v[142:145], v[210:213], v[76:79]
	v_mfma_f32_16x16x32_bf16 v[72:75], v[160:163], v[210:213], v[72:75]
	v_mfma_f32_16x16x32_bf16 v[124:127], v[146:149], v[190:193], v[124:127]
	v_mfma_f32_16x16x32_bf16 v[120:123], v[164:167], v[190:193], v[120:123]
	v_mfma_f32_16x16x32_bf16 v[108:111], v[146:149], v[198:201], v[108:111]
	v_mfma_f32_16x16x32_bf16 v[104:107], v[164:167], v[198:201], v[104:107]
	v_mfma_f32_16x16x32_bf16 v[92:95], v[146:149], v[206:209], v[92:95]
	v_mfma_f32_16x16x32_bf16 v[88:91], v[164:167], v[206:209], v[88:91]
	v_mfma_f32_16x16x32_bf16 v[76:79], v[146:149], v[214:217], v[76:79]
	v_mfma_f32_16x16x32_bf16 v[72:75], v[164:167], v[214:217], v[72:75]
.Lp8_qskip0:
	s_setprio 0
	s_setprio 1
	s_bitcmp1_b32 s32, 1
	s_cbranch_scc0 .Lp8_qskip1
	v_mfma_f32_16x16x32_bf16 v[116:119], v[168:171], v[186:189], v[116:119]
	v_mfma_f32_16x16x32_bf16 v[112:115], v[176:179], v[186:189], v[112:115]
	v_mfma_f32_16x16x32_bf16 v[100:103], v[168:171], v[194:197], v[100:103]
	v_mfma_f32_16x16x32_bf16 v[96:99], v[176:179], v[194:197], v[96:99]
	v_mfma_f32_16x16x32_bf16 v[84:87], v[168:171], v[202:205], v[84:87]
	v_mfma_f32_16x16x32_bf16 v[80:83], v[176:179], v[202:205], v[80:83]
	v_mfma_f32_16x16x32_bf16 v[68:71], v[168:171], v[210:213], v[68:71]
	v_mfma_f32_16x16x32_bf16 v[64:67], v[176:179], v[210:213], v[64:67]
	v_mfma_f32_16x16x32_bf16 v[116:119], v[172:175], v[190:193], v[116:119]
	v_mfma_f32_16x16x32_bf16 v[112:115], v[180:183], v[190:193], v[112:115]
	v_mfma_f32_16x16x32_bf16 v[100:103], v[172:175], v[198:201], v[100:103]
	v_mfma_f32_16x16x32_bf16 v[96:99], v[180:183], v[198:201], v[96:99]
	v_mfma_f32_16x16x32_bf16 v[84:87], v[172:175], v[206:209], v[84:87]
	v_mfma_f32_16x16x32_bf16 v[80:83], v[180:183], v[206:209], v[80:83]
	v_mfma_f32_16x16x32_bf16 v[68:71], v[172:175], v[214:217], v[68:71]
	v_mfma_f32_16x16x32_bf16 v[64:67], v[180:183], v[214:217], v[64:67]
; #define PG8_STAGE(bufoff, gbase, voff) do { _Pragma("unroll") for (int _i = 0; _i < 2; ++_i) \
;         __builtin_amdgcn_global_load_lds((const unsigned*)((const char*)(gbase) + (voff)[_i]), (PG8_LAS unsigned*)(lds + (bufoff) + ldsw + _i * 8192), 16, 0, 0); } while (0)
; #define PG8_LDA(dst, b, h) do { _Pragma("unroll") for (int m = 0; m < 4; ++m) _Pragma("unroll") for (int k = 0; k < 2; ++k) dst[m][k] = *(const PG8_LAS bf16x8*)(lds + PG8_SA(b, h) + aoff + m * 2048 + k * 1024); } while (0)
; #define PG8_LDB(dst, b, h) do { _Pragma("unroll") for (int n = 0; n < 2; ++n) _Pragma("unroll") for (int k = 0; k < 2; ++k) dst[n][k] = *(const PG8_LAS bf16x8*)(lds + PG8_SB(b, h) + boff + n * 2048 + k * 1024); } while (0)
; #define PG8_MMA(ai, bj, At, Bt) do { __builtin_amdgcn_s_setprio(1); _Pragma("unroll") for (int m = 0; m < 4; ++m) _Pragma("unroll") for (int n = 0; n < 2; ++n) _Pragma("unroll") for (int k = 0; k < 2; ++k) \
;         acc[ai][bj][m][n] = __builtin_amdgcn_mfma_f32_16x16x32_bf16(Bt[n][k], At[m][k], acc[ai][bj][m][n], 0, 0, 0); __builtin_amdgcn_s_setprio(0); } while (0)
; #define PG8_WAIT_V(n) asm volatile("s_waitcnt vmcnt(" #n ")" ::: "memory")
; #define PG8_WAIT_L(n) asm volatile("s_waitcnt lgkmcnt(" #n ")" ::: "memory")
; #define PG8_BAR __builtin_amdgcn_s_barrier()
; #define PG8_SCHED __builtin_amdgcn_sched_barrier(0)
; template <class Epi, class Sched, bool ALIGN_EPI = false, bool SP2 = false>
; __device__ __forceinline__ void gemm_phase(PG8_LAS unsigned char* lds, const Gemm g, const Sched& S, const Epi& E) {
;     ...
;             PG8_WAIT_V(8); PG8_WAIT_L(0); PG8_BAR; PG8_MMA(0, 0, At, B0); PG8_MMA(0, 1, At, B1); PG8_BAR; PG8_SCHED;
;             PG8_LDA(At, 0, 1); PG8_STAGE(PG8_SB(0, 0), b2, voffB); PG8_STAGE(PG8_SB(0, 1), b2 + hstep, voffB); PG8_STAGE(PG8_SA(0, 0), a2, voffA);
;             PG8_WAIT_V(8); PG8_WAIT_L(0); PG8_BAR; PG8_MMA(1, 0, At, B0); PG8_MMA(1, 1, At, B1); PG8_BAR; PG8_SCHED;
;             PG8_LDB(B0, 1, 0); PG8_LDB(B1, 1, 1); PG8_SCHED; PG8_LDA(At, 1, 0); PG8_STAGE(PG8_SA(0, 1), a2 + hstep, voffA);
;             PG8_WAIT_V(8); PG8_WAIT_L(0); PG8_BAR; PG8_MMA(0, 0, At, B0); PG8_MMA(0, 1, At, B1); PG8_BAR; PG8_SCHED;
.Lp8_qskip1:
	s_setprio 0
	s_barrier
	s_add_i32 s62, s69, s54
	v_lshl_add_u64 v[150:151], s[46:47], 0, v[128:129]
	s_mov_b32 m0, s62
	ds_read_b128 v[186:189], v157 offset:16384
	ds_read_b128 v[190:193], v157 offset:17408
	ds_read_b128 v[194:197], v157 offset:18432
	ds_read_b128 v[198:201], v157 offset:19456
	ds_read_b128 v[202:205], v157 offset:20480
	ds_read_b128 v[206:209], v157 offset:21504
	ds_read_b128 v[210:213], v157 offset:22528
	ds_read_b128 v[214:217], v157 offset:23552
	global_load_lds_dwordx4 v[150:151], off
	s_add_i32 m0, s62, 0x2000
	s_add_u32 s62, s46, 0x160000
	v_lshl_add_u64 v[218:219], s[46:47], 0, v[130:131]
	s_addc_u32 s63, s47, 0
	s_add_i32 s93, s70, s54
	global_load_lds_dwordx4 v[218:219], off
	v_lshl_add_u64 v[220:221], s[62:63], 0, v[128:129]
	s_mov_b32 m0, s93
	v_lshl_add_u64 v[222:223], s[48:49], 0, v[130:131]
	global_load_lds_dwordx4 v[220:221], off
	v_lshl_add_u64 v[220:221], s[62:63], 0, v[130:131]
	s_add_i32 m0, s93, 0x2000
	s_nop 0
	global_load_lds_dwordx4 v[220:221], off
	v_lshl_add_u64 v[220:221], s[48:49], 0, v[128:129]
	s_mov_b32 m0, s55
	s_nop 0
	global_load_lds_dwordx4 v[220:221], off
	s_mov_b32 m0, s56
	s_nop 0
	global_load_lds_dwordx4 v[222:223], off
	s_waitcnt vmcnt(8)
	s_waitcnt lgkmcnt(0)
	s_barrier
	s_setprio 1
	s_waitcnt lgkmcnt(0)
	s_bitcmp1_b32 s32, 2
	s_cbranch_scc0 .Lp8_qskip2
	v_mfma_f32_16x16x32_bf16 v[60:63], v[142:145], v[186:189], v[60:63]
	v_mfma_f32_16x16x32_bf16 v[56:59], v[160:163], v[186:189], v[56:59]
	v_mfma_f32_16x16x32_bf16 v[44:47], v[142:145], v[194:197], v[44:47]
	v_mfma_f32_16x16x32_bf16 v[40:43], v[160:163], v[194:197], v[40:43]
	v_mfma_f32_16x16x32_bf16 v[28:31], v[142:145], v[202:205], v[28:31]
	v_mfma_f32_16x16x32_bf16 v[24:27], v[160:163], v[202:205], v[24:27]
	v_mfma_f32_16x16x32_bf16 v[12:15], v[142:145], v[210:213], v[12:15]
	v_mfma_f32_16x16x32_bf16 v[8:11], v[160:163], v[210:213], v[8:11]
	v_mfma_f32_16x16x32_bf16 v[60:63], v[146:149], v[190:193], v[60:63]
	v_mfma_f32_16x16x32_bf16 v[56:59], v[164:167], v[190:193], v[56:59]
	v_mfma_f32_16x16x32_bf16 v[44:47], v[146:149], v[198:201], v[44:47]
	v_mfma_f32_16x16x32_bf16 v[40:43], v[164:167], v[198:201], v[40:43]
	v_mfma_f32_16x16x32_bf16 v[28:31], v[146:149], v[206:209], v[28:31]
	v_mfma_f32_16x16x32_bf16 v[24:27], v[164:167], v[206:209], v[24:27]
	v_mfma_f32_16x16x32_bf16 v[12:15], v[146:149], v[214:217], v[12:15]
	v_mfma_f32_16x16x32_bf16 v[8:11], v[164:167], v[214:217], v[8:11]
.Lp8_qskip2:
	s_setprio 0
	s_setprio 1
	s_bitcmp1_b32 s32, 3
	s_cbranch_scc0 .Lp8_qskip3
	v_mfma_f32_16x16x32_bf16 v[52:55], v[168:171], v[186:189], v[52:55]
	v_mfma_f32_16x16x32_bf16 v[48:51], v[176:179], v[186:189], v[48:51]
	v_mfma_f32_16x16x32_bf16 v[36:39], v[168:171], v[194:197], v[36:39]
	v_mfma_f32_16x16x32_bf16 v[32:35], v[176:179], v[194:197], v[32:35]
	v_mfma_f32_16x16x32_bf16 v[20:23], v[168:171], v[202:205], v[20:23]
	v_mfma_f32_16x16x32_bf16 v[16:19], v[176:179], v[202:205], v[16:19]
	v_mfma_f32_16x16x32_bf16 v[4:7], v[168:171], v[210:213], v[4:7]
	v_mfma_f32_16x16x32_bf16 v[0:3], v[176:179], v[210:213], v[0:3]
	v_mfma_f32_16x16x32_bf16 v[52:55], v[172:175], v[190:193], v[52:55]
	v_mfma_f32_16x16x32_bf16 v[48:51], v[180:183], v[190:193], v[48:51]
	v_mfma_f32_16x16x32_bf16 v[36:39], v[172:175], v[198:201], v[36:39]
	v_mfma_f32_16x16x32_bf16 v[32:35], v[180:183], v[198:201], v[32:35]
	v_mfma_f32_16x16x32_bf16 v[20:23], v[172:175], v[206:209], v[20:23]
	v_mfma_f32_16x16x32_bf16 v[16:19], v[180:183], v[206:209], v[16:19]
	v_mfma_f32_16x16x32_bf16 v[4:7], v[172:175], v[214:217], v[4:7]
	v_mfma_f32_16x16x32_bf16 v[0:3], v[180:183], v[214:217], v[0:3]
.Lp8_qskip3:
	s_setprio 0
	s_barrier
	s_add_i32 s62, 0, 0x18000
	v_add_u32_e32 v132, s62, v153
	s_add_i32 s63, 0, 0x1c000
	ds_read_b128 v[142:145], v132
	ds_read_b128 v[146:149], v132 offset:1024
	ds_read_b128 v[160:163], v132 offset:2048
	ds_read_b128 v[164:167], v132 offset:3072
	v_add_u32_e32 v132, s63, v153
	ds_read_b128 v[168:171], v132
	ds_read_b128 v[172:175], v132 offset:1024
	ds_read_b128 v[176:179], v132 offset:2048
	ds_read_b128 v[180:183], v132 offset:3072
	s_add_u32 s48, s48, 0x160000
	s_addc_u32 s49, s49, 0
	s_mov_b32 m0, s57
	v_lshl_add_u64 v[224:225], s[48:49], 0, v[128:129]
	ds_read_b128 v[186:189], v157 offset:32768
	ds_read_b128 v[190:193], v157 offset:33792
	ds_read_b128 v[194:197], v157 offset:34816
	ds_read_b128 v[198:201], v157 offset:35840
	ds_read_b128 v[202:205], v157 offset:36864
	ds_read_b128 v[206:209], v157 offset:37888
	ds_read_b128 v[210:213], v157 offset:38912
	ds_read_b128 v[214:217], v157 offset:39936
	global_load_lds_dwordx4 v[224:225], off
	v_lshl_add_u64 v[224:225], s[48:49], 0, v[130:131]
	s_mov_b32 m0, s58
	s_nop 0
	global_load_lds_dwordx4 v[224:225], off
	s_waitcnt vmcnt(8)
	s_waitcnt lgkmcnt(0)
	s_barrier
	s_setprio 1
	s_waitcnt lgkmcnt(0)
	s_bitcmp1_b32 s32, 0
	s_cbranch_scc0 .Lp8_qskip4
	v_mfma_f32_16x16x32_bf16 v[124:127], v[142:145], v[186:189], v[124:127]
	v_mfma_f32_16x16x32_bf16 v[120:123], v[160:163], v[186:189], v[120:123]
	v_mfma_f32_16x16x32_bf16 v[108:111], v[142:145], v[194:197], v[108:111]
	v_mfma_f32_16x16x32_bf16 v[104:107], v[160:163], v[194:197], v[104:107]
	v_mfma_f32_16x16x32_bf16 v[92:95], v[142:145], v[202:205], v[92:95]
	v_mfma_f32_16x16x32_bf16 v[88:91], v[160:163], v[202:205], v[88:91]
	v_mfma_f32_16x16x32_bf16 v[76:79], v[142:145], v[210:213], v[76:79]
	v_mfma_f32_16x16x32_bf16 v[72:75], v[160:163], v[210:213], v[72:75]
	v_mfma_f32_16x16x32_bf16 v[124:127], v[146:149], v[190:193], v[124:127]
	v_mfma_f32_16x16x32_bf16 v[120:123], v[164:167], v[190:193], v[120:123]
	v_mfma_f32_16x16x32_bf16 v[108:111], v[146:149], v[198:201], v[108:111]
	v_mfma_f32_16x16x32_bf16 v[104:107], v[164:167], v[198:201], v[104:107]
	v_mfma_f32_16x16x32_bf16 v[92:95], v[146:149], v[206:209], v[92:95]
	v_mfma_f32_16x16x32_bf16 v[88:91], v[164:167], v[206:209], v[88:91]
	v_mfma_f32_16x16x32_bf16 v[76:79], v[146:149], v[214:217], v[76:79]
	v_mfma_f32_16x16x32_bf16 v[72:75], v[164:167], v[214:217], v[72:75]

; #define PG8_STAGE(bufoff, gbase, voff) do { _Pragma("unroll") for (int _i = 0; _i < 2; ++_i) \
;         __builtin_amdgcn_global_load_lds((const unsigned*)((const char*)(gbase) + (voff)[_i]), (PG8_LAS unsigned*)(lds + (bufoff) + ldsw + _i * 8192), 16, 0, 0); } while (0)
; #define PG8_LDA(dst, b, h) do { _Pragma("unroll") for (int m = 0; m < 4; ++m) _Pragma("unroll") for (int k = 0; k < 2; ++k) dst[m][k] = *(const PG8_LAS bf16x8*)(lds + PG8_SA(b, h) + aoff + m * 2048 + k * 1024); } while (0)
; #define PG8_MMA(ai, bj, At, Bt) do { __builtin_amdgcn_s_setprio(1); _Pragma("unroll") for (int m = 0; m < 4; ++m) _Pragma("unroll") for (int n = 0; n < 2; ++n) _Pragma("unroll") for (int k = 0; k < 2; ++k) \
;         acc[ai][bj][m][n] = __builtin_amdgcn_mfma_f32_16x16x32_bf16(Bt[n][k], At[m][k], acc[ai][bj][m][n], 0, 0, 0); __builtin_amdgcn_s_setprio(0); } while (0)
; #define PG8_WAIT_V(n) asm volatile("s_waitcnt vmcnt(" #n ")" ::: "memory")
; #define PG8_WAIT_L(n) asm volatile("s_waitcnt lgkmcnt(" #n ")" ::: "memory")
; #define PG8_BAR __builtin_amdgcn_s_barrier()
; #define PG8_SCHED __builtin_amdgcn_sched_barrier(0)
; template <class Epi, class Sched, bool ALIGN_EPI = false, bool SP2 = false>
; __device__ __forceinline__ void gemm_phase(PG8_LAS unsigned char* lds, const Gemm g, const Sched& S, const Epi& E) {
;     ...
;             PG8_LDA(At, 1, 1); PG8_STAGE(PG8_SB(1, 0), b3, voffB); PG8_STAGE(PG8_SB(1, 1), b3 + hstep, voffB); PG8_STAGE(PG8_SA(1, 0), a3, voffA);
;             PG8_WAIT_V(8); PG8_WAIT_L(0); PG8_BAR; PG8_MMA(1, 0, At, B0); PG8_MMA(1, 1, At, B1); PG8_BAR; PG8_SCHED;
.Lp8_qskip5:
	s_setprio 0
	s_barrier
	s_add_i32 s48, s62, s54
	v_lshl_add_u64 v[150:151], v[150:151], 0, s[30:31]
	s_mov_b32 m0, s48
	ds_read_b128 v[186:189], v157 offset:49152
	ds_read_b128 v[190:193], v157 offset:50176
	ds_read_b128 v[194:197], v157 offset:51200
	ds_read_b128 v[198:201], v157 offset:52224
	ds_read_b128 v[202:205], v157 offset:53248
	ds_read_b128 v[206:209], v157 offset:54272
	ds_read_b128 v[210:213], v157 offset:55296
	ds_read_b128 v[214:217], v157 offset:56320
	global_load_lds_dwordx4 v[150:151], off
	s_add_i32 m0, s48, 0x2000
	s_add_u32 s46, s46, 0x160080
	v_lshl_add_u64 v[150:151], v[218:219], 0, s[30:31]
	s_addc_u32 s47, s47, 0
	s_add_i32 s48, s63, s54
	global_load_lds_dwordx4 v[150:151], off
	v_lshl_add_u64 v[150:151], s[46:47], 0, v[128:129]
	s_mov_b32 m0, s48
	s_nop 0
	global_load_lds_dwordx4 v[150:151], off
	v_lshl_add_u64 v[150:151], s[46:47], 0, v[130:131]
	s_add_i32 m0, s48, 0x2000
	s_nop 0
	global_load_lds_dwordx4 v[150:151], off
	v_lshl_add_u64 v[150:151], v[220:221], 0, s[30:31]
	s_mov_b32 m0, s61
	s_nop 0
	global_load_lds_dwordx4 v[150:151], off
	v_lshl_add_u64 v[150:151], v[222:223], 0, s[30:31]
	s_mov_b32 m0, s64
	s_nop 0
	global_load_lds_dwordx4 v[150:151], off
	s_waitcnt vmcnt(8)
	s_waitcnt lgkmcnt(0)
	s_barrier
	s_setprio 1
	s_waitcnt lgkmcnt(0)
	s_bitcmp1_b32 s32, 2
	s_cbranch_scc0 .Lp8_qskip6
	v_mfma_f32_16x16x32_bf16 v[60:63], v[142:145], v[186:189], v[60:63]
	v_mfma_f32_16x16x32_bf16 v[56:59], v[160:163], v[186:189], v[56:59]
	v_mfma_f32_16x16x32_bf16 v[44:47], v[142:145], v[194:197], v[44:47]
	v_mfma_f32_16x16x32_bf16 v[40:43], v[160:163], v[194:197], v[40:43]
	v_mfma_f32_16x16x32_bf16 v[28:31], v[142:145], v[202:205], v[28:31]
	v_mfma_f32_16x16x32_bf16 v[24:27], v[160:163], v[202:205], v[24:27]
	v_mfma_f32_16x16x32_bf16 v[12:15], v[142:145], v[210:213], v[12:15]
	v_mfma_f32_16x16x32_bf16 v[8:11], v[160:163], v[210:213], v[8:11]
	v_mfma_f32_16x16x32_bf16 v[60:63], v[146:149], v[190:193], v[60:63]
	v_mfma_f32_16x16x32_bf16 v[56:59], v[164:167], v[190:193], v[56:59]
	v_mfma_f32_16x16x32_bf16 v[44:47], v[146:149], v[198:201], v[44:47]
	v_mfma_f32_16x16x32_bf16 v[40:43], v[164:167], v[198:201], v[40:43]
	v_mfma_f32_16x16x32_bf16 v[28:31], v[146:149], v[206:209], v[28:31]
	v_mfma_f32_16x16x32_bf16 v[24:27], v[164:167], v[206:209], v[24:27]
	v_mfma_f32_16x16x32_bf16 v[12:15], v[146:149], v[214:217], v[12:15]
	v_mfma_f32_16x16x32_bf16 v[8:11], v[164:167], v[214:217], v[8:11]

; __device__ __forceinline__ unsigned cvt_pk_bf16(float lo, float hi) { unsigned r; asm volatile("v_cvt_pk_bf16_f32 %0, %1, %2" : "=v"(r) : "v"(lo), "v"(hi)); return r; }
; #define PG8_BAR __builtin_amdgcn_s_barrier()
; template <class Epi, class Sched, bool ALIGN_EPI = false, bool SP2 = false>
; __device__ __forceinline__ void gemm_phase(PG8_LAS unsigned char* lds, const Gemm g, const Sched& S, const Epi& E) {
;     ...
;         if constexpr (ALIGN_EPI) { if (wr == 0) PG8_BAR; }
;         if constexpr (!Epi::AFTER_DRAIN) { E(acc, cur, wr, wc, fr, fq); S.done(cur); }
;     __device__ __forceinline__ void operator()(const gacc_t (&acc)[2][2][4][2], const Unit& u, int wr, int wc, int fr, int fq) const {
;     ...
;             for (int m = 0; m < 4; ++m) { const int row = u.pm * 256 + ai * 128 + wr * 64 + m * 16 + fr;
;                 const float* bp = row < ML ? baseL + (size_t)row * D : baseC + (size_t)(row - ML) * D;
;                 const int mb = row < ML ? (row >> 11) : 8; const float* gp = mod + mb * MODW + chunk * D; float* op = out + (size_t)row * D;
;                 float sq = 0.f;
; #pragma unroll
;                 for (int bj = 0; bj < 2; ++bj)
; #pragma unroll
;                     for (int n = 0; n < 2; ++n) { const int col = u.pn * 256 + bj * 128 + wc * 32 + n * 16 + 4 * fq;
;                         const f32x4 b = *(const f32x4*)(bp + col), g = *(const f32x4*)(gp + col); const gacc_t a = acc[ai][bj][m][n];
;                         f32x4 o; o.x = b.x + g.x * a[0]; o.y = b.y + g.y * a[1]; o.z = b.z + g.z * a[2]; o.w = b.w + g.w * a[3];
;                         *(f32x4*)(op + col) = o;
;                         if (hu) { const f32x4 gg = *(const f32x4*)(gn + col), sc = *(const f32x4*)(scl + mb * MODW + col);
;                             sq += (o.x * o.x + o.y * o.y) + (o.z * o.z + o.w * o.w);
;                             u32x2 w; w.x = pg8::cvt_pk_bf16(o.x * gg.x * (1.f + sc.x), o.y * gg.y * (1.f + sc.y)); w.y = pg8::cvt_pk_bf16(o.z * gg.z * (1.f + sc.z), o.w * gg.w * (1.f + sc.w));
;                             *(u32x2*)(hu + (size_t)row * D + col) = w; } }
.Lp8_qskip7:
	s_setprio 0
	s_barrier
	s_add_i32 s92, s92, 2
	s_add_u32 s44, s44, 0x100
	s_addc_u32 s45, s45, 0
	s_add_u32 s76, s76, 0x100
	s_addc_u32 s77, s77, 0
	s_cmpk_gt_u32 s92, 0x55
	s_cbranch_scc0 .Lp8_qloop
	s_branch .Lp8_kdone
.Lp8_kdone:
	s_and_b64 vcc, exec, s[34:35]
	s_cbranch_vccz .LBB0_831
	s_barrier
.LBB0_831:
	s_lshl_b32 s48, s75, 8
	s_add_i32 s48, s48, s60
	s_lshr_b32 s45, s48, 11
	s_mul_i32 s45, s45, 0xc000
	s_cmpk_gt_i32 s48, 0x3fff
	s_cselect_b32 s45, 0x60000, s45
	s_cselect_b32 s46, s22, s10
	s_cselect_b32 s47, s23, s11
	v_lshl_or_b32 v132, s74, 8, v154
	v_lshlrev_b32_e32 v132, 2, v132
	v_add_u32_e32 v222, s45, v132
	v_add_u32_e32 v223, s36, v222
	v_add_u32_e32 v220, s48, v152
	v_lshl_add_u32 v219, v220, 13, v132
	s_cselect_b32 s45, 0x8000000, 0
	s_sub_u32 s46, s46, s45
	s_subb_u32 s47, s47, 0
	s_cmp_lg_u32 s32, 15
	s_cbranch_scc1 .Lp8_qepi
	v_mov_b32_e32 v218, v219
	global_load_dwordx4 v[142:145], v222, s[26:27] offset:0
	global_load_dwordx4 v[146:149], v222, s[26:27] offset:64
	global_load_dwordx4 v[176:179], v222, s[26:27] offset:512
	global_load_dwordx4 v[180:183], v222, s[26:27] offset:576
	global_load_dwordx4 v[186:189], v132, s[24:25] offset:0
	global_load_dwordx4 v[190:193], v132, s[24:25] offset:64
	global_load_dwordx4 v[194:197], v132, s[24:25] offset:512
	global_load_dwordx4 v[198:201], v132, s[24:25] offset:576
	global_load_dwordx4 v[160:163], v223, s[8:9] offset:0
	global_load_dwordx4 v[164:167], v223, s[8:9] offset:64
	global_load_dwordx4 v[168:171], v223, s[8:9] offset:512
	global_load_dwordx4 v[172:175], v223, s[8:9] offset:576
	global_load_dwordx4 v[202:205], v218, s[46:47] offset:0
	global_load_dwordx4 v[206:209], v218, s[46:47] offset:64
	global_load_dwordx4 v[210:213], v218, s[46:47] offset:512
	global_load_dwordx4 v[214:217], v218, s[46:47] offset:576
	v_add_u32_e32 v218, 0x20000, v218
	s_waitcnt vmcnt(8)
	v_add_f32_e32 v142, 1.0, v142
	v_add_f32_e32 v143, 1.0, v143
	v_add_f32_e32 v144, 1.0, v144
	v_add_f32_e32 v145, 1.0, v145
	v_add_f32_e32 v146, 1.0, v146
	v_add_f32_e32 v147, 1.0, v147
	v_add_f32_e32 v148, 1.0, v148
	v_add_f32_e32 v149, 1.0, v149
	v_add_f32_e32 v176, 1.0, v176
	v_add_f32_e32 v177, 1.0, v177
	v_add_f32_e32 v178, 1.0, v178
	v_add_f32_e32 v179, 1.0, v179
	v_add_f32_e32 v180, 1.0, v180
	v_add_f32_e32 v181, 1.0, v181
	v_add_f32_e32 v182, 1.0, v182
	v_add_f32_e32 v183, 1.0, v183
	v_mul_f32_e32 v186, v186, v142
	v_mul_f32_e32 v187, v187, v143
	v_mul_f32_e32 v188, v188, v144
	v_mul_f32_e32 v189, v189, v145
	v_mul_f32_e32 v190, v190, v146
	v_mul_f32_e32 v191, v191, v147
	v_mul_f32_e32 v192, v192, v148
	v_mul_f32_e32 v193, v193, v149
	v_mul_f32_e32 v194, v194, v176
	v_mul_f32_e32 v195, v195, v177
	v_mul_f32_e32 v196, v196, v178
	v_mul_f32_e32 v197, v197, v179
	v_mul_f32_e32 v198, v198, v180
	v_mul_f32_e32 v199, v199, v181
	v_mul_f32_e32 v200, v200, v182
	v_mul_f32_e32 v201, v201, v183
	global_load_dwordx4 v[142:145], v218, s[46:47] offset:0
	global_load_dwordx4 v[146:149], v218, s[46:47] offset:64
	global_load_dwordx4 v[176:179], v218, s[46:47] offset:512
	global_load_dwordx4 v[180:183], v218, s[46:47] offset:576
	v_add_u32_e32 v218, 0x20000, v218
	s_waitcnt vmcnt(4)
	v_pk_fma_f32 v[126:127], v[126:127], v[162:163], v[204:205]
	v_pk_fma_f32 v[124:125], v[124:125], v[160:161], v[202:203]
	global_store_dwordx4 v219, v[124:127], s[10:11] offset:0
	v_pk_fma_f32 v[122:123], v[122:123], v[166:167], v[208:209]
	v_pk_fma_f32 v[120:121], v[120:121], v[164:165], v[206:207]
	global_store_dwordx4 v219, v[120:123], s[10:11] offset:64
	v_pk_fma_f32 v[118:119], v[118:119], v[170:171], v[212:213]
	v_pk_fma_f32 v[116:117], v[116:117], v[168:169], v[210:211]
	global_store_dwordx4 v219, v[116:119], s[10:11] offset:512
	v_pk_fma_f32 v[114:115], v[114:115], v[174:175], v[216:217]
	v_pk_fma_f32 v[112:113], v[112:113], v[172:173], v[214:215]
	global_store_dwordx4 v219, v[112:115], s[10:11] offset:576
	v_lshrrev_b32_e32 v220, 1, v219
	v_mul_f32_e32 v202, v124, v186
	v_mul_f32_e32 v203, v125, v187
	v_mul_f32_e32 v204, v126, v188
	v_mul_f32_e32 v205, v127, v189
	v_mul_f32_e32 v221, v124, v124
	v_fmac_f32_e32 v221, v125, v125
	v_fmac_f32_e32 v221, v126, v126
	v_fmac_f32_e32 v221, v127, v127
	v_cvt_pk_bf16_f32 v202, v202, v203
	v_cvt_pk_bf16_f32 v203, v204, v205
	global_store_dwordx2 v220, v[202:203], s[14:15] offset:0
	v_mul_f32_e32 v206, v120, v190
	v_mul_f32_e32 v207, v121, v191
	v_mul_f32_e32 v208, v122, v192
	v_mul_f32_e32 v209, v123, v193
	v_fmac_f32_e32 v221, v120, v120
	v_fmac_f32_e32 v221, v121, v121
	v_fmac_f32_e32 v221, v122, v122
	v_fmac_f32_e32 v221, v123, v123
	v_cvt_pk_bf16_f32 v206, v206, v207
	v_cvt_pk_bf16_f32 v207, v208, v209
	global_store_dwordx2 v220, v[206:207], s[14:15] offset:32
	v_mul_f32_e32 v210, v116, v194
	v_mul_f32_e32 v211, v117, v195
	v_mul_f32_e32 v212, v118, v196
	v_mul_f32_e32 v213, v119, v197
	v_fmac_f32_e32 v221, v116, v116
	v_fmac_f32_e32 v221, v117, v117
	v_fmac_f32_e32 v221, v118, v118
	v_fmac_f32_e32 v221, v119, v119
	v_cvt_pk_bf16_f32 v210, v210, v211
	v_cvt_pk_bf16_f32 v211, v212, v213
	global_store_dwordx2 v220, v[210:211], s[14:15] offset:256
	v_mul_f32_e32 v214, v112, v198
	v_mul_f32_e32 v215, v113, v199
	v_mul_f32_e32 v216, v114, v200
	v_mul_f32_e32 v217, v115, v201
	v_fmac_f32_e32 v221, v112, v112
	v_fmac_f32_e32 v221, v113, v113
	v_fmac_f32_e32 v221, v114, v114
	v_fmac_f32_e32 v221, v115, v115
	v_cvt_pk_bf16_f32 v214, v214, v215
	v_cvt_pk_bf16_f32 v215, v216, v217
	global_store_dwordx2 v220, v[214:215], s[14:15] offset:288
	v_mov_b32_e32 v124, v221
	global_load_dwordx4 v[202:205], v218, s[46:47] offset:0
	global_load_dwordx4 v[206:209], v218, s[46:47] offset:64
	global_load_dwordx4 v[210:213], v218, s[46:47] offset:512
	global_load_dwordx4 v[214:217], v218, s[46:47] offset:576
	v_add_u32_e32 v218, 0x20000, v218
	v_add_u32_e32 v219, 0x20000, v219
	s_waitcnt vmcnt(12)
; __device__ __forceinline__ unsigned cvt_pk_bf16(float lo, float hi) { unsigned r; asm volatile("v_cvt_pk_bf16_f32 %0, %1, %2" : "=v"(r) : "v"(lo), "v"(hi)); return r; }
;     __device__ __forceinline__ void operator()(const gacc_t (&acc)[2][2][4][2], const Unit& u, int wr, int wc, int fr, int fq) const {
;     ...
;                 for (int bj = 0; bj < 2; ++bj)
; #pragma unroll
;                     for (int n = 0; n < 2; ++n) { const int col = u.pn * 256 + bj * 128 + wc * 32 + n * 16 + 4 * fq;
;                         const f32x4 b = *(const f32x4*)(bp + col), g = *(const f32x4*)(gp + col); const gacc_t a = acc[ai][bj][m][n];
;                         f32x4 o; o.x = b.x + g.x * a[0]; o.y = b.y + g.y * a[1]; o.z = b.z + g.z * a[2]; o.w = b.w + g.w * a[3];
;                         *(f32x4*)(op + col) = o;
;                         if (hu) { const f32x4 gg = *(const f32x4*)(gn + col), sc = *(const f32x4*)(scl + mb * MODW + col);
;                             sq += (o.x * o.x + o.y * o.y) + (o.z * o.z + o.w * o.w);
;                             u32x2 w; w.x = pg8::cvt_pk_bf16(o.x * gg.x * (1.f + sc.x), o.y * gg.y * (1.f + sc.y)); w.y = pg8::cvt_pk_bf16(o.z * gg.z * (1.f + sc.z), o.w * gg.w * (1.f + sc.w));
;                             *(u32x2*)(hu + (size_t)row * D + col) = w; } }
	v_pk_fma_f32 v[110:111], v[110:111], v[162:163], v[144:145]
	v_pk_fma_f32 v[108:109], v[108:109], v[160:161], v[142:143]
	global_store_dwordx4 v219, v[108:111], s[10:11] offset:0
	v_pk_fma_f32 v[106:107], v[106:107], v[166:167], v[148:149]
	v_pk_fma_f32 v[104:105], v[104:105], v[164:165], v[146:147]
	global_store_dwordx4 v219, v[104:107], s[10:11] offset:64
	v_pk_fma_f32 v[102:103], v[102:103], v[170:171], v[178:179]
	v_pk_fma_f32 v[100:101], v[100:101], v[168:169], v[176:177]
	global_store_dwordx4 v219, v[100:103], s[10:11] offset:512
	v_pk_fma_f32 v[98:99], v[98:99], v[174:175], v[182:183]
	v_pk_fma_f32 v[96:97], v[96:97], v[172:173], v[180:181]
	global_store_dwordx4 v219, v[96:99], s[10:11] offset:576
	v_lshrrev_b32_e32 v220, 1, v219
	v_mul_f32_e32 v142, v108, v186
	v_mul_f32_e32 v143, v109, v187
	v_mul_f32_e32 v144, v110, v188
	v_mul_f32_e32 v145, v111, v189
	v_mul_f32_e32 v221, v108, v108
	v_fmac_f32_e32 v221, v109, v109
	v_fmac_f32_e32 v221, v110, v110
	v_fmac_f32_e32 v221, v111, v111
	v_cvt_pk_bf16_f32 v142, v142, v143
	v_cvt_pk_bf16_f32 v143, v144, v145
	global_store_dwordx2 v220, v[142:143], s[14:15] offset:0
	v_mul_f32_e32 v146, v104, v190
	v_mul_f32_e32 v147, v105, v191
	v_mul_f32_e32 v148, v106, v192
	v_mul_f32_e32 v149, v107, v193
	v_fmac_f32_e32 v221, v104, v104
	v_fmac_f32_e32 v221, v105, v105
	v_fmac_f32_e32 v221, v106, v106
	v_fmac_f32_e32 v221, v107, v107
	v_cvt_pk_bf16_f32 v146, v146, v147
	v_cvt_pk_bf16_f32 v147, v148, v149
	global_store_dwordx2 v220, v[146:147], s[14:15] offset:32
	v_mul_f32_e32 v176, v100, v194
	v_mul_f32_e32 v177, v101, v195
	v_mul_f32_e32 v178, v102, v196
	v_mul_f32_e32 v179, v103, v197
	v_fmac_f32_e32 v221, v100, v100
	v_fmac_f32_e32 v221, v101, v101
	v_fmac_f32_e32 v221, v102, v102
	v_fmac_f32_e32 v221, v103, v103
	v_cvt_pk_bf16_f32 v176, v176, v177
	v_cvt_pk_bf16_f32 v177, v178, v179
	global_store_dwordx2 v220, v[176:177], s[14:15] offset:256
	v_mul_f32_e32 v180, v96, v198
	v_mul_f32_e32 v181, v97, v199
	v_mul_f32_e32 v182, v98, v200
	v_mul_f32_e32 v183, v99, v201
	v_fmac_f32_e32 v221, v96, v96
	v_fmac_f32_e32 v221, v97, v97
	v_fmac_f32_e32 v221, v98, v98
	v_fmac_f32_e32 v221, v99, v99
	v_cvt_pk_bf16_f32 v180, v180, v181
	v_cvt_pk_bf16_f32 v181, v182, v183
	global_store_dwordx2 v220, v[180:181], s[14:15] offset:288
	v_mov_b32_e32 v108, v221
	global_load_dwordx4 v[142:145], v218, s[46:47] offset:0
	global_load_dwordx4 v[146:149], v218, s[46:47] offset:64
	global_load_dwordx4 v[176:179], v218, s[46:47] offset:512
	global_load_dwordx4 v[180:183], v218, s[46:47] offset:576
	v_add_u32_e32 v218, 0xa0000, v218
	v_add_u32_e32 v219, 0x20000, v219
	s_waitcnt vmcnt(12)
	v_pk_fma_f32 v[94:95], v[94:95], v[162:163], v[204:205]
	v_pk_fma_f32 v[92:93], v[92:93], v[160:161], v[202:203]
	global_store_dwordx4 v219, v[92:95], s[10:11] offset:0
	v_pk_fma_f32 v[90:91], v[90:91], v[166:167], v[208:209]
	v_pk_fma_f32 v[88:89], v[88:89], v[164:165], v[206:207]
	global_store_dwordx4 v219, v[88:91], s[10:11] offset:64
	v_pk_fma_f32 v[86:87], v[86:87], v[170:171], v[212:213]
	v_pk_fma_f32 v[84:85], v[84:85], v[168:169], v[210:211]
	global_store_dwordx4 v219, v[84:87], s[10:11] offset:512
	v_pk_fma_f32 v[82:83], v[82:83], v[174:175], v[216:217]
	v_pk_fma_f32 v[80:81], v[80:81], v[172:173], v[214:215]
	global_store_dwordx4 v219, v[80:83], s[10:11] offset:576
	v_lshrrev_b32_e32 v220, 1, v219
	v_mul_f32_e32 v202, v92, v186
	v_mul_f32_e32 v203, v93, v187
	v_mul_f32_e32 v204, v94, v188
	v_mul_f32_e32 v205, v95, v189
	v_mul_f32_e32 v221, v92, v92
	v_fmac_f32_e32 v221, v93, v93
	v_fmac_f32_e32 v221, v94, v94
	v_fmac_f32_e32 v221, v95, v95
	v_cvt_pk_bf16_f32 v202, v202, v203
	v_cvt_pk_bf16_f32 v203, v204, v205
	global_store_dwordx2 v220, v[202:203], s[14:15] offset:0
	v_mul_f32_e32 v206, v88, v190
	v_mul_f32_e32 v207, v89, v191
	v_mul_f32_e32 v208, v90, v192
	v_mul_f32_e32 v209, v91, v193
	v_fmac_f32_e32 v221, v88, v88
	v_fmac_f32_e32 v221, v89, v89
	v_fmac_f32_e32 v221, v90, v90
	v_fmac_f32_e32 v221, v91, v91
	v_cvt_pk_bf16_f32 v206, v206, v207
	v_cvt_pk_bf16_f32 v207, v208, v209
	global_store_dwordx2 v220, v[206:207], s[14:15] offset:32
	v_mul_f32_e32 v210, v84, v194
	v_mul_f32_e32 v211, v85, v195
	v_mul_f32_e32 v212, v86, v196
	v_mul_f32_e32 v213, v87, v197
	v_fmac_f32_e32 v221, v84, v84
	v_fmac_f32_e32 v221, v85, v85
	v_fmac_f32_e32 v221, v86, v86
	v_fmac_f32_e32 v221, v87, v87
	v_cvt_pk_bf16_f32 v210, v210, v211
	v_cvt_pk_bf16_f32 v211, v212, v213
	global_store_dwordx2 v220, v[210:211], s[14:15] offset:256
	v_mul_f32_e32 v214, v80, v198
	v_mul_f32_e32 v215, v81, v199
	v_mul_f32_e32 v216, v82, v200
	v_mul_f32_e32 v217, v83, v201
	v_fmac_f32_e32 v221, v80, v80
	v_fmac_f32_e32 v221, v81, v81
	v_fmac_f32_e32 v221, v82, v82
	v_fmac_f32_e32 v221, v83, v83
	v_cvt_pk_bf16_f32 v214, v214, v215
	v_cvt_pk_bf16_f32 v215, v216, v217
	global_store_dwordx2 v220, v[214:215], s[14:15] offset:288
	v_mov_b32_e32 v92, v221
	global_load_dwordx4 v[202:205], v218, s[46:47] offset:0
	global_load_dwordx4 v[206:209], v218, s[46:47] offset:64
	global_load_dwordx4 v[210:213], v218, s[46:47] offset:512
	global_load_dwordx4 v[214:217], v218, s[46:47] offset:576
	v_add_u32_e32 v218, 0x20000, v218
	v_add_u32_e32 v219, 0x20000, v219
	s_waitcnt vmcnt(12)
; __device__ __forceinline__ unsigned cvt_pk_bf16(float lo, float hi) { unsigned r; asm volatile("v_cvt_pk_bf16_f32 %0, %1, %2" : "=v"(r) : "v"(lo), "v"(hi)); return r; }
;     __device__ __forceinline__ void operator()(const gacc_t (&acc)[2][2][4][2], const Unit& u, int wr, int wc, int fr, int fq) const {
;     ...
;                 for (int bj = 0; bj < 2; ++bj)
; #pragma unroll
;                     for (int n = 0; n < 2; ++n) { const int col = u.pn * 256 + bj * 128 + wc * 32 + n * 16 + 4 * fq;
;                         const f32x4 b = *(const f32x4*)(bp + col), g = *(const f32x4*)(gp + col); const gacc_t a = acc[ai][bj][m][n];
;                         f32x4 o; o.x = b.x + g.x * a[0]; o.y = b.y + g.y * a[1]; o.z = b.z + g.z * a[2]; o.w = b.w + g.w * a[3];
;                         *(f32x4*)(op + col) = o;
;                         if (hu) { const f32x4 gg = *(const f32x4*)(gn + col), sc = *(const f32x4*)(scl + mb * MODW + col);
;                             sq += (o.x * o.x + o.y * o.y) + (o.z * o.z + o.w * o.w);
;                             u32x2 w; w.x = pg8::cvt_pk_bf16(o.x * gg.x * (1.f + sc.x), o.y * gg.y * (1.f + sc.y)); w.y = pg8::cvt_pk_bf16(o.z * gg.z * (1.f + sc.z), o.w * gg.w * (1.f + sc.w));
;                             *(u32x2*)(hu + (size_t)row * D + col) = w; } }
	v_pk_fma_f32 v[78:79], v[78:79], v[162:163], v[144:145]
	v_pk_fma_f32 v[76:77], v[76:77], v[160:161], v[142:143]
	global_store_dwordx4 v219, v[76:79], s[10:11] offset:0
	v_pk_fma_f32 v[74:75], v[74:75], v[166:167], v[148:149]
	v_pk_fma_f32 v[72:73], v[72:73], v[164:165], v[146:147]
	global_store_dwordx4 v219, v[72:75], s[10:11] offset:64
	v_pk_fma_f32 v[70:71], v[70:71], v[170:171], v[178:179]
	v_pk_fma_f32 v[68:69], v[68:69], v[168:169], v[176:177]
	global_store_dwordx4 v219, v[68:71], s[10:11] offset:512
	v_pk_fma_f32 v[66:67], v[66:67], v[174:175], v[182:183]
	v_pk_fma_f32 v[64:65], v[64:65], v[172:173], v[180:181]
	global_store_dwordx4 v219, v[64:67], s[10:11] offset:576
	v_lshrrev_b32_e32 v220, 1, v219
	v_mul_f32_e32 v142, v76, v186
	v_mul_f32_e32 v143, v77, v187
	v_mul_f32_e32 v144, v78, v188
	v_mul_f32_e32 v145, v79, v189
	v_mul_f32_e32 v221, v76, v76
	v_fmac_f32_e32 v221, v77, v77
	v_fmac_f32_e32 v221, v78, v78
	v_fmac_f32_e32 v221, v79, v79
	v_cvt_pk_bf16_f32 v142, v142, v143
	v_cvt_pk_bf16_f32 v143, v144, v145
	global_store_dwordx2 v220, v[142:143], s[14:15] offset:0
	v_mul_f32_e32 v146, v72, v190
	v_mul_f32_e32 v147, v73, v191
	v_mul_f32_e32 v148, v74, v192
	v_mul_f32_e32 v149, v75, v193
	v_fmac_f32_e32 v221, v72, v72
	v_fmac_f32_e32 v221, v73, v73
	v_fmac_f32_e32 v221, v74, v74
	v_fmac_f32_e32 v221, v75, v75
	v_cvt_pk_bf16_f32 v146, v146, v147
	v_cvt_pk_bf16_f32 v147, v148, v149
	global_store_dwordx2 v220, v[146:147], s[14:15] offset:32
	v_mul_f32_e32 v176, v68, v194
	v_mul_f32_e32 v177, v69, v195
	v_mul_f32_e32 v178, v70, v196
	v_mul_f32_e32 v179, v71, v197
	v_fmac_f32_e32 v221, v68, v68
	v_fmac_f32_e32 v221, v69, v69
	v_fmac_f32_e32 v221, v70, v70
	v_fmac_f32_e32 v221, v71, v71
	v_cvt_pk_bf16_f32 v176, v176, v177
	v_cvt_pk_bf16_f32 v177, v178, v179
	global_store_dwordx2 v220, v[176:177], s[14:15] offset:256
	v_mul_f32_e32 v180, v64, v198
	v_mul_f32_e32 v181, v65, v199
	v_mul_f32_e32 v182, v66, v200
	v_mul_f32_e32 v183, v67, v201
	v_fmac_f32_e32 v221, v64, v64
	v_fmac_f32_e32 v221, v65, v65
	v_fmac_f32_e32 v221, v66, v66
	v_fmac_f32_e32 v221, v67, v67
	v_cvt_pk_bf16_f32 v180, v180, v181
	v_cvt_pk_bf16_f32 v181, v182, v183
	global_store_dwordx2 v220, v[180:181], s[14:15] offset:288
	v_mov_b32_e32 v76, v221
	global_load_dwordx4 v[142:145], v218, s[46:47] offset:0
	global_load_dwordx4 v[146:149], v218, s[46:47] offset:64
	global_load_dwordx4 v[176:179], v218, s[46:47] offset:512
	global_load_dwordx4 v[180:183], v218, s[46:47] offset:576
	v_add_u32_e32 v218, 0x20000, v218
	v_add_u32_e32 v219, 0xa0000, v219
	s_waitcnt vmcnt(12)
	v_pk_fma_f32 v[62:63], v[62:63], v[162:163], v[204:205]
	v_pk_fma_f32 v[60:61], v[60:61], v[160:161], v[202:203]
	global_store_dwordx4 v219, v[60:63], s[10:11] offset:0
	v_pk_fma_f32 v[58:59], v[58:59], v[166:167], v[208:209]
	v_pk_fma_f32 v[56:57], v[56:57], v[164:165], v[206:207]
	global_store_dwordx4 v219, v[56:59], s[10:11] offset:64
	v_pk_fma_f32 v[54:55], v[54:55], v[170:171], v[212:213]
	v_pk_fma_f32 v[52:53], v[52:53], v[168:169], v[210:211]
	global_store_dwordx4 v219, v[52:55], s[10:11] offset:512
	v_pk_fma_f32 v[50:51], v[50:51], v[174:175], v[216:217]
	v_pk_fma_f32 v[48:49], v[48:49], v[172:173], v[214:215]
	global_store_dwordx4 v219, v[48:51], s[10:11] offset:576
	v_lshrrev_b32_e32 v220, 1, v219
	v_mul_f32_e32 v202, v60, v186
	v_mul_f32_e32 v203, v61, v187
	v_mul_f32_e32 v204, v62, v188
	v_mul_f32_e32 v205, v63, v189
	v_mul_f32_e32 v221, v60, v60
	v_fmac_f32_e32 v221, v61, v61
	v_fmac_f32_e32 v221, v62, v62
	v_fmac_f32_e32 v221, v63, v63
	v_cvt_pk_bf16_f32 v202, v202, v203
	v_cvt_pk_bf16_f32 v203, v204, v205
	global_store_dwordx2 v220, v[202:203], s[14:15] offset:0
	v_mul_f32_e32 v206, v56, v190
	v_mul_f32_e32 v207, v57, v191
	v_mul_f32_e32 v208, v58, v192
	v_mul_f32_e32 v209, v59, v193
	v_fmac_f32_e32 v221, v56, v56
	v_fmac_f32_e32 v221, v57, v57
	v_fmac_f32_e32 v221, v58, v58
	v_fmac_f32_e32 v221, v59, v59
	v_cvt_pk_bf16_f32 v206, v206, v207
	v_cvt_pk_bf16_f32 v207, v208, v209
	global_store_dwordx2 v220, v[206:207], s[14:15] offset:32
	v_mul_f32_e32 v210, v52, v194
	v_mul_f32_e32 v211, v53, v195
	v_mul_f32_e32 v212, v54, v196
	v_mul_f32_e32 v213, v55, v197
	v_fmac_f32_e32 v221, v52, v52
	v_fmac_f32_e32 v221, v53, v53
	v_fmac_f32_e32 v221, v54, v54
	v_fmac_f32_e32 v221, v55, v55
	v_cvt_pk_bf16_f32 v210, v210, v211
	v_cvt_pk_bf16_f32 v211, v212, v213
	global_store_dwordx2 v220, v[210:211], s[14:15] offset:256
	v_mul_f32_e32 v214, v48, v198
	v_mul_f32_e32 v215, v49, v199
	v_mul_f32_e32 v216, v50, v200
	v_mul_f32_e32 v217, v51, v201
	v_fmac_f32_e32 v221, v48, v48
	v_fmac_f32_e32 v221, v49, v49
	v_fmac_f32_e32 v221, v50, v50
	v_fmac_f32_e32 v221, v51, v51
	v_cvt_pk_bf16_f32 v214, v214, v215
	v_cvt_pk_bf16_f32 v215, v216, v217
	global_store_dwordx2 v220, v[214:215], s[14:15] offset:288
	v_mov_b32_e32 v60, v221
	global_load_dwordx4 v[202:205], v218, s[46:47] offset:0
	global_load_dwordx4 v[206:209], v218, s[46:47] offset:64
	global_load_dwordx4 v[210:213], v218, s[46:47] offset:512
	global_load_dwordx4 v[214:217], v218, s[46:47] offset:576
	v_add_u32_e32 v218, 0x20000, v218
	v_add_u32_e32 v219, 0x20000, v219
	s_waitcnt vmcnt(12)
; __device__ __forceinline__ unsigned cvt_pk_bf16(float lo, float hi) { unsigned r; asm volatile("v_cvt_pk_bf16_f32 %0, %1, %2" : "=v"(r) : "v"(lo), "v"(hi)); return r; }
;     __device__ __forceinline__ void operator()(const gacc_t (&acc)[2][2][4][2], const Unit& u, int wr, int wc, int fr, int fq) const {
;     ...
;                 for (int bj = 0; bj < 2; ++bj)
; #pragma unroll
;                     for (int n = 0; n < 2; ++n) { const int col = u.pn * 256 + bj * 128 + wc * 32 + n * 16 + 4 * fq;
;                         const f32x4 b = *(const f32x4*)(bp + col), g = *(const f32x4*)(gp + col); const gacc_t a = acc[ai][bj][m][n];
;                         f32x4 o; o.x = b.x + g.x * a[0]; o.y = b.y + g.y * a[1]; o.z = b.z + g.z * a[2]; o.w = b.w + g.w * a[3];
;                         *(f32x4*)(op + col) = o;
;                         if (hu) { const f32x4 gg = *(const f32x4*)(gn + col), sc = *(const f32x4*)(scl + mb * MODW + col);
;                             sq += (o.x * o.x + o.y * o.y) + (o.z * o.z + o.w * o.w);
;                             u32x2 w; w.x = pg8::cvt_pk_bf16(o.x * gg.x * (1.f + sc.x), o.y * gg.y * (1.f + sc.y)); w.y = pg8::cvt_pk_bf16(o.z * gg.z * (1.f + sc.z), o.w * gg.w * (1.f + sc.w));
;                             *(u32x2*)(hu + (size_t)row * D + col) = w; } }
	v_pk_fma_f32 v[46:47], v[46:47], v[162:163], v[144:145]
	v_pk_fma_f32 v[44:45], v[44:45], v[160:161], v[142:143]
	global_store_dwordx4 v219, v[44:47], s[10:11] offset:0
	v_pk_fma_f32 v[42:43], v[42:43], v[166:167], v[148:149]
	v_pk_fma_f32 v[40:41], v[40:41], v[164:165], v[146:147]
	global_store_dwordx4 v219, v[40:43], s[10:11] offset:64
	v_pk_fma_f32 v[38:39], v[38:39], v[170:171], v[178:179]
	v_pk_fma_f32 v[36:37], v[36:37], v[168:169], v[176:177]
	global_store_dwordx4 v219, v[36:39], s[10:11] offset:512
	v_pk_fma_f32 v[34:35], v[34:35], v[174:175], v[182:183]
	v_pk_fma_f32 v[32:33], v[32:33], v[172:173], v[180:181]
	global_store_dwordx4 v219, v[32:35], s[10:11] offset:576
	v_lshrrev_b32_e32 v220, 1, v219
	v_mul_f32_e32 v142, v44, v186
	v_mul_f32_e32 v143, v45, v187
	v_mul_f32_e32 v144, v46, v188
	v_mul_f32_e32 v145, v47, v189
	v_mul_f32_e32 v221, v44, v44
	v_fmac_f32_e32 v221, v45, v45
	v_fmac_f32_e32 v221, v46, v46
	v_fmac_f32_e32 v221, v47, v47
	v_cvt_pk_bf16_f32 v142, v142, v143
	v_cvt_pk_bf16_f32 v143, v144, v145
	global_store_dwordx2 v220, v[142:143], s[14:15] offset:0
	v_mul_f32_e32 v146, v40, v190
	v_mul_f32_e32 v147, v41, v191
	v_mul_f32_e32 v148, v42, v192
	v_mul_f32_e32 v149, v43, v193
	v_fmac_f32_e32 v221, v40, v40
	v_fmac_f32_e32 v221, v41, v41
	v_fmac_f32_e32 v221, v42, v42
	v_fmac_f32_e32 v221, v43, v43
	v_cvt_pk_bf16_f32 v146, v146, v147
	v_cvt_pk_bf16_f32 v147, v148, v149
	global_store_dwordx2 v220, v[146:147], s[14:15] offset:32
	v_mul_f32_e32 v176, v36, v194
	v_mul_f32_e32 v177, v37, v195
	v_mul_f32_e32 v178, v38, v196
	v_mul_f32_e32 v179, v39, v197
	v_fmac_f32_e32 v221, v36, v36
	v_fmac_f32_e32 v221, v37, v37
	v_fmac_f32_e32 v221, v38, v38
	v_fmac_f32_e32 v221, v39, v39
	v_cvt_pk_bf16_f32 v176, v176, v177
	v_cvt_pk_bf16_f32 v177, v178, v179
	global_store_dwordx2 v220, v[176:177], s[14:15] offset:256
	v_mul_f32_e32 v180, v32, v198
	v_mul_f32_e32 v181, v33, v199
	v_mul_f32_e32 v182, v34, v200
	v_mul_f32_e32 v183, v35, v201
	v_fmac_f32_e32 v221, v32, v32
	v_fmac_f32_e32 v221, v33, v33
	v_fmac_f32_e32 v221, v34, v34
	v_fmac_f32_e32 v221, v35, v35
	v_cvt_pk_bf16_f32 v180, v180, v181
	v_cvt_pk_bf16_f32 v181, v182, v183
	global_store_dwordx2 v220, v[180:181], s[14:15] offset:288
	v_mov_b32_e32 v44, v221
	global_load_dwordx4 v[142:145], v218, s[46:47] offset:0
	global_load_dwordx4 v[146:149], v218, s[46:47] offset:64
	global_load_dwordx4 v[176:179], v218, s[46:47] offset:512
	global_load_dwordx4 v[180:183], v218, s[46:47] offset:576
	v_add_u32_e32 v219, 0x20000, v219
	s_waitcnt vmcnt(12)
	v_pk_fma_f32 v[30:31], v[30:31], v[162:163], v[204:205]
	v_pk_fma_f32 v[28:29], v[28:29], v[160:161], v[202:203]
	global_store_dwordx4 v219, v[28:31], s[10:11] offset:0
	v_pk_fma_f32 v[26:27], v[26:27], v[166:167], v[208:209]
	v_pk_fma_f32 v[24:25], v[24:25], v[164:165], v[206:207]
	global_store_dwordx4 v219, v[24:27], s[10:11] offset:64
	v_pk_fma_f32 v[22:23], v[22:23], v[170:171], v[212:213]
	v_pk_fma_f32 v[20:21], v[20:21], v[168:169], v[210:211]
	global_store_dwordx4 v219, v[20:23], s[10:11] offset:512
	v_pk_fma_f32 v[18:19], v[18:19], v[174:175], v[216:217]
	v_pk_fma_f32 v[16:17], v[16:17], v[172:173], v[214:215]
	global_store_dwordx4 v219, v[16:19], s[10:11] offset:576
	v_lshrrev_b32_e32 v220, 1, v219
	v_mul_f32_e32 v202, v28, v186
	v_mul_f32_e32 v203, v29, v187
	v_mul_f32_e32 v204, v30, v188
	v_mul_f32_e32 v205, v31, v189
	v_mul_f32_e32 v221, v28, v28
	v_fmac_f32_e32 v221, v29, v29
	v_fmac_f32_e32 v221, v30, v30
	v_fmac_f32_e32 v221, v31, v31
	v_cvt_pk_bf16_f32 v202, v202, v203
	v_cvt_pk_bf16_f32 v203, v204, v205
	global_store_dwordx2 v220, v[202:203], s[14:15] offset:0
	v_mul_f32_e32 v206, v24, v190
	v_mul_f32_e32 v207, v25, v191
	v_mul_f32_e32 v208, v26, v192
	v_mul_f32_e32 v209, v27, v193
	v_fmac_f32_e32 v221, v24, v24
	v_fmac_f32_e32 v221, v25, v25
	v_fmac_f32_e32 v221, v26, v26
	v_fmac_f32_e32 v221, v27, v27
	v_cvt_pk_bf16_f32 v206, v206, v207
	v_cvt_pk_bf16_f32 v207, v208, v209
	global_store_dwordx2 v220, v[206:207], s[14:15] offset:32
	v_mul_f32_e32 v210, v20, v194
	v_mul_f32_e32 v211, v21, v195
	v_mul_f32_e32 v212, v22, v196
	v_mul_f32_e32 v213, v23, v197
	v_fmac_f32_e32 v221, v20, v20
	v_fmac_f32_e32 v221, v21, v21
	v_fmac_f32_e32 v221, v22, v22
	v_fmac_f32_e32 v221, v23, v23
	v_cvt_pk_bf16_f32 v210, v210, v211
	v_cvt_pk_bf16_f32 v211, v212, v213
	global_store_dwordx2 v220, v[210:211], s[14:15] offset:256
	v_mul_f32_e32 v214, v16, v198
	v_mul_f32_e32 v215, v17, v199
	v_mul_f32_e32 v216, v18, v200
	v_mul_f32_e32 v217, v19, v201
	v_fmac_f32_e32 v221, v16, v16
	v_fmac_f32_e32 v221, v17, v17
	v_fmac_f32_e32 v221, v18, v18
	v_fmac_f32_e32 v221, v19, v19
	v_cvt_pk_bf16_f32 v214, v214, v215
	v_cvt_pk_bf16_f32 v215, v216, v217
	global_store_dwordx2 v220, v[214:215], s[14:15] offset:288
	v_mov_b32_e32 v28, v221
	v_add_u32_e32 v219, 0x20000, v219
	s_waitcnt vmcnt(8)
; __device__ __forceinline__ unsigned cvt_pk_bf16(float lo, float hi) { unsigned r; asm volatile("v_cvt_pk_bf16_f32 %0, %1, %2" : "=v"(r) : "v"(lo), "v"(hi)); return r; }
;     __device__ __forceinline__ void operator()(const gacc_t (&acc)[2][2][4][2], const Unit& u, int wr, int wc, int fr, int fq) const {
;     ...
;                 for (int bj = 0; bj < 2; ++bj)
; #pragma unroll
;                     for (int n = 0; n < 2; ++n) { const int col = u.pn * 256 + bj * 128 + wc * 32 + n * 16 + 4 * fq;
;                         const f32x4 b = *(const f32x4*)(bp + col), g = *(const f32x4*)(gp + col); const gacc_t a = acc[ai][bj][m][n];
;                         f32x4 o; o.x = b.x + g.x * a[0]; o.y = b.y + g.y * a[1]; o.z = b.z + g.z * a[2]; o.w = b.w + g.w * a[3];
;                         *(f32x4*)(op + col) = o;
;                         if (hu) { const f32x4 gg = *(const f32x4*)(gn + col), sc = *(const f32x4*)(scl + mb * MODW + col);
;                             sq += (o.x * o.x + o.y * o.y) + (o.z * o.z + o.w * o.w);
;                             u32x2 w; w.x = pg8::cvt_pk_bf16(o.x * gg.x * (1.f + sc.x), o.y * gg.y * (1.f + sc.y)); w.y = pg8::cvt_pk_bf16(o.z * gg.z * (1.f + sc.z), o.w * gg.w * (1.f + sc.w));
;                             *(u32x2*)(hu + (size_t)row * D + col) = w; } }
;                 if (hu) { sq += __shfl_xor(sq, 16); sq += __shfl_xor(sq, 32); if (fq == 0) __hip_atomic_fetch_add(ss + row, sq, __ATOMIC_RELAXED, __HIP_MEMORY_SCOPE_AGENT); } }
	v_pk_fma_f32 v[14:15], v[14:15], v[162:163], v[144:145]
	v_pk_fma_f32 v[12:13], v[12:13], v[160:161], v[142:143]
	global_store_dwordx4 v219, v[12:15], s[10:11] offset:0
	v_pk_fma_f32 v[10:11], v[10:11], v[166:167], v[148:149]
	v_pk_fma_f32 v[8:9], v[8:9], v[164:165], v[146:147]
	global_store_dwordx4 v219, v[8:11], s[10:11] offset:64
	v_pk_fma_f32 v[6:7], v[6:7], v[170:171], v[178:179]
	v_pk_fma_f32 v[4:5], v[4:5], v[168:169], v[176:177]
	global_store_dwordx4 v219, v[4:7], s[10:11] offset:512
	v_pk_fma_f32 v[2:3], v[2:3], v[174:175], v[182:183]
	v_pk_fma_f32 v[0:1], v[0:1], v[172:173], v[180:181]
	global_store_dwordx4 v219, v[0:3], s[10:11] offset:576
	v_lshrrev_b32_e32 v220, 1, v219
	v_mul_f32_e32 v142, v12, v186
	v_mul_f32_e32 v143, v13, v187
	v_mul_f32_e32 v144, v14, v188
	v_mul_f32_e32 v145, v15, v189
	v_mul_f32_e32 v221, v12, v12
	v_fmac_f32_e32 v221, v13, v13
	v_fmac_f32_e32 v221, v14, v14
	v_fmac_f32_e32 v221, v15, v15
	v_cvt_pk_bf16_f32 v142, v142, v143
	v_cvt_pk_bf16_f32 v143, v144, v145
	global_store_dwordx2 v220, v[142:143], s[14:15] offset:0
	v_mul_f32_e32 v146, v8, v190
	v_mul_f32_e32 v147, v9, v191
	v_mul_f32_e32 v148, v10, v192
	v_mul_f32_e32 v149, v11, v193
	v_fmac_f32_e32 v221, v8, v8
	v_fmac_f32_e32 v221, v9, v9
	v_fmac_f32_e32 v221, v10, v10
	v_fmac_f32_e32 v221, v11, v11
	v_cvt_pk_bf16_f32 v146, v146, v147
	v_cvt_pk_bf16_f32 v147, v148, v149
	global_store_dwordx2 v220, v[146:147], s[14:15] offset:32
	v_mul_f32_e32 v176, v4, v194
	v_mul_f32_e32 v177, v5, v195
	v_mul_f32_e32 v178, v6, v196
	v_mul_f32_e32 v179, v7, v197
	v_fmac_f32_e32 v221, v4, v4
	v_fmac_f32_e32 v221, v5, v5
	v_fmac_f32_e32 v221, v6, v6
	v_fmac_f32_e32 v221, v7, v7
	v_cvt_pk_bf16_f32 v176, v176, v177
	v_cvt_pk_bf16_f32 v177, v178, v179
	global_store_dwordx2 v220, v[176:177], s[14:15] offset:256
	v_mul_f32_e32 v180, v0, v198
	v_mul_f32_e32 v181, v1, v199
	v_mul_f32_e32 v182, v2, v200
	v_mul_f32_e32 v183, v3, v201
	v_fmac_f32_e32 v221, v0, v0
	v_fmac_f32_e32 v221, v1, v1
	v_fmac_f32_e32 v221, v2, v2
	v_fmac_f32_e32 v221, v3, v3
	v_cvt_pk_bf16_f32 v180, v180, v181
	v_cvt_pk_bf16_f32 v181, v182, v183
	global_store_dwordx2 v220, v[180:181], s[14:15] offset:288
	v_mov_b32_e32 v12, v221
	v_xor_b32_e32 v220, 16, v158
	v_lshlrev_b32_e32 v220, 2, v220
	v_xor_b32_e32 v221, 32, v158
	v_lshlrev_b32_e32 v221, 2, v221
	ds_bpermute_b32 v202, v220, v124
	ds_bpermute_b32 v203, v220, v108
	ds_bpermute_b32 v204, v220, v92
	ds_bpermute_b32 v205, v220, v76
	ds_bpermute_b32 v206, v220, v60
	ds_bpermute_b32 v207, v220, v44
	ds_bpermute_b32 v208, v220, v28
	ds_bpermute_b32 v209, v220, v12
	s_waitcnt lgkmcnt(0)
	v_add_f32_e32 v124, v124, v202
	v_add_f32_e32 v108, v108, v203
	v_add_f32_e32 v92, v92, v204
	v_add_f32_e32 v76, v76, v205
	v_add_f32_e32 v60, v60, v206
	v_add_f32_e32 v44, v44, v207
	v_add_f32_e32 v28, v28, v208
	v_add_f32_e32 v12, v12, v209
	ds_bpermute_b32 v202, v221, v124
	ds_bpermute_b32 v203, v221, v108
	ds_bpermute_b32 v204, v221, v92
	ds_bpermute_b32 v205, v221, v76
	ds_bpermute_b32 v206, v221, v60
	ds_bpermute_b32 v207, v221, v44
	ds_bpermute_b32 v208, v221, v28
	ds_bpermute_b32 v209, v221, v12
	v_add_u32_e32 v220, s48, v152
	v_lshlrev_b32_e32 v220, 2, v220
	s_waitcnt lgkmcnt(0)
	v_add_f32_e32 v124, v124, v202
	v_add_f32_e32 v108, v108, v203
	v_add_f32_e32 v92, v92, v204
	v_add_f32_e32 v76, v76, v205
	v_add_f32_e32 v60, v60, v206
	v_add_f32_e32 v44, v44, v207
	v_add_f32_e32 v28, v28, v208
	v_add_f32_e32 v12, v12, v209
	s_and_saveexec_b64 s[44:45], s[2:3]
	global_atomic_add_f32 v220, v124, s[28:29] offset:0
	global_atomic_add_f32 v220, v108, s[28:29] offset:64
	global_atomic_add_f32 v220, v92, s[28:29] offset:128
	global_atomic_add_f32 v220, v76, s[28:29] offset:192
	global_atomic_add_f32 v220, v60, s[28:29] offset:512
	global_atomic_add_f32 v220, v44, s[28:29] offset:576
	global_atomic_add_f32 v220, v28, s[28:29] offset:640
	global_atomic_add_f32 v220, v12, s[28:29] offset:704
	s_mov_b64 exec, s[44:45]
	s_branch .Lp8_epi_done
.Lp8_qepi:
	s_cmp_lg_u32 s32, 1
	s_cbranch_scc1 .Lp8_qepi_n0
	v_mov_b32_e32 v218, v219
	global_load_dwordx4 v[60:63], v222, s[26:27] offset:0
	global_load_dwordx4 v[56:59], v222, s[26:27] offset:64
	global_load_dwordx4 v[186:189], v132, s[24:25] offset:0
	global_load_dwordx4 v[190:193], v132, s[24:25] offset:64
	global_load_dwordx4 v[160:163], v223, s[8:9] offset:0
	global_load_dwordx4 v[164:167], v223, s[8:9] offset:64
	global_load_dwordx4 v[202:205], v218, s[46:47] offset:0
	global_load_dwordx4 v[206:209], v218, s[46:47] offset:64
	v_add_u32_e32 v218, 0x20000, v218
	global_load_dwordx4 v[210:213], v218, s[46:47] offset:0
	global_load_dwordx4 v[214:217], v218, s[46:47] offset:64
	v_add_u32_e32 v218, 0x20000, v218
	global_load_dwordx4 v[142:145], v218, s[46:47] offset:0
	global_load_dwordx4 v[146:149], v218, s[46:47] offset:64
	v_add_u32_e32 v218, 0x20000, v218
	global_load_dwordx4 v[176:179], v218, s[46:47] offset:0
	global_load_dwordx4 v[180:183], v218, s[46:47] offset:64
	s_waitcnt vmcnt(10)
	v_add_f32_e32 v60, 1.0, v60
	v_add_f32_e32 v61, 1.0, v61
	v_add_f32_e32 v62, 1.0, v62
	v_add_f32_e32 v63, 1.0, v63
	v_add_f32_e32 v56, 1.0, v56
	v_add_f32_e32 v57, 1.0, v57
	v_add_f32_e32 v58, 1.0, v58
	v_add_f32_e32 v59, 1.0, v59
	v_mul_f32_e32 v186, v186, v60
	v_mul_f32_e32 v187, v187, v61
	v_mul_f32_e32 v188, v188, v62
	v_mul_f32_e32 v189, v189, v63
	v_mul_f32_e32 v190, v190, v56
	v_mul_f32_e32 v191, v191, v57
	v_mul_f32_e32 v192, v192, v58
	v_mul_f32_e32 v193, v193, v59
	s_waitcnt vmcnt(6)
; __device__ __forceinline__ unsigned cvt_pk_bf16(float lo, float hi) { unsigned r; asm volatile("v_cvt_pk_bf16_f32 %0, %1, %2" : "=v"(r) : "v"(lo), "v"(hi)); return r; }
;     __device__ __forceinline__ void operator()(const gacc_t (&acc)[2][2][4][2], const Unit& u, int wr, int wc, int fr, int fq) const {
;     ...
;             for (int m = 0; m < 4; ++m) { const int row = u.pm * 256 + ai * 128 + wr * 64 + m * 16 + fr;
;                 const float* bp = row < ML ? baseL + (size_t)row * D : baseC + (size_t)(row - ML) * D;
;                 const int mb = row < ML ? (row >> 11) : 8; const float* gp = mod + mb * MODW + chunk * D; float* op = out + (size_t)row * D;
;                 float sq = 0.f;
; #pragma unroll
;                 for (int bj = 0; bj < 2; ++bj)
; #pragma unroll
;                     for (int n = 0; n < 2; ++n) { const int col = u.pn * 256 + bj * 128 + wc * 32 + n * 16 + 4 * fq;
;                         const f32x4 b = *(const f32x4*)(bp + col), g = *(const f32x4*)(gp + col); const gacc_t a = acc[ai][bj][m][n];
;                         f32x4 o; o.x = b.x + g.x * a[0]; o.y = b.y + g.y * a[1]; o.z = b.z + g.z * a[2]; o.w = b.w + g.w * a[3];
;                         *(f32x4*)(op + col) = o;
;                         if (hu) { const f32x4 gg = *(const f32x4*)(gn + col), sc = *(const f32x4*)(scl + mb * MODW + col);
;                             sq += (o.x * o.x + o.y * o.y) + (o.z * o.z + o.w * o.w);
;                             u32x2 w; w.x = pg8::cvt_pk_bf16(o.x * gg.x * (1.f + sc.x), o.y * gg.y * (1.f + sc.y)); w.y = pg8::cvt_pk_bf16(o.z * gg.z * (1.f + sc.z), o.w * gg.w * (1.f + sc.w));
;                             *(u32x2*)(hu + (size_t)row * D + col) = w; } }
;                 if (hu) { sq += __shfl_xor(sq, 16); sq += __shfl_xor(sq, 32); if (fq == 0) __hip_atomic_fetch_add(ss + row, sq, __ATOMIC_RELAXED, __HIP_MEMORY_SCOPE_AGENT); } }
	v_pk_fma_f32 v[126:127], v[126:127], v[162:163], v[204:205]
	v_pk_fma_f32 v[124:125], v[124:125], v[160:161], v[202:203]
	global_store_dwordx4 v219, v[124:127], s[10:11] offset:0
	v_pk_fma_f32 v[122:123], v[122:123], v[166:167], v[208:209]
	v_pk_fma_f32 v[120:121], v[120:121], v[164:165], v[206:207]
	global_store_dwordx4 v219, v[120:123], s[10:11] offset:64
	v_lshrrev_b32_e32 v220, 1, v219
	v_mul_f32_e32 v202, v124, v186
	v_mul_f32_e32 v203, v125, v187
	v_mul_f32_e32 v204, v126, v188
	v_mul_f32_e32 v205, v127, v189
	v_mul_f32_e32 v221, v124, v124
	v_fmac_f32_e32 v221, v125, v125
	v_fmac_f32_e32 v221, v126, v126
	v_fmac_f32_e32 v221, v127, v127
	v_cvt_pk_bf16_f32 v202, v202, v203
	v_cvt_pk_bf16_f32 v203, v204, v205
	global_store_dwordx2 v220, v[202:203], s[14:15] offset:0
	v_mul_f32_e32 v206, v120, v190
	v_mul_f32_e32 v207, v121, v191
	v_mul_f32_e32 v208, v122, v192
	v_mul_f32_e32 v209, v123, v193
	v_fmac_f32_e32 v221, v120, v120
	v_fmac_f32_e32 v221, v121, v121
	v_fmac_f32_e32 v221, v122, v122
	v_fmac_f32_e32 v221, v123, v123
	v_cvt_pk_bf16_f32 v206, v206, v207
	v_cvt_pk_bf16_f32 v207, v208, v209
	global_store_dwordx2 v220, v[206:207], s[14:15] offset:32
	v_mov_b32_e32 v124, v221
	v_add_u32_e32 v219, 0x20000, v219
	s_waitcnt vmcnt(8)
	v_pk_fma_f32 v[110:111], v[110:111], v[162:163], v[212:213]
	v_pk_fma_f32 v[108:109], v[108:109], v[160:161], v[210:211]
	global_store_dwordx4 v219, v[108:111], s[10:11] offset:0
	v_pk_fma_f32 v[106:107], v[106:107], v[166:167], v[216:217]
	v_pk_fma_f32 v[104:105], v[104:105], v[164:165], v[214:215]
	global_store_dwordx4 v219, v[104:107], s[10:11] offset:64
	v_lshrrev_b32_e32 v220, 1, v219
	v_mul_f32_e32 v210, v108, v186
	v_mul_f32_e32 v211, v109, v187
	v_mul_f32_e32 v212, v110, v188
	v_mul_f32_e32 v213, v111, v189
	v_mul_f32_e32 v221, v108, v108
	v_fmac_f32_e32 v221, v109, v109
	v_fmac_f32_e32 v221, v110, v110
	v_fmac_f32_e32 v221, v111, v111
	v_cvt_pk_bf16_f32 v210, v210, v211
	v_cvt_pk_bf16_f32 v211, v212, v213
	global_store_dwordx2 v220, v[210:211], s[14:15] offset:0
	v_mul_f32_e32 v214, v104, v190
	v_mul_f32_e32 v215, v105, v191
	v_mul_f32_e32 v216, v106, v192
	v_mul_f32_e32 v217, v107, v193
	v_fmac_f32_e32 v221, v104, v104
	v_fmac_f32_e32 v221, v105, v105
	v_fmac_f32_e32 v221, v106, v106
	v_fmac_f32_e32 v221, v107, v107
	v_cvt_pk_bf16_f32 v214, v214, v215
	v_cvt_pk_bf16_f32 v215, v216, v217
	global_store_dwordx2 v220, v[214:215], s[14:15] offset:32
	v_mov_b32_e32 v108, v221
	v_add_u32_e32 v219, 0x20000, v219
	s_waitcnt vmcnt(10)
	v_pk_fma_f32 v[94:95], v[94:95], v[162:163], v[144:145]
	v_pk_fma_f32 v[92:93], v[92:93], v[160:161], v[142:143]
	global_store_dwordx4 v219, v[92:95], s[10:11] offset:0
	v_pk_fma_f32 v[90:91], v[90:91], v[166:167], v[148:149]
	v_pk_fma_f32 v[88:89], v[88:89], v[164:165], v[146:147]
	global_store_dwordx4 v219, v[88:91], s[10:11] offset:64
	v_lshrrev_b32_e32 v220, 1, v219
	v_mul_f32_e32 v142, v92, v186
	v_mul_f32_e32 v143, v93, v187
	v_mul_f32_e32 v144, v94, v188
	v_mul_f32_e32 v145, v95, v189
	v_mul_f32_e32 v221, v92, v92
	v_fmac_f32_e32 v221, v93, v93
	v_fmac_f32_e32 v221, v94, v94
	v_fmac_f32_e32 v221, v95, v95
	v_cvt_pk_bf16_f32 v142, v142, v143
	v_cvt_pk_bf16_f32 v143, v144, v145
	global_store_dwordx2 v220, v[142:143], s[14:15] offset:0
	v_mul_f32_e32 v146, v88, v190
	v_mul_f32_e32 v147, v89, v191
	v_mul_f32_e32 v148, v90, v192
	v_mul_f32_e32 v149, v91, v193
	v_fmac_f32_e32 v221, v88, v88
	v_fmac_f32_e32 v221, v89, v89
	v_fmac_f32_e32 v221, v90, v90
	v_fmac_f32_e32 v221, v91, v91
	v_cvt_pk_bf16_f32 v146, v146, v147
	v_cvt_pk_bf16_f32 v147, v148, v149
	global_store_dwordx2 v220, v[146:147], s[14:15] offset:32
	v_mov_b32_e32 v92, v221
	v_add_u32_e32 v219, 0x20000, v219
	s_waitcnt vmcnt(12)
	v_pk_fma_f32 v[78:79], v[78:79], v[162:163], v[178:179]
	v_pk_fma_f32 v[76:77], v[76:77], v[160:161], v[176:177]
	global_store_dwordx4 v219, v[76:79], s[10:11] offset:0
	v_pk_fma_f32 v[74:75], v[74:75], v[166:167], v[182:183]
	v_pk_fma_f32 v[72:73], v[72:73], v[164:165], v[180:181]
	global_store_dwordx4 v219, v[72:75], s[10:11] offset:64
	v_lshrrev_b32_e32 v220, 1, v219
	v_mul_f32_e32 v176, v76, v186
	v_mul_f32_e32 v177, v77, v187
	v_mul_f32_e32 v178, v78, v188
	v_mul_f32_e32 v179, v79, v189
	v_mul_f32_e32 v221, v76, v76
	v_fmac_f32_e32 v221, v77, v77
	v_fmac_f32_e32 v221, v78, v78
	v_fmac_f32_e32 v221, v79, v79
	v_cvt_pk_bf16_f32 v176, v176, v177
	v_cvt_pk_bf16_f32 v177, v178, v179
	global_store_dwordx2 v220, v[176:177], s[14:15] offset:0
	v_mul_f32_e32 v180, v72, v190
	v_mul_f32_e32 v181, v73, v191
	v_mul_f32_e32 v182, v74, v192
	v_mul_f32_e32 v183, v75, v193
	v_fmac_f32_e32 v221, v72, v72
	v_fmac_f32_e32 v221, v73, v73
	v_fmac_f32_e32 v221, v74, v74
	v_fmac_f32_e32 v221, v75, v75
	v_cvt_pk_bf16_f32 v180, v180, v181
	v_cvt_pk_bf16_f32 v181, v182, v183
	global_store_dwordx2 v220, v[180:181], s[14:15] offset:32
	v_mov_b32_e32 v76, v221
	v_xor_b32_e32 v220, 16, v158
	v_lshlrev_b32_e32 v220, 2, v220
	v_xor_b32_e32 v221, 32, v158
	v_lshlrev_b32_e32 v221, 2, v221
	ds_bpermute_b32 v202, v220, v124
	ds_bpermute_b32 v203, v220, v108
	ds_bpermute_b32 v204, v220, v92
	ds_bpermute_b32 v205, v220, v76
	s_waitcnt lgkmcnt(0)
	v_add_f32_e32 v124, v124, v202
	v_add_f32_e32 v108, v108, v203
	v_add_f32_e32 v92, v92, v204
	v_add_f32_e32 v76, v76, v205
	ds_bpermute_b32 v202, v221, v124
	ds_bpermute_b32 v203, v221, v108
	ds_bpermute_b32 v204, v221, v92
	ds_bpermute_b32 v205, v221, v76
	v_add_u32_e32 v220, s48, v152
	v_lshlrev_b32_e32 v220, 2, v220
	s_waitcnt lgkmcnt(0)
	v_add_f32_e32 v124, v124, v202
	v_add_f32_e32 v108, v108, v203
	v_add_f32_e32 v92, v92, v204
	v_add_f32_e32 v76, v76, v205
	s_and_saveexec_b64 s[44:45], s[2:3]
	global_atomic_add_f32 v220, v124, s[28:29] offset:0
	global_atomic_add_f32 v220, v108, s[28:29] offset:64
	global_atomic_add_f32 v220, v92, s[28:29] offset:128
	global_atomic_add_f32 v220, v76, s[28:29] offset:192
	s_mov_b64 exec, s[44:45]
	s_branch .Lp8_epi_done
; __device__ __forceinline__ unsigned cvt_pk_bf16(float lo, float hi) { unsigned r; asm volatile("v_cvt_pk_bf16_f32 %0, %1, %2" : "=v"(r) : "v"(lo), "v"(hi)); return r; }
;     __device__ __forceinline__ void operator()(const gacc_t (&acc)[2][2][4][2], const Unit& u, int wr, int wc, int fr, int fq) const {
;     ...
;             for (int m = 0; m < 4; ++m) { const int row = u.pm * 256 + ai * 128 + wr * 64 + m * 16 + fr;
;                 const float* bp = row < ML ? baseL + (size_t)row * D : baseC + (size_t)(row - ML) * D;
;                 const int mb = row < ML ? (row >> 11) : 8; const float* gp = mod + mb * MODW + chunk * D; float* op = out + (size_t)row * D;
;                 float sq = 0.f;
; #pragma unroll
;                 for (int bj = 0; bj < 2; ++bj)
; #pragma unroll
;                     for (int n = 0; n < 2; ++n) { const int col = u.pn * 256 + bj * 128 + wc * 32 + n * 16 + 4 * fq;
;                         const f32x4 b = *(const f32x4*)(bp + col), g = *(const f32x4*)(gp + col); const gacc_t a = acc[ai][bj][m][n];
;                         f32x4 o; o.x = b.x + g.x * a[0]; o.y = b.y + g.y * a[1]; o.z = b.z + g.z * a[2]; o.w = b.w + g.w * a[3];
;                         *(f32x4*)(op + col) = o;
;                         if (hu) { const f32x4 gg = *(const f32x4*)(gn + col), sc = *(const f32x4*)(scl + mb * MODW + col);
;                             sq += (o.x * o.x + o.y * o.y) + (o.z * o.z + o.w * o.w);
;                             u32x2 w; w.x = pg8::cvt_pk_bf16(o.x * gg.x * (1.f + sc.x), o.y * gg.y * (1.f + sc.y)); w.y = pg8::cvt_pk_bf16(o.z * gg.z * (1.f + sc.z), o.w * gg.w * (1.f + sc.w));
;                             *(u32x2*)(hu + (size_t)row * D + col) = w; } }
;                 if (hu) { sq += __shfl_xor(sq, 16); sq += __shfl_xor(sq, 32); if (fq == 0) __hip_atomic_fetch_add(ss + row, sq, __ATOMIC_RELAXED, __HIP_MEMORY_SCOPE_AGENT); } }
.Lp8_qepi_n0:
	s_cmp_lg_u32 s32, 2
	s_cbranch_scc1 .Lp8_qepi_n1
	v_mov_b32_e32 v218, v219
	global_load_dwordx4 v[60:63], v222, s[26:27] offset:512
	global_load_dwordx4 v[56:59], v222, s[26:27] offset:576
	global_load_dwordx4 v[194:197], v132, s[24:25] offset:512
	global_load_dwordx4 v[198:201], v132, s[24:25] offset:576
	global_load_dwordx4 v[168:171], v223, s[8:9] offset:512
	global_load_dwordx4 v[172:175], v223, s[8:9] offset:576
	global_load_dwordx4 v[202:205], v218, s[46:47] offset:512
	global_load_dwordx4 v[206:209], v218, s[46:47] offset:576
	v_add_u32_e32 v218, 0x20000, v218
	global_load_dwordx4 v[210:213], v218, s[46:47] offset:512
	global_load_dwordx4 v[214:217], v218, s[46:47] offset:576
	v_add_u32_e32 v218, 0x20000, v218
	global_load_dwordx4 v[142:145], v218, s[46:47] offset:512
	global_load_dwordx4 v[146:149], v218, s[46:47] offset:576
	v_add_u32_e32 v218, 0x20000, v218
	global_load_dwordx4 v[176:179], v218, s[46:47] offset:512
	global_load_dwordx4 v[180:183], v218, s[46:47] offset:576
	s_waitcnt vmcnt(10)
	v_add_f32_e32 v60, 1.0, v60
	v_add_f32_e32 v61, 1.0, v61
	v_add_f32_e32 v62, 1.0, v62
	v_add_f32_e32 v63, 1.0, v63
	v_add_f32_e32 v56, 1.0, v56
	v_add_f32_e32 v57, 1.0, v57
	v_add_f32_e32 v58, 1.0, v58
	v_add_f32_e32 v59, 1.0, v59
	v_mul_f32_e32 v194, v194, v60
	v_mul_f32_e32 v195, v195, v61
	v_mul_f32_e32 v196, v196, v62
	v_mul_f32_e32 v197, v197, v63
	v_mul_f32_e32 v198, v198, v56
	v_mul_f32_e32 v199, v199, v57
	v_mul_f32_e32 v200, v200, v58
	v_mul_f32_e32 v201, v201, v59
	s_waitcnt vmcnt(6)
	v_pk_fma_f32 v[118:119], v[118:119], v[170:171], v[204:205]
	v_pk_fma_f32 v[116:117], v[116:117], v[168:169], v[202:203]
	global_store_dwordx4 v219, v[116:119], s[10:11] offset:512
	v_pk_fma_f32 v[114:115], v[114:115], v[174:175], v[208:209]
	v_pk_fma_f32 v[112:113], v[112:113], v[172:173], v[206:207]
	global_store_dwordx4 v219, v[112:115], s[10:11] offset:576
	v_lshrrev_b32_e32 v220, 1, v219
	v_mul_f32_e32 v202, v116, v194
	v_mul_f32_e32 v203, v117, v195
	v_mul_f32_e32 v204, v118, v196
	v_mul_f32_e32 v205, v119, v197
	v_mul_f32_e32 v221, v116, v116
	v_fmac_f32_e32 v221, v117, v117
	v_fmac_f32_e32 v221, v118, v118
	v_fmac_f32_e32 v221, v119, v119
	v_cvt_pk_bf16_f32 v202, v202, v203
	v_cvt_pk_bf16_f32 v203, v204, v205
	global_store_dwordx2 v220, v[202:203], s[14:15] offset:256
	v_mul_f32_e32 v206, v112, v198
	v_mul_f32_e32 v207, v113, v199
	v_mul_f32_e32 v208, v114, v200
	v_mul_f32_e32 v209, v115, v201
	v_fmac_f32_e32 v221, v112, v112
	v_fmac_f32_e32 v221, v113, v113
	v_fmac_f32_e32 v221, v114, v114
	v_fmac_f32_e32 v221, v115, v115
	v_cvt_pk_bf16_f32 v206, v206, v207
	v_cvt_pk_bf16_f32 v207, v208, v209
	global_store_dwordx2 v220, v[206:207], s[14:15] offset:288
	v_mov_b32_e32 v116, v221
	v_add_u32_e32 v219, 0x20000, v219
	s_waitcnt vmcnt(8)
	v_pk_fma_f32 v[102:103], v[102:103], v[170:171], v[212:213]
	v_pk_fma_f32 v[100:101], v[100:101], v[168:169], v[210:211]
	global_store_dwordx4 v219, v[100:103], s[10:11] offset:512
	v_pk_fma_f32 v[98:99], v[98:99], v[174:175], v[216:217]
	v_pk_fma_f32 v[96:97], v[96:97], v[172:173], v[214:215]
	global_store_dwordx4 v219, v[96:99], s[10:11] offset:576
	v_lshrrev_b32_e32 v220, 1, v219
	v_mul_f32_e32 v210, v100, v194
	v_mul_f32_e32 v211, v101, v195
	v_mul_f32_e32 v212, v102, v196
	v_mul_f32_e32 v213, v103, v197
	v_mul_f32_e32 v221, v100, v100
	v_fmac_f32_e32 v221, v101, v101
	v_fmac_f32_e32 v221, v102, v102
	v_fmac_f32_e32 v221, v103, v103
	v_cvt_pk_bf16_f32 v210, v210, v211
	v_cvt_pk_bf16_f32 v211, v212, v213
	global_store_dwordx2 v220, v[210:211], s[14:15] offset:256
	v_mul_f32_e32 v214, v96, v198
	v_mul_f32_e32 v215, v97, v199
	v_mul_f32_e32 v216, v98, v200
	v_mul_f32_e32 v217, v99, v201
	v_fmac_f32_e32 v221, v96, v96
	v_fmac_f32_e32 v221, v97, v97
	v_fmac_f32_e32 v221, v98, v98
	v_fmac_f32_e32 v221, v99, v99
	v_cvt_pk_bf16_f32 v214, v214, v215
	v_cvt_pk_bf16_f32 v215, v216, v217
	global_store_dwordx2 v220, v[214:215], s[14:15] offset:288
	v_mov_b32_e32 v100, v221
	v_add_u32_e32 v219, 0x20000, v219
	s_waitcnt vmcnt(10)
	v_pk_fma_f32 v[86:87], v[86:87], v[170:171], v[144:145]
	v_pk_fma_f32 v[84:85], v[84:85], v[168:169], v[142:143]
	global_store_dwordx4 v219, v[84:87], s[10:11] offset:512
	v_pk_fma_f32 v[82:83], v[82:83], v[174:175], v[148:149]
	v_pk_fma_f32 v[80:81], v[80:81], v[172:173], v[146:147]
	global_store_dwordx4 v219, v[80:83], s[10:11] offset:576
	v_lshrrev_b32_e32 v220, 1, v219
	v_mul_f32_e32 v142, v84, v194
	v_mul_f32_e32 v143, v85, v195
	v_mul_f32_e32 v144, v86, v196
	v_mul_f32_e32 v145, v87, v197
	v_mul_f32_e32 v221, v84, v84
	v_fmac_f32_e32 v221, v85, v85
	v_fmac_f32_e32 v221, v86, v86
	v_fmac_f32_e32 v221, v87, v87
	v_cvt_pk_bf16_f32 v142, v142, v143
	v_cvt_pk_bf16_f32 v143, v144, v145
	global_store_dwordx2 v220, v[142:143], s[14:15] offset:256
	v_mul_f32_e32 v146, v80, v198
	v_mul_f32_e32 v147, v81, v199
	v_mul_f32_e32 v148, v82, v200
	v_mul_f32_e32 v149, v83, v201
	v_fmac_f32_e32 v221, v80, v80
	v_fmac_f32_e32 v221, v81, v81
	v_fmac_f32_e32 v221, v82, v82
	v_fmac_f32_e32 v221, v83, v83
	v_cvt_pk_bf16_f32 v146, v146, v147
	v_cvt_pk_bf16_f32 v147, v148, v149
	global_store_dwordx2 v220, v[146:147], s[14:15] offset:288
	v_mov_b32_e32 v84, v221
	v_add_u32_e32 v219, 0x20000, v219
	s_waitcnt vmcnt(12)
; __device__ __forceinline__ unsigned cvt_pk_bf16(float lo, float hi) { unsigned r; asm volatile("v_cvt_pk_bf16_f32 %0, %1, %2" : "=v"(r) : "v"(lo), "v"(hi)); return r; }
;     __device__ __forceinline__ void operator()(const gacc_t (&acc)[2][2][4][2], const Unit& u, int wr, int wc, int fr, int fq) const {
;     ...
;             for (int m = 0; m < 4; ++m) { const int row = u.pm * 256 + ai * 128 + wr * 64 + m * 16 + fr;
;                 const float* bp = row < ML ? baseL + (size_t)row * D : baseC + (size_t)(row - ML) * D;
;                 const int mb = row < ML ? (row >> 11) : 8; const float* gp = mod + mb * MODW + chunk * D; float* op = out + (size_t)row * D;
;                 float sq = 0.f;
; #pragma unroll
;                 for (int bj = 0; bj < 2; ++bj)
; #pragma unroll
;                     for (int n = 0; n < 2; ++n) { const int col = u.pn * 256 + bj * 128 + wc * 32 + n * 16 + 4 * fq;
;                         const f32x4 b = *(const f32x4*)(bp + col), g = *(const f32x4*)(gp + col); const gacc_t a = acc[ai][bj][m][n];
;                         f32x4 o; o.x = b.x + g.x * a[0]; o.y = b.y + g.y * a[1]; o.z = b.z + g.z * a[2]; o.w = b.w + g.w * a[3];
;                         *(f32x4*)(op + col) = o;
;                         if (hu) { const f32x4 gg = *(const f32x4*)(gn + col), sc = *(const f32x4*)(scl + mb * MODW + col);
;                             sq += (o.x * o.x + o.y * o.y) + (o.z * o.z + o.w * o.w);
;                             u32x2 w; w.x = pg8::cvt_pk_bf16(o.x * gg.x * (1.f + sc.x), o.y * gg.y * (1.f + sc.y)); w.y = pg8::cvt_pk_bf16(o.z * gg.z * (1.f + sc.z), o.w * gg.w * (1.f + sc.w));
;                             *(u32x2*)(hu + (size_t)row * D + col) = w; } }
;                 if (hu) { sq += __shfl_xor(sq, 16); sq += __shfl_xor(sq, 32); if (fq == 0) __hip_atomic_fetch_add(ss + row, sq, __ATOMIC_RELAXED, __HIP_MEMORY_SCOPE_AGENT); } }
	v_pk_fma_f32 v[70:71], v[70:71], v[170:171], v[178:179]
	v_pk_fma_f32 v[68:69], v[68:69], v[168:169], v[176:177]
	global_store_dwordx4 v219, v[68:71], s[10:11] offset:512
	v_pk_fma_f32 v[66:67], v[66:67], v[174:175], v[182:183]
	v_pk_fma_f32 v[64:65], v[64:65], v[172:173], v[180:181]
	global_store_dwordx4 v219, v[64:67], s[10:11] offset:576
	v_lshrrev_b32_e32 v220, 1, v219
	v_mul_f32_e32 v176, v68, v194
	v_mul_f32_e32 v177, v69, v195
	v_mul_f32_e32 v178, v70, v196
	v_mul_f32_e32 v179, v71, v197
	v_mul_f32_e32 v221, v68, v68
	v_fmac_f32_e32 v221, v69, v69
	v_fmac_f32_e32 v221, v70, v70
	v_fmac_f32_e32 v221, v71, v71
	v_cvt_pk_bf16_f32 v176, v176, v177
	v_cvt_pk_bf16_f32 v177, v178, v179
	global_store_dwordx2 v220, v[176:177], s[14:15] offset:256
	v_mul_f32_e32 v180, v64, v198
	v_mul_f32_e32 v181, v65, v199
	v_mul_f32_e32 v182, v66, v200
	v_mul_f32_e32 v183, v67, v201
	v_fmac_f32_e32 v221, v64, v64
	v_fmac_f32_e32 v221, v65, v65
	v_fmac_f32_e32 v221, v66, v66
	v_fmac_f32_e32 v221, v67, v67
	v_cvt_pk_bf16_f32 v180, v180, v181
	v_cvt_pk_bf16_f32 v181, v182, v183
	global_store_dwordx2 v220, v[180:181], s[14:15] offset:288
	v_mov_b32_e32 v68, v221
	v_xor_b32_e32 v220, 16, v158
	v_lshlrev_b32_e32 v220, 2, v220
	v_xor_b32_e32 v221, 32, v158
	v_lshlrev_b32_e32 v221, 2, v221
	ds_bpermute_b32 v202, v220, v116
	ds_bpermute_b32 v203, v220, v100
	ds_bpermute_b32 v204, v220, v84
	ds_bpermute_b32 v205, v220, v68
	s_waitcnt lgkmcnt(0)
	v_add_f32_e32 v116, v116, v202
	v_add_f32_e32 v100, v100, v203
	v_add_f32_e32 v84, v84, v204
	v_add_f32_e32 v68, v68, v205
	ds_bpermute_b32 v202, v221, v116
	ds_bpermute_b32 v203, v221, v100
	ds_bpermute_b32 v204, v221, v84
	ds_bpermute_b32 v205, v221, v68
	v_add_u32_e32 v220, s48, v152
	v_lshlrev_b32_e32 v220, 2, v220
	s_waitcnt lgkmcnt(0)
	v_add_f32_e32 v116, v116, v202
	v_add_f32_e32 v100, v100, v203
	v_add_f32_e32 v84, v84, v204
	v_add_f32_e32 v68, v68, v205
	s_and_saveexec_b64 s[44:45], s[2:3]
	global_atomic_add_f32 v220, v116, s[28:29] offset:0
	global_atomic_add_f32 v220, v100, s[28:29] offset:64
	global_atomic_add_f32 v220, v84, s[28:29] offset:128
	global_atomic_add_f32 v220, v68, s[28:29] offset:192
	s_mov_b64 exec, s[44:45]
	s_branch .Lp8_epi_done
.Lp8_qepi_n1:
	s_cmp_lg_u32 s32, 4
	s_cbranch_scc1 .Lp8_qepi_n2
	v_add_u32_e32 v219, 0x100000, v219
	v_mov_b32_e32 v218, v219
	global_load_dwordx4 v[124:127], v222, s[26:27] offset:0
	global_load_dwordx4 v[120:123], v222, s[26:27] offset:64
	global_load_dwordx4 v[186:189], v132, s[24:25] offset:0
	global_load_dwordx4 v[190:193], v132, s[24:25] offset:64
	global_load_dwordx4 v[160:163], v223, s[8:9] offset:0
	global_load_dwordx4 v[164:167], v223, s[8:9] offset:64
	global_load_dwordx4 v[202:205], v218, s[46:47] offset:0
	global_load_dwordx4 v[206:209], v218, s[46:47] offset:64
	v_add_u32_e32 v218, 0x20000, v218
	global_load_dwordx4 v[210:213], v218, s[46:47] offset:0
	global_load_dwordx4 v[214:217], v218, s[46:47] offset:64
	v_add_u32_e32 v218, 0x20000, v218
	global_load_dwordx4 v[142:145], v218, s[46:47] offset:0
	global_load_dwordx4 v[146:149], v218, s[46:47] offset:64
	v_add_u32_e32 v218, 0x20000, v218
	global_load_dwordx4 v[176:179], v218, s[46:47] offset:0
	global_load_dwordx4 v[180:183], v218, s[46:47] offset:64
	s_waitcnt vmcnt(10)
	v_add_f32_e32 v124, 1.0, v124
	v_add_f32_e32 v125, 1.0, v125
	v_add_f32_e32 v126, 1.0, v126
	v_add_f32_e32 v127, 1.0, v127
	v_add_f32_e32 v120, 1.0, v120
	v_add_f32_e32 v121, 1.0, v121
	v_add_f32_e32 v122, 1.0, v122
	v_add_f32_e32 v123, 1.0, v123
	v_mul_f32_e32 v186, v186, v124
	v_mul_f32_e32 v187, v187, v125
	v_mul_f32_e32 v188, v188, v126
	v_mul_f32_e32 v189, v189, v127
	v_mul_f32_e32 v190, v190, v120
	v_mul_f32_e32 v191, v191, v121
	v_mul_f32_e32 v192, v192, v122
	v_mul_f32_e32 v193, v193, v123
	s_waitcnt vmcnt(6)
	v_pk_fma_f32 v[62:63], v[62:63], v[162:163], v[204:205]
	v_pk_fma_f32 v[60:61], v[60:61], v[160:161], v[202:203]
	global_store_dwordx4 v219, v[60:63], s[10:11] offset:0
	v_pk_fma_f32 v[58:59], v[58:59], v[166:167], v[208:209]
	v_pk_fma_f32 v[56:57], v[56:57], v[164:165], v[206:207]
	global_store_dwordx4 v219, v[56:59], s[10:11] offset:64
	v_lshrrev_b32_e32 v220, 1, v219
	v_mul_f32_e32 v202, v60, v186
	v_mul_f32_e32 v203, v61, v187
	v_mul_f32_e32 v204, v62, v188
	v_mul_f32_e32 v205, v63, v189
	v_mul_f32_e32 v221, v60, v60
	v_fmac_f32_e32 v221, v61, v61
	v_fmac_f32_e32 v221, v62, v62
	v_fmac_f32_e32 v221, v63, v63
	v_cvt_pk_bf16_f32 v202, v202, v203
	v_cvt_pk_bf16_f32 v203, v204, v205
	global_store_dwordx2 v220, v[202:203], s[14:15] offset:0
	v_mul_f32_e32 v206, v56, v190
	v_mul_f32_e32 v207, v57, v191
	v_mul_f32_e32 v208, v58, v192
	v_mul_f32_e32 v209, v59, v193
	v_fmac_f32_e32 v221, v56, v56
	v_fmac_f32_e32 v221, v57, v57
	v_fmac_f32_e32 v221, v58, v58
	v_fmac_f32_e32 v221, v59, v59
	v_cvt_pk_bf16_f32 v206, v206, v207
	v_cvt_pk_bf16_f32 v207, v208, v209
	global_store_dwordx2 v220, v[206:207], s[14:15] offset:32
	v_mov_b32_e32 v60, v221
	v_add_u32_e32 v219, 0x20000, v219
	s_waitcnt vmcnt(8)
	v_pk_fma_f32 v[46:47], v[46:47], v[162:163], v[212:213]
	v_pk_fma_f32 v[44:45], v[44:45], v[160:161], v[210:211]
	global_store_dwordx4 v219, v[44:47], s[10:11] offset:0
	v_pk_fma_f32 v[42:43], v[42:43], v[166:167], v[216:217]
	v_pk_fma_f32 v[40:41], v[40:41], v[164:165], v[214:215]
	global_store_dwordx4 v219, v[40:43], s[10:11] offset:64
	v_lshrrev_b32_e32 v220, 1, v219
	v_mul_f32_e32 v210, v44, v186
	v_mul_f32_e32 v211, v45, v187
	v_mul_f32_e32 v212, v46, v188
	v_mul_f32_e32 v213, v47, v189
	v_mul_f32_e32 v221, v44, v44
	v_fmac_f32_e32 v221, v45, v45
	v_fmac_f32_e32 v221, v46, v46
	v_fmac_f32_e32 v221, v47, v47
	v_cvt_pk_bf16_f32 v210, v210, v211
	v_cvt_pk_bf16_f32 v211, v212, v213
	global_store_dwordx2 v220, v[210:211], s[14:15] offset:0
	v_mul_f32_e32 v214, v40, v190
	v_mul_f32_e32 v215, v41, v191
	v_mul_f32_e32 v216, v42, v192
	v_mul_f32_e32 v217, v43, v193
	v_fmac_f32_e32 v221, v40, v40
	v_fmac_f32_e32 v221, v41, v41
	v_fmac_f32_e32 v221, v42, v42
	v_fmac_f32_e32 v221, v43, v43
	v_cvt_pk_bf16_f32 v214, v214, v215
	v_cvt_pk_bf16_f32 v215, v216, v217
	global_store_dwordx2 v220, v[214:215], s[14:15] offset:32
	v_mov_b32_e32 v44, v221
	v_add_u32_e32 v219, 0x20000, v219
	s_waitcnt vmcnt(10)
; __device__ __forceinline__ unsigned cvt_pk_bf16(float lo, float hi) { unsigned r; asm volatile("v_cvt_pk_bf16_f32 %0, %1, %2" : "=v"(r) : "v"(lo), "v"(hi)); return r; }
;     __device__ __forceinline__ void operator()(const gacc_t (&acc)[2][2][4][2], const Unit& u, int wr, int wc, int fr, int fq) const {
;     ...
;             for (int m = 0; m < 4; ++m) { const int row = u.pm * 256 + ai * 128 + wr * 64 + m * 16 + fr;
;                 const float* bp = row < ML ? baseL + (size_t)row * D : baseC + (size_t)(row - ML) * D;
;                 const int mb = row < ML ? (row >> 11) : 8; const float* gp = mod + mb * MODW + chunk * D; float* op = out + (size_t)row * D;
;                 float sq = 0.f;
; #pragma unroll
;                 for (int bj = 0; bj < 2; ++bj)
; #pragma unroll
;                     for (int n = 0; n < 2; ++n) { const int col = u.pn * 256 + bj * 128 + wc * 32 + n * 16 + 4 * fq;
;                         const f32x4 b = *(const f32x4*)(bp + col), g = *(const f32x4*)(gp + col); const gacc_t a = acc[ai][bj][m][n];
;                         f32x4 o; o.x = b.x + g.x * a[0]; o.y = b.y + g.y * a[1]; o.z = b.z + g.z * a[2]; o.w = b.w + g.w * a[3];
;                         *(f32x4*)(op + col) = o;
;                         if (hu) { const f32x4 gg = *(const f32x4*)(gn + col), sc = *(const f32x4*)(scl + mb * MODW + col);
;                             sq += (o.x * o.x + o.y * o.y) + (o.z * o.z + o.w * o.w);
;                             u32x2 w; w.x = pg8::cvt_pk_bf16(o.x * gg.x * (1.f + sc.x), o.y * gg.y * (1.f + sc.y)); w.y = pg8::cvt_pk_bf16(o.z * gg.z * (1.f + sc.z), o.w * gg.w * (1.f + sc.w));
;                             *(u32x2*)(hu + (size_t)row * D + col) = w; } }
;                 if (hu) { sq += __shfl_xor(sq, 16); sq += __shfl_xor(sq, 32); if (fq == 0) __hip_atomic_fetch_add(ss + row, sq, __ATOMIC_RELAXED, __HIP_MEMORY_SCOPE_AGENT); } }
	v_pk_fma_f32 v[30:31], v[30:31], v[162:163], v[144:145]
	v_pk_fma_f32 v[28:29], v[28:29], v[160:161], v[142:143]
	global_store_dwordx4 v219, v[28:31], s[10:11] offset:0
	v_pk_fma_f32 v[26:27], v[26:27], v[166:167], v[148:149]
	v_pk_fma_f32 v[24:25], v[24:25], v[164:165], v[146:147]
	global_store_dwordx4 v219, v[24:27], s[10:11] offset:64
	v_lshrrev_b32_e32 v220, 1, v219
	v_mul_f32_e32 v142, v28, v186
	v_mul_f32_e32 v143, v29, v187
	v_mul_f32_e32 v144, v30, v188
	v_mul_f32_e32 v145, v31, v189
	v_mul_f32_e32 v221, v28, v28
	v_fmac_f32_e32 v221, v29, v29
	v_fmac_f32_e32 v221, v30, v30
	v_fmac_f32_e32 v221, v31, v31
	v_cvt_pk_bf16_f32 v142, v142, v143
	v_cvt_pk_bf16_f32 v143, v144, v145
	global_store_dwordx2 v220, v[142:143], s[14:15] offset:0
	v_mul_f32_e32 v146, v24, v190
	v_mul_f32_e32 v147, v25, v191
	v_mul_f32_e32 v148, v26, v192
	v_mul_f32_e32 v149, v27, v193
	v_fmac_f32_e32 v221, v24, v24
	v_fmac_f32_e32 v221, v25, v25
	v_fmac_f32_e32 v221, v26, v26
	v_fmac_f32_e32 v221, v27, v27
	v_cvt_pk_bf16_f32 v146, v146, v147
	v_cvt_pk_bf16_f32 v147, v148, v149
	global_store_dwordx2 v220, v[146:147], s[14:15] offset:32
	v_mov_b32_e32 v28, v221
	v_add_u32_e32 v219, 0x20000, v219
	s_waitcnt vmcnt(12)
	v_pk_fma_f32 v[14:15], v[14:15], v[162:163], v[178:179]
	v_pk_fma_f32 v[12:13], v[12:13], v[160:161], v[176:177]
	global_store_dwordx4 v219, v[12:15], s[10:11] offset:0
	v_pk_fma_f32 v[10:11], v[10:11], v[166:167], v[182:183]
	v_pk_fma_f32 v[8:9], v[8:9], v[164:165], v[180:181]
	global_store_dwordx4 v219, v[8:11], s[10:11] offset:64
	v_lshrrev_b32_e32 v220, 1, v219
	v_mul_f32_e32 v176, v12, v186
	v_mul_f32_e32 v177, v13, v187
	v_mul_f32_e32 v178, v14, v188
	v_mul_f32_e32 v179, v15, v189
	v_mul_f32_e32 v221, v12, v12
	v_fmac_f32_e32 v221, v13, v13
	v_fmac_f32_e32 v221, v14, v14
	v_fmac_f32_e32 v221, v15, v15
	v_cvt_pk_bf16_f32 v176, v176, v177
	v_cvt_pk_bf16_f32 v177, v178, v179
	global_store_dwordx2 v220, v[176:177], s[14:15] offset:0
	v_mul_f32_e32 v180, v8, v190
	v_mul_f32_e32 v181, v9, v191
	v_mul_f32_e32 v182, v10, v192
	v_mul_f32_e32 v183, v11, v193
	v_fmac_f32_e32 v221, v8, v8
	v_fmac_f32_e32 v221, v9, v9
	v_fmac_f32_e32 v221, v10, v10
	v_fmac_f32_e32 v221, v11, v11
	v_cvt_pk_bf16_f32 v180, v180, v181
	v_cvt_pk_bf16_f32 v181, v182, v183
	global_store_dwordx2 v220, v[180:181], s[14:15] offset:32
	v_mov_b32_e32 v12, v221
	v_xor_b32_e32 v220, 16, v158
	v_lshlrev_b32_e32 v220, 2, v220
	v_xor_b32_e32 v221, 32, v158
	v_lshlrev_b32_e32 v221, 2, v221
	ds_bpermute_b32 v202, v220, v60
	ds_bpermute_b32 v203, v220, v44
	ds_bpermute_b32 v204, v220, v28
	ds_bpermute_b32 v205, v220, v12
	s_waitcnt lgkmcnt(0)
	v_add_f32_e32 v60, v60, v202
	v_add_f32_e32 v44, v44, v203
	v_add_f32_e32 v28, v28, v204
	v_add_f32_e32 v12, v12, v205
	ds_bpermute_b32 v202, v221, v60
	ds_bpermute_b32 v203, v221, v44
	ds_bpermute_b32 v204, v221, v28
	ds_bpermute_b32 v205, v221, v12
	v_add_u32_e32 v220, s48, v152
	v_lshlrev_b32_e32 v220, 2, v220
	s_waitcnt lgkmcnt(0)
	v_add_f32_e32 v60, v60, v202
	v_add_f32_e32 v44, v44, v203
	v_add_f32_e32 v28, v28, v204
	v_add_f32_e32 v12, v12, v205
	s_and_saveexec_b64 s[44:45], s[2:3]
	global_atomic_add_f32 v220, v60, s[28:29] offset:512
	global_atomic_add_f32 v220, v44, s[28:29] offset:576
	global_atomic_add_f32 v220, v28, s[28:29] offset:640
	global_atomic_add_f32 v220, v12, s[28:29] offset:704
	s_mov_b64 exec, s[44:45]
	s_branch .Lp8_epi_done
.Lp8_qepi_n2:
	v_add_u32_e32 v219, 0x100000, v219
	v_mov_b32_e32 v218, v219
	global_load_dwordx4 v[124:127], v222, s[26:27] offset:512
	global_load_dwordx4 v[120:123], v222, s[26:27] offset:576
	global_load_dwordx4 v[194:197], v132, s[24:25] offset:512
	global_load_dwordx4 v[198:201], v132, s[24:25] offset:576
	global_load_dwordx4 v[168:171], v223, s[8:9] offset:512
	global_load_dwordx4 v[172:175], v223, s[8:9] offset:576
	global_load_dwordx4 v[202:205], v218, s[46:47] offset:512
	global_load_dwordx4 v[206:209], v218, s[46:47] offset:576
	v_add_u32_e32 v218, 0x20000, v218
	global_load_dwordx4 v[210:213], v218, s[46:47] offset:512
	global_load_dwordx4 v[214:217], v218, s[46:47] offset:576
	v_add_u32_e32 v218, 0x20000, v218
	global_load_dwordx4 v[142:145], v218, s[46:47] offset:512
	global_load_dwordx4 v[146:149], v218, s[46:47] offset:576
	v_add_u32_e32 v218, 0x20000, v218
	global_load_dwordx4 v[176:179], v218, s[46:47] offset:512
	global_load_dwordx4 v[180:183], v218, s[46:47] offset:576
	s_waitcnt vmcnt(10)
	v_add_f32_e32 v124, 1.0, v124
	v_add_f32_e32 v125, 1.0, v125
	v_add_f32_e32 v126, 1.0, v126
	v_add_f32_e32 v127, 1.0, v127
	v_add_f32_e32 v120, 1.0, v120
	v_add_f32_e32 v121, 1.0, v121
	v_add_f32_e32 v122, 1.0, v122
	v_add_f32_e32 v123, 1.0, v123
	v_mul_f32_e32 v194, v194, v124
	v_mul_f32_e32 v195, v195, v125
	v_mul_f32_e32 v196, v196, v126
	v_mul_f32_e32 v197, v197, v127
	v_mul_f32_e32 v198, v198, v120
	v_mul_f32_e32 v199, v199, v121
	v_mul_f32_e32 v200, v200, v122
	v_mul_f32_e32 v201, v201, v123
	s_waitcnt vmcnt(6)
; __device__ __forceinline__ unsigned cvt_pk_bf16(float lo, float hi) { unsigned r; asm volatile("v_cvt_pk_bf16_f32 %0, %1, %2" : "=v"(r) : "v"(lo), "v"(hi)); return r; }
;     __device__ __forceinline__ void operator()(const gacc_t (&acc)[2][2][4][2], const Unit& u, int wr, int wc, int fr, int fq) const {
;     ...
;             for (int m = 0; m < 4; ++m) { const int row = u.pm * 256 + ai * 128 + wr * 64 + m * 16 + fr;
;                 const float* bp = row < ML ? baseL + (size_t)row * D : baseC + (size_t)(row - ML) * D;
;                 const int mb = row < ML ? (row >> 11) : 8; const float* gp = mod + mb * MODW + chunk * D; float* op = out + (size_t)row * D;
;                 float sq = 0.f;
; #pragma unroll
;                 for (int bj = 0; bj < 2; ++bj)
; #pragma unroll
;                     for (int n = 0; n < 2; ++n) { const int col = u.pn * 256 + bj * 128 + wc * 32 + n * 16 + 4 * fq;
;                         const f32x4 b = *(const f32x4*)(bp + col), g = *(const f32x4*)(gp + col); const gacc_t a = acc[ai][bj][m][n];
;                         f32x4 o; o.x = b.x + g.x * a[0]; o.y = b.y + g.y * a[1]; o.z = b.z + g.z * a[2]; o.w = b.w + g.w * a[3];
;                         *(f32x4*)(op + col) = o;
;                         if (hu) { const f32x4 gg = *(const f32x4*)(gn + col), sc = *(const f32x4*)(scl + mb * MODW + col);
;                             sq += (o.x * o.x + o.y * o.y) + (o.z * o.z + o.w * o.w);
;                             u32x2 w; w.x = pg8::cvt_pk_bf16(o.x * gg.x * (1.f + sc.x), o.y * gg.y * (1.f + sc.y)); w.y = pg8::cvt_pk_bf16(o.z * gg.z * (1.f + sc.z), o.w * gg.w * (1.f + sc.w));
;                             *(u32x2*)(hu + (size_t)row * D + col) = w; } }
;                 if (hu) { sq += __shfl_xor(sq, 16); sq += __shfl_xor(sq, 32); if (fq == 0) __hip_atomic_fetch_add(ss + row, sq, __ATOMIC_RELAXED, __HIP_MEMORY_SCOPE_AGENT); } }
	v_pk_fma_f32 v[54:55], v[54:55], v[170:171], v[204:205]
	v_pk_fma_f32 v[52:53], v[52:53], v[168:169], v[202:203]
	global_store_dwordx4 v219, v[52:55], s[10:11] offset:512
	v_pk_fma_f32 v[50:51], v[50:51], v[174:175], v[208:209]
	v_pk_fma_f32 v[48:49], v[48:49], v[172:173], v[206:207]
	global_store_dwordx4 v219, v[48:51], s[10:11] offset:576
	v_lshrrev_b32_e32 v220, 1, v219
	v_mul_f32_e32 v202, v52, v194
	v_mul_f32_e32 v203, v53, v195
	v_mul_f32_e32 v204, v54, v196
	v_mul_f32_e32 v205, v55, v197
	v_mul_f32_e32 v221, v52, v52
	v_fmac_f32_e32 v221, v53, v53
	v_fmac_f32_e32 v221, v54, v54
	v_fmac_f32_e32 v221, v55, v55
	v_cvt_pk_bf16_f32 v202, v202, v203
	v_cvt_pk_bf16_f32 v203, v204, v205
	global_store_dwordx2 v220, v[202:203], s[14:15] offset:256
	v_mul_f32_e32 v206, v48, v198
	v_mul_f32_e32 v207, v49, v199
	v_mul_f32_e32 v208, v50, v200
	v_mul_f32_e32 v209, v51, v201
	v_fmac_f32_e32 v221, v48, v48
	v_fmac_f32_e32 v221, v49, v49
	v_fmac_f32_e32 v221, v50, v50
	v_fmac_f32_e32 v221, v51, v51
	v_cvt_pk_bf16_f32 v206, v206, v207
	v_cvt_pk_bf16_f32 v207, v208, v209
	global_store_dwordx2 v220, v[206:207], s[14:15] offset:288
	v_mov_b32_e32 v52, v221
	v_add_u32_e32 v219, 0x20000, v219
	s_waitcnt vmcnt(8)
	v_pk_fma_f32 v[38:39], v[38:39], v[170:171], v[212:213]
	v_pk_fma_f32 v[36:37], v[36:37], v[168:169], v[210:211]
	global_store_dwordx4 v219, v[36:39], s[10:11] offset:512
	v_pk_fma_f32 v[34:35], v[34:35], v[174:175], v[216:217]
	v_pk_fma_f32 v[32:33], v[32:33], v[172:173], v[214:215]
	global_store_dwordx4 v219, v[32:35], s[10:11] offset:576
	v_lshrrev_b32_e32 v220, 1, v219
	v_mul_f32_e32 v210, v36, v194
	v_mul_f32_e32 v211, v37, v195
	v_mul_f32_e32 v212, v38, v196
	v_mul_f32_e32 v213, v39, v197
	v_mul_f32_e32 v221, v36, v36
	v_fmac_f32_e32 v221, v37, v37
	v_fmac_f32_e32 v221, v38, v38
	v_fmac_f32_e32 v221, v39, v39
	v_cvt_pk_bf16_f32 v210, v210, v211
	v_cvt_pk_bf16_f32 v211, v212, v213
	global_store_dwordx2 v220, v[210:211], s[14:15] offset:256
	v_mul_f32_e32 v214, v32, v198
	v_mul_f32_e32 v215, v33, v199
	v_mul_f32_e32 v216, v34, v200
	v_mul_f32_e32 v217, v35, v201
	v_fmac_f32_e32 v221, v32, v32
	v_fmac_f32_e32 v221, v33, v33
	v_fmac_f32_e32 v221, v34, v34
	v_fmac_f32_e32 v221, v35, v35
	v_cvt_pk_bf16_f32 v214, v214, v215
	v_cvt_pk_bf16_f32 v215, v216, v217
	global_store_dwordx2 v220, v[214:215], s[14:15] offset:288
	v_mov_b32_e32 v36, v221
	v_add_u32_e32 v219, 0x20000, v219
	s_waitcnt vmcnt(10)
	v_pk_fma_f32 v[22:23], v[22:23], v[170:171], v[144:145]
	v_pk_fma_f32 v[20:21], v[20:21], v[168:169], v[142:143]
	global_store_dwordx4 v219, v[20:23], s[10:11] offset:512
	v_pk_fma_f32 v[18:19], v[18:19], v[174:175], v[148:149]
	v_pk_fma_f32 v[16:17], v[16:17], v[172:173], v[146:147]
	global_store_dwordx4 v219, v[16:19], s[10:11] offset:576
	v_lshrrev_b32_e32 v220, 1, v219
	v_mul_f32_e32 v142, v20, v194
	v_mul_f32_e32 v143, v21, v195
	v_mul_f32_e32 v144, v22, v196
	v_mul_f32_e32 v145, v23, v197
	v_mul_f32_e32 v221, v20, v20
	v_fmac_f32_e32 v221, v21, v21
	v_fmac_f32_e32 v221, v22, v22
	v_fmac_f32_e32 v221, v23, v23
	v_cvt_pk_bf16_f32 v142, v142, v143
	v_cvt_pk_bf16_f32 v143, v144, v145
	global_store_dwordx2 v220, v[142:143], s[14:15] offset:256
	v_mul_f32_e32 v146, v16, v198
	v_mul_f32_e32 v147, v17, v199
	v_mul_f32_e32 v148, v18, v200
	v_mul_f32_e32 v149, v19, v201
	v_fmac_f32_e32 v221, v16, v16
	v_fmac_f32_e32 v221, v17, v17
	v_fmac_f32_e32 v221, v18, v18
	v_fmac_f32_e32 v221, v19, v19
	v_cvt_pk_bf16_f32 v146, v146, v147
	v_cvt_pk_bf16_f32 v147, v148, v149
	global_store_dwordx2 v220, v[146:147], s[14:15] offset:288
	v_mov_b32_e32 v20, v221
	v_add_u32_e32 v219, 0x20000, v219
	s_waitcnt vmcnt(12)
	v_pk_fma_f32 v[6:7], v[6:7], v[170:171], v[178:179]
	v_pk_fma_f32 v[4:5], v[4:5], v[168:169], v[176:177]
	global_store_dwordx4 v219, v[4:7], s[10:11] offset:512
	v_pk_fma_f32 v[2:3], v[2:3], v[174:175], v[182:183]
	v_pk_fma_f32 v[0:1], v[0:1], v[172:173], v[180:181]
	global_store_dwordx4 v219, v[0:3], s[10:11] offset:576
	v_lshrrev_b32_e32 v220, 1, v219
	v_mul_f32_e32 v176, v4, v194
	v_mul_f32_e32 v177, v5, v195
	v_mul_f32_e32 v178, v6, v196
	v_mul_f32_e32 v179, v7, v197
	v_mul_f32_e32 v221, v4, v4
	v_fmac_f32_e32 v221, v5, v5
	v_fmac_f32_e32 v221, v6, v6
	v_fmac_f32_e32 v221, v7, v7
	v_cvt_pk_bf16_f32 v176, v176, v177
	v_cvt_pk_bf16_f32 v177, v178, v179
	global_store_dwordx2 v220, v[176:177], s[14:15] offset:256
	v_mul_f32_e32 v180, v0, v198
	v_mul_f32_e32 v181, v1, v199
	v_mul_f32_e32 v182, v2, v200
	v_mul_f32_e32 v183, v3, v201
	v_fmac_f32_e32 v221, v0, v0
	v_fmac_f32_e32 v221, v1, v1
	v_fmac_f32_e32 v221, v2, v2
	v_fmac_f32_e32 v221, v3, v3
	v_cvt_pk_bf16_f32 v180, v180, v181
	v_cvt_pk_bf16_f32 v181, v182, v183
	global_store_dwordx2 v220, v[180:181], s[14:15] offset:288
	v_mov_b32_e32 v4, v221
	v_xor_b32_e32 v220, 16, v158
	v_lshlrev_b32_e32 v220, 2, v220
	v_xor_b32_e32 v221, 32, v158
	v_lshlrev_b32_e32 v221, 2, v221
	ds_bpermute_b32 v202, v220, v52
	ds_bpermute_b32 v203, v220, v36
	ds_bpermute_b32 v204, v220, v20
	ds_bpermute_b32 v205, v220, v4
	s_waitcnt lgkmcnt(0)
	v_add_f32_e32 v52, v52, v202
	v_add_f32_e32 v36, v36, v203
	v_add_f32_e32 v20, v20, v204
	v_add_f32_e32 v4, v4, v205
	ds_bpermute_b32 v202, v221, v52
	ds_bpermute_b32 v203, v221, v36
	ds_bpermute_b32 v204, v221, v20
	ds_bpermute_b32 v205, v221, v4
	v_add_u32_e32 v220, s48, v152
	v_lshlrev_b32_e32 v220, 2, v220
	s_waitcnt lgkmcnt(0)
	v_add_f32_e32 v52, v52, v202
	v_add_f32_e32 v36, v36, v203
	v_add_f32_e32 v20, v20, v204
	v_add_f32_e32 v4, v4, v205
	s_and_saveexec_b64 s[44:45], s[2:3]
	global_atomic_add_f32 v220, v52, s[28:29] offset:512
	global_atomic_add_f32 v220, v36, s[28:29] offset:576
	global_atomic_add_f32 v220, v20, s[28:29] offset:640
	global_atomic_add_f32 v220, v4, s[28:29] offset:704
	s_mov_b64 exec, s[44:45]
.Lp8_epi_done:
	s_and_b64 vcc, exec, s[4:5]
	s_mov_b64 s[4:5], -1
	s_cbranch_vccnz .LBB0_820
	s_andn2_b64 vcc, exec, s[0:1]
	s_cbranch_vccnz .LBB0_819
	s_barrier
	s_branch .LBB0_819

; __device__ __forceinline__ unsigned cvt_pk_bf16(float lo, float hi) { unsigned r; asm volatile("v_cvt_pk_bf16_f32 %0, %1, %2" : "=v"(r) : "v"(lo), "v"(hi)); return r; }
;     __device__ __forceinline__ void operator()(const gacc_t (&acc)[2][2][4][2], const Unit& u, int wr, int wc, int fr, int fq) const {
;     ...
;             for (int m = 0; m < 4; ++m) { const int row = u.pm * 256 + ai * 128 + wr * 64 + m * 16 + fr;
;                 const float* bp = row < ML ? baseL + (size_t)row * D : baseC + (size_t)(row - ML) * D;
;                 const int mb = row < ML ? (row >> 11) : 8; const float* gp = mod + mb * MODW + chunk * D; float* op = out + (size_t)row * D;
;                 float sq = 0.f;
; #pragma unroll
;                 for (int bj = 0; bj < 2; ++bj)
; #pragma unroll
;                     for (int n = 0; n < 2; ++n) { const int col = u.pn * 256 + bj * 128 + wc * 32 + n * 16 + 4 * fq;
;                         const f32x4 b = *(const f32x4*)(bp + col), g = *(const f32x4*)(gp + col); const gacc_t a = acc[ai][bj][m][n];
;                         f32x4 o; o.x = b.x + g.x * a[0]; o.y = b.y + g.y * a[1]; o.z = b.z + g.z * a[2]; o.w = b.w + g.w * a[3];
;                         *(f32x4*)(op + col) = o;
;                         if (hu) { const f32x4 gg = *(const f32x4*)(gn + col), sc = *(const f32x4*)(scl + mb * MODW + col);
;                             sq += (o.x * o.x + o.y * o.y) + (o.z * o.z + o.w * o.w);
;                             u32x2 w; w.x = pg8::cvt_pk_bf16(o.x * gg.x * (1.f + sc.x), o.y * gg.y * (1.f + sc.y)); w.y = pg8::cvt_pk_bf16(o.z * gg.z * (1.f + sc.z), o.w * gg.w * (1.f + sc.w));
;                             *(u32x2*)(hu + (size_t)row * D + col) = w; } }
.LBB0_1479:
	s_lshl_b32 s27, s38, 8
	s_add_i32 s27, s27, s56
	s_lshr_b32 s29, s27, 11
	s_mul_i32 s29, s29, 0xc000
	s_cmpk_gt_i32 s27, 0x3fff
	s_cselect_b32 s29, 0x60000, s29
	s_cselect_b32 s40, s10, s6
	s_cselect_b32 s41, s11, s7
	v_lshl_or_b32 v132, s36, 8, v154
	v_lshlrev_b32_e32 v132, 2, v132
	v_add_u32_e32 v222, s29, v132
	v_add_u32_e32 v223, s24, v222
	v_add_u32_e32 v220, s27, v152
	v_lshl_add_u32 v219, v220, 13, v132
	s_cselect_b32 s29, 0x8000000, 0
	s_sub_u32 s40, s40, s29
	s_subb_u32 s41, s41, 0
	v_mov_b32_e32 v218, v219
	global_load_dwordx4 v[142:145], v222, s[16:17] offset:0
	global_load_dwordx4 v[146:149], v222, s[16:17] offset:64
	global_load_dwordx4 v[176:179], v222, s[16:17] offset:512
	global_load_dwordx4 v[180:183], v222, s[16:17] offset:576
	global_load_dwordx4 v[186:189], v132, s[14:15] offset:0
	global_load_dwordx4 v[190:193], v132, s[14:15] offset:64
	global_load_dwordx4 v[194:197], v132, s[14:15] offset:512
	global_load_dwordx4 v[198:201], v132, s[14:15] offset:576
	global_load_dwordx4 v[160:163], v223, s[12:13] offset:0
	global_load_dwordx4 v[164:167], v223, s[12:13] offset:64
	global_load_dwordx4 v[168:171], v223, s[12:13] offset:512
	global_load_dwordx4 v[172:175], v223, s[12:13] offset:576
	global_load_dwordx4 v[202:205], v218, s[40:41] offset:0
	global_load_dwordx4 v[206:209], v218, s[40:41] offset:64
	global_load_dwordx4 v[210:213], v218, s[40:41] offset:512
	global_load_dwordx4 v[214:217], v218, s[40:41] offset:576
	v_add_u32_e32 v218, 0x20000, v218
	s_waitcnt vmcnt(8)
	v_add_f32_e32 v142, 1.0, v142
	v_add_f32_e32 v143, 1.0, v143
	v_add_f32_e32 v144, 1.0, v144
	v_add_f32_e32 v145, 1.0, v145
	v_add_f32_e32 v146, 1.0, v146
	v_add_f32_e32 v147, 1.0, v147
	v_add_f32_e32 v148, 1.0, v148
	v_add_f32_e32 v149, 1.0, v149
	v_add_f32_e32 v176, 1.0, v176
	v_add_f32_e32 v177, 1.0, v177
	v_add_f32_e32 v178, 1.0, v178
	v_add_f32_e32 v179, 1.0, v179
	v_add_f32_e32 v180, 1.0, v180
	v_add_f32_e32 v181, 1.0, v181
	v_add_f32_e32 v182, 1.0, v182
	v_add_f32_e32 v183, 1.0, v183
	v_mul_f32_e32 v186, v186, v142
	v_mul_f32_e32 v187, v187, v143
	v_mul_f32_e32 v188, v188, v144
	v_mul_f32_e32 v189, v189, v145
	v_mul_f32_e32 v190, v190, v146
	v_mul_f32_e32 v191, v191, v147
	v_mul_f32_e32 v192, v192, v148
	v_mul_f32_e32 v193, v193, v149
	v_mul_f32_e32 v194, v194, v176
	v_mul_f32_e32 v195, v195, v177
	v_mul_f32_e32 v196, v196, v178
	v_mul_f32_e32 v197, v197, v179
	v_mul_f32_e32 v198, v198, v180
	v_mul_f32_e32 v199, v199, v181
	v_mul_f32_e32 v200, v200, v182
	v_mul_f32_e32 v201, v201, v183
	global_load_dwordx4 v[142:145], v218, s[40:41] offset:0
	global_load_dwordx4 v[146:149], v218, s[40:41] offset:64
	global_load_dwordx4 v[176:179], v218, s[40:41] offset:512
	global_load_dwordx4 v[180:183], v218, s[40:41] offset:576
	v_add_u32_e32 v218, 0x20000, v218
	s_waitcnt vmcnt(4)
	v_pk_fma_f32 v[126:127], v[126:127], v[162:163], v[204:205]
	v_pk_fma_f32 v[124:125], v[124:125], v[160:161], v[202:203]
	global_store_dwordx4 v219, v[124:127], s[6:7] offset:0
	v_pk_fma_f32 v[122:123], v[122:123], v[166:167], v[208:209]
	v_pk_fma_f32 v[120:121], v[120:121], v[164:165], v[206:207]
	global_store_dwordx4 v219, v[120:123], s[6:7] offset:64
	v_pk_fma_f32 v[118:119], v[118:119], v[170:171], v[212:213]
	v_pk_fma_f32 v[116:117], v[116:117], v[168:169], v[210:211]
	global_store_dwordx4 v219, v[116:119], s[6:7] offset:512
	v_pk_fma_f32 v[114:115], v[114:115], v[174:175], v[216:217]
	v_pk_fma_f32 v[112:113], v[112:113], v[172:173], v[214:215]
	global_store_dwordx4 v219, v[112:115], s[6:7] offset:576
	v_lshrrev_b32_e32 v220, 1, v219
	v_mul_f32_e32 v202, v124, v186
	v_mul_f32_e32 v203, v125, v187
	v_mul_f32_e32 v204, v126, v188
	v_mul_f32_e32 v205, v127, v189
	v_mul_f32_e32 v221, v124, v124
	v_fmac_f32_e32 v221, v125, v125
	v_fmac_f32_e32 v221, v126, v126
	v_fmac_f32_e32 v221, v127, v127
	v_cvt_pk_bf16_f32 v202, v202, v203
	v_cvt_pk_bf16_f32 v203, v204, v205
	global_store_dwordx2 v220, v[202:203], s[8:9] offset:0
	v_mul_f32_e32 v206, v120, v190
	v_mul_f32_e32 v207, v121, v191
	v_mul_f32_e32 v208, v122, v192
	v_mul_f32_e32 v209, v123, v193
	v_fmac_f32_e32 v221, v120, v120
	v_fmac_f32_e32 v221, v121, v121
	v_fmac_f32_e32 v221, v122, v122
	v_fmac_f32_e32 v221, v123, v123
	v_cvt_pk_bf16_f32 v206, v206, v207
	v_cvt_pk_bf16_f32 v207, v208, v209
	global_store_dwordx2 v220, v[206:207], s[8:9] offset:32
	v_mul_f32_e32 v210, v116, v194
	v_mul_f32_e32 v211, v117, v195
	v_mul_f32_e32 v212, v118, v196
	v_mul_f32_e32 v213, v119, v197
	v_fmac_f32_e32 v221, v116, v116
	v_fmac_f32_e32 v221, v117, v117
	v_fmac_f32_e32 v221, v118, v118
	v_fmac_f32_e32 v221, v119, v119
	v_cvt_pk_bf16_f32 v210, v210, v211
	v_cvt_pk_bf16_f32 v211, v212, v213
	global_store_dwordx2 v220, v[210:211], s[8:9] offset:256
	v_mul_f32_e32 v214, v112, v198
	v_mul_f32_e32 v215, v113, v199
	v_mul_f32_e32 v216, v114, v200
	v_mul_f32_e32 v217, v115, v201
	v_fmac_f32_e32 v221, v112, v112
	v_fmac_f32_e32 v221, v113, v113
	v_fmac_f32_e32 v221, v114, v114
	v_fmac_f32_e32 v221, v115, v115
	v_cvt_pk_bf16_f32 v214, v214, v215
	v_cvt_pk_bf16_f32 v215, v216, v217
	global_store_dwordx2 v220, v[214:215], s[8:9] offset:288
	v_mov_b32_e32 v124, v221
	global_load_dwordx4 v[202:205], v218, s[40:41] offset:0
	global_load_dwordx4 v[206:209], v218, s[40:41] offset:64
	global_load_dwordx4 v[210:213], v218, s[40:41] offset:512
	global_load_dwordx4 v[214:217], v218, s[40:41] offset:576
	v_add_u32_e32 v218, 0x20000, v218
	v_add_u32_e32 v219, 0x20000, v219
	s_waitcnt vmcnt(12)
; __device__ __forceinline__ unsigned cvt_pk_bf16(float lo, float hi) { unsigned r; asm volatile("v_cvt_pk_bf16_f32 %0, %1, %2" : "=v"(r) : "v"(lo), "v"(hi)); return r; }
;     __device__ __forceinline__ void operator()(const gacc_t (&acc)[2][2][4][2], const Unit& u, int wr, int wc, int fr, int fq) const {
;     ...
;                 for (int bj = 0; bj < 2; ++bj)
; #pragma unroll
;                     for (int n = 0; n < 2; ++n) { const int col = u.pn * 256 + bj * 128 + wc * 32 + n * 16 + 4 * fq;
;                         const f32x4 b = *(const f32x4*)(bp + col), g = *(const f32x4*)(gp + col); const gacc_t a = acc[ai][bj][m][n];
;                         f32x4 o; o.x = b.x + g.x * a[0]; o.y = b.y + g.y * a[1]; o.z = b.z + g.z * a[2]; o.w = b.w + g.w * a[3];
;                         *(f32x4*)(op + col) = o;
;                         if (hu) { const f32x4 gg = *(const f32x4*)(gn + col), sc = *(const f32x4*)(scl + mb * MODW + col);
;                             sq += (o.x * o.x + o.y * o.y) + (o.z * o.z + o.w * o.w);
;                             u32x2 w; w.x = pg8::cvt_pk_bf16(o.x * gg.x * (1.f + sc.x), o.y * gg.y * (1.f + sc.y)); w.y = pg8::cvt_pk_bf16(o.z * gg.z * (1.f + sc.z), o.w * gg.w * (1.f + sc.w));
;                             *(u32x2*)(hu + (size_t)row * D + col) = w; } }
	v_pk_fma_f32 v[110:111], v[110:111], v[162:163], v[144:145]
	v_pk_fma_f32 v[108:109], v[108:109], v[160:161], v[142:143]
	global_store_dwordx4 v219, v[108:111], s[6:7] offset:0
	v_pk_fma_f32 v[106:107], v[106:107], v[166:167], v[148:149]
	v_pk_fma_f32 v[104:105], v[104:105], v[164:165], v[146:147]
	global_store_dwordx4 v219, v[104:107], s[6:7] offset:64
	v_pk_fma_f32 v[102:103], v[102:103], v[170:171], v[178:179]
	v_pk_fma_f32 v[100:101], v[100:101], v[168:169], v[176:177]
	global_store_dwordx4 v219, v[100:103], s[6:7] offset:512
	v_pk_fma_f32 v[98:99], v[98:99], v[174:175], v[182:183]
	v_pk_fma_f32 v[96:97], v[96:97], v[172:173], v[180:181]
	global_store_dwordx4 v219, v[96:99], s[6:7] offset:576
	v_lshrrev_b32_e32 v220, 1, v219
	v_mul_f32_e32 v142, v108, v186
	v_mul_f32_e32 v143, v109, v187
	v_mul_f32_e32 v144, v110, v188
	v_mul_f32_e32 v145, v111, v189
	v_mul_f32_e32 v221, v108, v108
	v_fmac_f32_e32 v221, v109, v109
	v_fmac_f32_e32 v221, v110, v110
	v_fmac_f32_e32 v221, v111, v111
	v_cvt_pk_bf16_f32 v142, v142, v143
	v_cvt_pk_bf16_f32 v143, v144, v145
	global_store_dwordx2 v220, v[142:143], s[8:9] offset:0
	v_mul_f32_e32 v146, v104, v190
	v_mul_f32_e32 v147, v105, v191
	v_mul_f32_e32 v148, v106, v192
	v_mul_f32_e32 v149, v107, v193
	v_fmac_f32_e32 v221, v104, v104
	v_fmac_f32_e32 v221, v105, v105
	v_fmac_f32_e32 v221, v106, v106
	v_fmac_f32_e32 v221, v107, v107
	v_cvt_pk_bf16_f32 v146, v146, v147
	v_cvt_pk_bf16_f32 v147, v148, v149
	global_store_dwordx2 v220, v[146:147], s[8:9] offset:32
	v_mul_f32_e32 v176, v100, v194
	v_mul_f32_e32 v177, v101, v195
	v_mul_f32_e32 v178, v102, v196
	v_mul_f32_e32 v179, v103, v197
	v_fmac_f32_e32 v221, v100, v100
	v_fmac_f32_e32 v221, v101, v101
	v_fmac_f32_e32 v221, v102, v102
	v_fmac_f32_e32 v221, v103, v103
	v_cvt_pk_bf16_f32 v176, v176, v177
	v_cvt_pk_bf16_f32 v177, v178, v179
	global_store_dwordx2 v220, v[176:177], s[8:9] offset:256
	v_mul_f32_e32 v180, v96, v198
	v_mul_f32_e32 v181, v97, v199
	v_mul_f32_e32 v182, v98, v200
	v_mul_f32_e32 v183, v99, v201
	v_fmac_f32_e32 v221, v96, v96
	v_fmac_f32_e32 v221, v97, v97
	v_fmac_f32_e32 v221, v98, v98
	v_fmac_f32_e32 v221, v99, v99
	v_cvt_pk_bf16_f32 v180, v180, v181
	v_cvt_pk_bf16_f32 v181, v182, v183
	global_store_dwordx2 v220, v[180:181], s[8:9] offset:288
	v_mov_b32_e32 v108, v221
	global_load_dwordx4 v[142:145], v218, s[40:41] offset:0
	global_load_dwordx4 v[146:149], v218, s[40:41] offset:64
	global_load_dwordx4 v[176:179], v218, s[40:41] offset:512
	global_load_dwordx4 v[180:183], v218, s[40:41] offset:576
	v_add_u32_e32 v218, 0xa0000, v218
	v_add_u32_e32 v219, 0x20000, v219
	s_waitcnt vmcnt(12)
	v_pk_fma_f32 v[94:95], v[94:95], v[162:163], v[204:205]
	v_pk_fma_f32 v[92:93], v[92:93], v[160:161], v[202:203]
	global_store_dwordx4 v219, v[92:95], s[6:7] offset:0
	v_pk_fma_f32 v[90:91], v[90:91], v[166:167], v[208:209]
	v_pk_fma_f32 v[88:89], v[88:89], v[164:165], v[206:207]
	global_store_dwordx4 v219, v[88:91], s[6:7] offset:64
	v_pk_fma_f32 v[86:87], v[86:87], v[170:171], v[212:213]
	v_pk_fma_f32 v[84:85], v[84:85], v[168:169], v[210:211]
	global_store_dwordx4 v219, v[84:87], s[6:7] offset:512
	v_pk_fma_f32 v[82:83], v[82:83], v[174:175], v[216:217]
	v_pk_fma_f32 v[80:81], v[80:81], v[172:173], v[214:215]
	global_store_dwordx4 v219, v[80:83], s[6:7] offset:576
	v_lshrrev_b32_e32 v220, 1, v219
	v_mul_f32_e32 v202, v92, v186
	v_mul_f32_e32 v203, v93, v187
	v_mul_f32_e32 v204, v94, v188
	v_mul_f32_e32 v205, v95, v189
	v_mul_f32_e32 v221, v92, v92
	v_fmac_f32_e32 v221, v93, v93
	v_fmac_f32_e32 v221, v94, v94
	v_fmac_f32_e32 v221, v95, v95
	v_cvt_pk_bf16_f32 v202, v202, v203
	v_cvt_pk_bf16_f32 v203, v204, v205
	global_store_dwordx2 v220, v[202:203], s[8:9] offset:0
	v_mul_f32_e32 v206, v88, v190
	v_mul_f32_e32 v207, v89, v191
	v_mul_f32_e32 v208, v90, v192
	v_mul_f32_e32 v209, v91, v193
	v_fmac_f32_e32 v221, v88, v88
	v_fmac_f32_e32 v221, v89, v89
	v_fmac_f32_e32 v221, v90, v90
	v_fmac_f32_e32 v221, v91, v91
	v_cvt_pk_bf16_f32 v206, v206, v207
	v_cvt_pk_bf16_f32 v207, v208, v209
	global_store_dwordx2 v220, v[206:207], s[8:9] offset:32
	v_mul_f32_e32 v210, v84, v194
	v_mul_f32_e32 v211, v85, v195
	v_mul_f32_e32 v212, v86, v196
	v_mul_f32_e32 v213, v87, v197
	v_fmac_f32_e32 v221, v84, v84
	v_fmac_f32_e32 v221, v85, v85
	v_fmac_f32_e32 v221, v86, v86
	v_fmac_f32_e32 v221, v87, v87
	v_cvt_pk_bf16_f32 v210, v210, v211
	v_cvt_pk_bf16_f32 v211, v212, v213
	global_store_dwordx2 v220, v[210:211], s[8:9] offset:256
	v_mul_f32_e32 v214, v80, v198
	v_mul_f32_e32 v215, v81, v199
	v_mul_f32_e32 v216, v82, v200
	v_mul_f32_e32 v217, v83, v201
	v_fmac_f32_e32 v221, v80, v80
	v_fmac_f32_e32 v221, v81, v81
	v_fmac_f32_e32 v221, v82, v82
	v_fmac_f32_e32 v221, v83, v83
	v_cvt_pk_bf16_f32 v214, v214, v215
	v_cvt_pk_bf16_f32 v215, v216, v217
	global_store_dwordx2 v220, v[214:215], s[8:9] offset:288
	v_mov_b32_e32 v92, v221
	global_load_dwordx4 v[202:205], v218, s[40:41] offset:0
	global_load_dwordx4 v[206:209], v218, s[40:41] offset:64
	global_load_dwordx4 v[210:213], v218, s[40:41] offset:512
	global_load_dwordx4 v[214:217], v218, s[40:41] offset:576
	v_add_u32_e32 v218, 0x20000, v218
	v_add_u32_e32 v219, 0x20000, v219
	s_waitcnt vmcnt(12)
; __device__ __forceinline__ unsigned cvt_pk_bf16(float lo, float hi) { unsigned r; asm volatile("v_cvt_pk_bf16_f32 %0, %1, %2" : "=v"(r) : "v"(lo), "v"(hi)); return r; }
;     __device__ __forceinline__ void operator()(const gacc_t (&acc)[2][2][4][2], const Unit& u, int wr, int wc, int fr, int fq) const {
;     ...
;                     for (int n = 0; n < 2; ++n) { const int col = u.pn * 256 + bj * 128 + wc * 32 + n * 16 + 4 * fq;
;                         const f32x4 b = *(const f32x4*)(bp + col), g = *(const f32x4*)(gp + col); const gacc_t a = acc[ai][bj][m][n];
;                         f32x4 o; o.x = b.x + g.x * a[0]; o.y = b.y + g.y * a[1]; o.z = b.z + g.z * a[2]; o.w = b.w + g.w * a[3];
;                         *(f32x4*)(op + col) = o;
;                         if (hu) { const f32x4 gg = *(const f32x4*)(gn + col), sc = *(const f32x4*)(scl + mb * MODW + col);
;                             sq += (o.x * o.x + o.y * o.y) + (o.z * o.z + o.w * o.w);
;                             u32x2 w; w.x = pg8::cvt_pk_bf16(o.x * gg.x * (1.f + sc.x), o.y * gg.y * (1.f + sc.y)); w.y = pg8::cvt_pk_bf16(o.z * gg.z * (1.f + sc.z), o.w * gg.w * (1.f + sc.w));
;                             *(u32x2*)(hu + (size_t)row * D + col) = w; } }
	v_pk_fma_f32 v[78:79], v[78:79], v[162:163], v[144:145]
	v_pk_fma_f32 v[76:77], v[76:77], v[160:161], v[142:143]
	global_store_dwordx4 v219, v[76:79], s[6:7] offset:0
	v_pk_fma_f32 v[74:75], v[74:75], v[166:167], v[148:149]
	v_pk_fma_f32 v[72:73], v[72:73], v[164:165], v[146:147]
	global_store_dwordx4 v219, v[72:75], s[6:7] offset:64
	v_pk_fma_f32 v[70:71], v[70:71], v[170:171], v[178:179]
	v_pk_fma_f32 v[68:69], v[68:69], v[168:169], v[176:177]
	global_store_dwordx4 v219, v[68:71], s[6:7] offset:512
	v_pk_fma_f32 v[66:67], v[66:67], v[174:175], v[182:183]
	v_pk_fma_f32 v[64:65], v[64:65], v[172:173], v[180:181]
	global_store_dwordx4 v219, v[64:67], s[6:7] offset:576
	v_lshrrev_b32_e32 v220, 1, v219
	v_mul_f32_e32 v142, v76, v186
	v_mul_f32_e32 v143, v77, v187
	v_mul_f32_e32 v144, v78, v188
	v_mul_f32_e32 v145, v79, v189
	v_mul_f32_e32 v221, v76, v76
	v_fmac_f32_e32 v221, v77, v77
	v_fmac_f32_e32 v221, v78, v78
	v_fmac_f32_e32 v221, v79, v79
	v_cvt_pk_bf16_f32 v142, v142, v143
	v_cvt_pk_bf16_f32 v143, v144, v145
	global_store_dwordx2 v220, v[142:143], s[8:9] offset:0
	v_mul_f32_e32 v146, v72, v190
	v_mul_f32_e32 v147, v73, v191
	v_mul_f32_e32 v148, v74, v192
	v_mul_f32_e32 v149, v75, v193
	v_fmac_f32_e32 v221, v72, v72
	v_fmac_f32_e32 v221, v73, v73
	v_fmac_f32_e32 v221, v74, v74
	v_fmac_f32_e32 v221, v75, v75
	v_cvt_pk_bf16_f32 v146, v146, v147
	v_cvt_pk_bf16_f32 v147, v148, v149
	global_store_dwordx2 v220, v[146:147], s[8:9] offset:32
	v_mul_f32_e32 v176, v68, v194
	v_mul_f32_e32 v177, v69, v195
	v_mul_f32_e32 v178, v70, v196
	v_mul_f32_e32 v179, v71, v197
	v_fmac_f32_e32 v221, v68, v68
	v_fmac_f32_e32 v221, v69, v69
	v_fmac_f32_e32 v221, v70, v70
	v_fmac_f32_e32 v221, v71, v71
	v_cvt_pk_bf16_f32 v176, v176, v177
	v_cvt_pk_bf16_f32 v177, v178, v179
	global_store_dwordx2 v220, v[176:177], s[8:9] offset:256
	v_mul_f32_e32 v180, v64, v198
	v_mul_f32_e32 v181, v65, v199
	v_mul_f32_e32 v182, v66, v200
	v_mul_f32_e32 v183, v67, v201
	v_fmac_f32_e32 v221, v64, v64
	v_fmac_f32_e32 v221, v65, v65
	v_fmac_f32_e32 v221, v66, v66
	v_fmac_f32_e32 v221, v67, v67
	v_cvt_pk_bf16_f32 v180, v180, v181
	v_cvt_pk_bf16_f32 v181, v182, v183
	global_store_dwordx2 v220, v[180:181], s[8:9] offset:288
	v_mov_b32_e32 v76, v221
	global_load_dwordx4 v[142:145], v218, s[40:41] offset:0
	global_load_dwordx4 v[146:149], v218, s[40:41] offset:64
	global_load_dwordx4 v[176:179], v218, s[40:41] offset:512
	global_load_dwordx4 v[180:183], v218, s[40:41] offset:576
	v_add_u32_e32 v218, 0x20000, v218
	v_add_u32_e32 v219, 0xa0000, v219
	s_waitcnt vmcnt(12)
	v_pk_fma_f32 v[62:63], v[62:63], v[162:163], v[204:205]
	v_pk_fma_f32 v[60:61], v[60:61], v[160:161], v[202:203]
	global_store_dwordx4 v219, v[60:63], s[6:7] offset:0
	v_pk_fma_f32 v[58:59], v[58:59], v[166:167], v[208:209]
	v_pk_fma_f32 v[56:57], v[56:57], v[164:165], v[206:207]
	global_store_dwordx4 v219, v[56:59], s[6:7] offset:64
	v_pk_fma_f32 v[54:55], v[54:55], v[170:171], v[212:213]
	v_pk_fma_f32 v[52:53], v[52:53], v[168:169], v[210:211]
	global_store_dwordx4 v219, v[52:55], s[6:7] offset:512
	v_pk_fma_f32 v[50:51], v[50:51], v[174:175], v[216:217]
	v_pk_fma_f32 v[48:49], v[48:49], v[172:173], v[214:215]
	global_store_dwordx4 v219, v[48:51], s[6:7] offset:576
	v_lshrrev_b32_e32 v220, 1, v219
	v_mul_f32_e32 v202, v60, v186
	v_mul_f32_e32 v203, v61, v187
	v_mul_f32_e32 v204, v62, v188
	v_mul_f32_e32 v205, v63, v189
	v_mul_f32_e32 v221, v60, v60
	v_fmac_f32_e32 v221, v61, v61
	v_fmac_f32_e32 v221, v62, v62
	v_fmac_f32_e32 v221, v63, v63
	v_cvt_pk_bf16_f32 v202, v202, v203
	v_cvt_pk_bf16_f32 v203, v204, v205
	global_store_dwordx2 v220, v[202:203], s[8:9] offset:0
	v_mul_f32_e32 v206, v56, v190
	v_mul_f32_e32 v207, v57, v191
	v_mul_f32_e32 v208, v58, v192
	v_mul_f32_e32 v209, v59, v193
	v_fmac_f32_e32 v221, v56, v56
	v_fmac_f32_e32 v221, v57, v57
	v_fmac_f32_e32 v221, v58, v58
	v_fmac_f32_e32 v221, v59, v59
	v_cvt_pk_bf16_f32 v206, v206, v207
	v_cvt_pk_bf16_f32 v207, v208, v209
	global_store_dwordx2 v220, v[206:207], s[8:9] offset:32
	v_mul_f32_e32 v210, v52, v194
	v_mul_f32_e32 v211, v53, v195
	v_mul_f32_e32 v212, v54, v196
	v_mul_f32_e32 v213, v55, v197
	v_fmac_f32_e32 v221, v52, v52
	v_fmac_f32_e32 v221, v53, v53
	v_fmac_f32_e32 v221, v54, v54
	v_fmac_f32_e32 v221, v55, v55
	v_cvt_pk_bf16_f32 v210, v210, v211
	v_cvt_pk_bf16_f32 v211, v212, v213
	global_store_dwordx2 v220, v[210:211], s[8:9] offset:256
	v_mul_f32_e32 v214, v48, v198
	v_mul_f32_e32 v215, v49, v199
	v_mul_f32_e32 v216, v50, v200
	v_mul_f32_e32 v217, v51, v201
	v_fmac_f32_e32 v221, v48, v48
	v_fmac_f32_e32 v221, v49, v49
	v_fmac_f32_e32 v221, v50, v50
	v_fmac_f32_e32 v221, v51, v51
	v_cvt_pk_bf16_f32 v214, v214, v215
	v_cvt_pk_bf16_f32 v215, v216, v217
	global_store_dwordx2 v220, v[214:215], s[8:9] offset:288
	v_mov_b32_e32 v60, v221
	global_load_dwordx4 v[202:205], v218, s[40:41] offset:0
	global_load_dwordx4 v[206:209], v218, s[40:41] offset:64
	global_load_dwordx4 v[210:213], v218, s[40:41] offset:512
	global_load_dwordx4 v[214:217], v218, s[40:41] offset:576
	v_add_u32_e32 v218, 0x20000, v218
	v_add_u32_e32 v219, 0x20000, v219
	s_waitcnt vmcnt(12)
; __device__ __forceinline__ unsigned cvt_pk_bf16(float lo, float hi) { unsigned r; asm volatile("v_cvt_pk_bf16_f32 %0, %1, %2" : "=v"(r) : "v"(lo), "v"(hi)); return r; }
;     __device__ __forceinline__ void operator()(const gacc_t (&acc)[2][2][4][2], const Unit& u, int wr, int wc, int fr, int fq) const {
;     ...
;                     for (int n = 0; n < 2; ++n) { const int col = u.pn * 256 + bj * 128 + wc * 32 + n * 16 + 4 * fq;
;                         const f32x4 b = *(const f32x4*)(bp + col), g = *(const f32x4*)(gp + col); const gacc_t a = acc[ai][bj][m][n];
;                         f32x4 o; o.x = b.x + g.x * a[0]; o.y = b.y + g.y * a[1]; o.z = b.z + g.z * a[2]; o.w = b.w + g.w * a[3];
;                         *(f32x4*)(op + col) = o;
;                         if (hu) { const f32x4 gg = *(const f32x4*)(gn + col), sc = *(const f32x4*)(scl + mb * MODW + col);
;                             sq += (o.x * o.x + o.y * o.y) + (o.z * o.z + o.w * o.w);
;                             u32x2 w; w.x = pg8::cvt_pk_bf16(o.x * gg.x * (1.f + sc.x), o.y * gg.y * (1.f + sc.y)); w.y = pg8::cvt_pk_bf16(o.z * gg.z * (1.f + sc.z), o.w * gg.w * (1.f + sc.w));
;                             *(u32x2*)(hu + (size_t)row * D + col) = w; } }
	v_pk_fma_f32 v[46:47], v[46:47], v[162:163], v[144:145]
	v_pk_fma_f32 v[44:45], v[44:45], v[160:161], v[142:143]
	global_store_dwordx4 v219, v[44:47], s[6:7] offset:0
	v_pk_fma_f32 v[42:43], v[42:43], v[166:167], v[148:149]
	v_pk_fma_f32 v[40:41], v[40:41], v[164:165], v[146:147]
	global_store_dwordx4 v219, v[40:43], s[6:7] offset:64
	v_pk_fma_f32 v[38:39], v[38:39], v[170:171], v[178:179]
	v_pk_fma_f32 v[36:37], v[36:37], v[168:169], v[176:177]
	global_store_dwordx4 v219, v[36:39], s[6:7] offset:512
	v_pk_fma_f32 v[34:35], v[34:35], v[174:175], v[182:183]
	v_pk_fma_f32 v[32:33], v[32:33], v[172:173], v[180:181]
	global_store_dwordx4 v219, v[32:35], s[6:7] offset:576
	v_lshrrev_b32_e32 v220, 1, v219
	v_mul_f32_e32 v142, v44, v186
	v_mul_f32_e32 v143, v45, v187
	v_mul_f32_e32 v144, v46, v188
	v_mul_f32_e32 v145, v47, v189
	v_mul_f32_e32 v221, v44, v44
	v_fmac_f32_e32 v221, v45, v45
	v_fmac_f32_e32 v221, v46, v46
	v_fmac_f32_e32 v221, v47, v47
	v_cvt_pk_bf16_f32 v142, v142, v143
	v_cvt_pk_bf16_f32 v143, v144, v145
	global_store_dwordx2 v220, v[142:143], s[8:9] offset:0
	v_mul_f32_e32 v146, v40, v190
	v_mul_f32_e32 v147, v41, v191
	v_mul_f32_e32 v148, v42, v192
	v_mul_f32_e32 v149, v43, v193
	v_fmac_f32_e32 v221, v40, v40
	v_fmac_f32_e32 v221, v41, v41
	v_fmac_f32_e32 v221, v42, v42
	v_fmac_f32_e32 v221, v43, v43
	v_cvt_pk_bf16_f32 v146, v146, v147
	v_cvt_pk_bf16_f32 v147, v148, v149
	global_store_dwordx2 v220, v[146:147], s[8:9] offset:32
	v_mul_f32_e32 v176, v36, v194
	v_mul_f32_e32 v177, v37, v195
	v_mul_f32_e32 v178, v38, v196
	v_mul_f32_e32 v179, v39, v197
	v_fmac_f32_e32 v221, v36, v36
	v_fmac_f32_e32 v221, v37, v37
	v_fmac_f32_e32 v221, v38, v38
	v_fmac_f32_e32 v221, v39, v39
	v_cvt_pk_bf16_f32 v176, v176, v177
	v_cvt_pk_bf16_f32 v177, v178, v179
	global_store_dwordx2 v220, v[176:177], s[8:9] offset:256
	v_mul_f32_e32 v180, v32, v198
	v_mul_f32_e32 v181, v33, v199
	v_mul_f32_e32 v182, v34, v200
	v_mul_f32_e32 v183, v35, v201
	v_fmac_f32_e32 v221, v32, v32
	v_fmac_f32_e32 v221, v33, v33
	v_fmac_f32_e32 v221, v34, v34
	v_fmac_f32_e32 v221, v35, v35
	v_cvt_pk_bf16_f32 v180, v180, v181
	v_cvt_pk_bf16_f32 v181, v182, v183
	global_store_dwordx2 v220, v[180:181], s[8:9] offset:288
	v_mov_b32_e32 v44, v221
	global_load_dwordx4 v[142:145], v218, s[40:41] offset:0
	global_load_dwordx4 v[146:149], v218, s[40:41] offset:64
	global_load_dwordx4 v[176:179], v218, s[40:41] offset:512
	global_load_dwordx4 v[180:183], v218, s[40:41] offset:576
	v_add_u32_e32 v219, 0x20000, v219
	s_waitcnt vmcnt(12)
	v_pk_fma_f32 v[30:31], v[30:31], v[162:163], v[204:205]
	v_pk_fma_f32 v[28:29], v[28:29], v[160:161], v[202:203]
	global_store_dwordx4 v219, v[28:31], s[6:7] offset:0
	v_pk_fma_f32 v[26:27], v[26:27], v[166:167], v[208:209]
	v_pk_fma_f32 v[24:25], v[24:25], v[164:165], v[206:207]
	global_store_dwordx4 v219, v[24:27], s[6:7] offset:64
	v_pk_fma_f32 v[22:23], v[22:23], v[170:171], v[212:213]
	v_pk_fma_f32 v[20:21], v[20:21], v[168:169], v[210:211]
	global_store_dwordx4 v219, v[20:23], s[6:7] offset:512
	v_pk_fma_f32 v[18:19], v[18:19], v[174:175], v[216:217]
	v_pk_fma_f32 v[16:17], v[16:17], v[172:173], v[214:215]
	global_store_dwordx4 v219, v[16:19], s[6:7] offset:576
	v_lshrrev_b32_e32 v220, 1, v219
	v_mul_f32_e32 v202, v28, v186
	v_mul_f32_e32 v203, v29, v187
	v_mul_f32_e32 v204, v30, v188
	v_mul_f32_e32 v205, v31, v189
	v_mul_f32_e32 v221, v28, v28
	v_fmac_f32_e32 v221, v29, v29
	v_fmac_f32_e32 v221, v30, v30
	v_fmac_f32_e32 v221, v31, v31
	v_cvt_pk_bf16_f32 v202, v202, v203
	v_cvt_pk_bf16_f32 v203, v204, v205
	global_store_dwordx2 v220, v[202:203], s[8:9] offset:0
	v_mul_f32_e32 v206, v24, v190
	v_mul_f32_e32 v207, v25, v191
	v_mul_f32_e32 v208, v26, v192
	v_mul_f32_e32 v209, v27, v193
	v_fmac_f32_e32 v221, v24, v24
	v_fmac_f32_e32 v221, v25, v25
	v_fmac_f32_e32 v221, v26, v26
	v_fmac_f32_e32 v221, v27, v27
	v_cvt_pk_bf16_f32 v206, v206, v207
	v_cvt_pk_bf16_f32 v207, v208, v209
	global_store_dwordx2 v220, v[206:207], s[8:9] offset:32
	v_mul_f32_e32 v210, v20, v194
	v_mul_f32_e32 v211, v21, v195
	v_mul_f32_e32 v212, v22, v196
	v_mul_f32_e32 v213, v23, v197
	v_fmac_f32_e32 v221, v20, v20
	v_fmac_f32_e32 v221, v21, v21
	v_fmac_f32_e32 v221, v22, v22
	v_fmac_f32_e32 v221, v23, v23
	v_cvt_pk_bf16_f32 v210, v210, v211
	v_cvt_pk_bf16_f32 v211, v212, v213
	global_store_dwordx2 v220, v[210:211], s[8:9] offset:256
	v_mul_f32_e32 v214, v16, v198
	v_mul_f32_e32 v215, v17, v199
	v_mul_f32_e32 v216, v18, v200
	v_mul_f32_e32 v217, v19, v201
	v_fmac_f32_e32 v221, v16, v16
	v_fmac_f32_e32 v221, v17, v17
	v_fmac_f32_e32 v221, v18, v18
	v_fmac_f32_e32 v221, v19, v19
	v_cvt_pk_bf16_f32 v214, v214, v215
	v_cvt_pk_bf16_f32 v215, v216, v217
	global_store_dwordx2 v220, v[214:215], s[8:9] offset:288
	v_mov_b32_e32 v28, v221
	v_add_u32_e32 v219, 0x20000, v219
	s_waitcnt vmcnt(8)
; __device__ __forceinline__ unsigned cvt_pk_bf16(float lo, float hi) { unsigned r; asm volatile("v_cvt_pk_bf16_f32 %0, %1, %2" : "=v"(r) : "v"(lo), "v"(hi)); return r; }
;     __device__ __forceinline__ void operator()(const gacc_t (&acc)[2][2][4][2], const Unit& u, int wr, int wc, int fr, int fq) const {
;     ...
;                     for (int n = 0; n < 2; ++n) { const int col = u.pn * 256 + bj * 128 + wc * 32 + n * 16 + 4 * fq;
;                         const f32x4 b = *(const f32x4*)(bp + col), g = *(const f32x4*)(gp + col); const gacc_t a = acc[ai][bj][m][n];
;                         f32x4 o; o.x = b.x + g.x * a[0]; o.y = b.y + g.y * a[1]; o.z = b.z + g.z * a[2]; o.w = b.w + g.w * a[3];
;                         *(f32x4*)(op + col) = o;
;                         if (hu) { const f32x4 gg = *(const f32x4*)(gn + col), sc = *(const f32x4*)(scl + mb * MODW + col);
;                             sq += (o.x * o.x + o.y * o.y) + (o.z * o.z + o.w * o.w);
;                             u32x2 w; w.x = pg8::cvt_pk_bf16(o.x * gg.x * (1.f + sc.x), o.y * gg.y * (1.f + sc.y)); w.y = pg8::cvt_pk_bf16(o.z * gg.z * (1.f + sc.z), o.w * gg.w * (1.f + sc.w));
;                             *(u32x2*)(hu + (size_t)row * D + col) = w; } }
;                 if (hu) { sq += __shfl_xor(sq, 16); sq += __shfl_xor(sq, 32); if (fq == 0) __hip_atomic_fetch_add(ss + row, sq, __ATOMIC_RELAXED, __HIP_MEMORY_SCOPE_AGENT); } }
	v_pk_fma_f32 v[14:15], v[14:15], v[162:163], v[144:145]
	v_pk_fma_f32 v[12:13], v[12:13], v[160:161], v[142:143]
	global_store_dwordx4 v219, v[12:15], s[6:7] offset:0
	v_pk_fma_f32 v[10:11], v[10:11], v[166:167], v[148:149]
	v_pk_fma_f32 v[8:9], v[8:9], v[164:165], v[146:147]
	global_store_dwordx4 v219, v[8:11], s[6:7] offset:64
	v_pk_fma_f32 v[6:7], v[6:7], v[170:171], v[178:179]
	v_pk_fma_f32 v[4:5], v[4:5], v[168:169], v[176:177]
	global_store_dwordx4 v219, v[4:7], s[6:7] offset:512
	v_pk_fma_f32 v[2:3], v[2:3], v[174:175], v[182:183]
	v_pk_fma_f32 v[0:1], v[0:1], v[172:173], v[180:181]
	global_store_dwordx4 v219, v[0:3], s[6:7] offset:576
	v_lshrrev_b32_e32 v220, 1, v219
	v_mul_f32_e32 v142, v12, v186
	v_mul_f32_e32 v143, v13, v187
	v_mul_f32_e32 v144, v14, v188
	v_mul_f32_e32 v145, v15, v189
	v_mul_f32_e32 v221, v12, v12
	v_fmac_f32_e32 v221, v13, v13
	v_fmac_f32_e32 v221, v14, v14
	v_fmac_f32_e32 v221, v15, v15
	v_cvt_pk_bf16_f32 v142, v142, v143
	v_cvt_pk_bf16_f32 v143, v144, v145
	global_store_dwordx2 v220, v[142:143], s[8:9] offset:0
	v_mul_f32_e32 v146, v8, v190
	v_mul_f32_e32 v147, v9, v191
	v_mul_f32_e32 v148, v10, v192
	v_mul_f32_e32 v149, v11, v193
	v_fmac_f32_e32 v221, v8, v8
	v_fmac_f32_e32 v221, v9, v9
	v_fmac_f32_e32 v221, v10, v10
	v_fmac_f32_e32 v221, v11, v11
	v_cvt_pk_bf16_f32 v146, v146, v147
	v_cvt_pk_bf16_f32 v147, v148, v149
	global_store_dwordx2 v220, v[146:147], s[8:9] offset:32
	v_mul_f32_e32 v176, v4, v194
	v_mul_f32_e32 v177, v5, v195
	v_mul_f32_e32 v178, v6, v196
	v_mul_f32_e32 v179, v7, v197
	v_fmac_f32_e32 v221, v4, v4
	v_fmac_f32_e32 v221, v5, v5
	v_fmac_f32_e32 v221, v6, v6
	v_fmac_f32_e32 v221, v7, v7
	v_cvt_pk_bf16_f32 v176, v176, v177
	v_cvt_pk_bf16_f32 v177, v178, v179
	global_store_dwordx2 v220, v[176:177], s[8:9] offset:256
	v_mul_f32_e32 v180, v0, v198
	v_mul_f32_e32 v181, v1, v199
	v_mul_f32_e32 v182, v2, v200
	v_mul_f32_e32 v183, v3, v201
	v_fmac_f32_e32 v221, v0, v0
	v_fmac_f32_e32 v221, v1, v1
	v_fmac_f32_e32 v221, v2, v2
	v_fmac_f32_e32 v221, v3, v3
	v_cvt_pk_bf16_f32 v180, v180, v181
	v_cvt_pk_bf16_f32 v181, v182, v183
	global_store_dwordx2 v220, v[180:181], s[8:9] offset:288
	v_mov_b32_e32 v12, v221
	v_xor_b32_e32 v220, 16, v158
	v_lshlrev_b32_e32 v220, 2, v220
	v_xor_b32_e32 v221, 32, v158
	v_lshlrev_b32_e32 v221, 2, v221
	ds_bpermute_b32 v202, v220, v124
	ds_bpermute_b32 v203, v220, v108
	ds_bpermute_b32 v204, v220, v92
	ds_bpermute_b32 v205, v220, v76
	ds_bpermute_b32 v206, v220, v60
	ds_bpermute_b32 v207, v220, v44
	ds_bpermute_b32 v208, v220, v28
	ds_bpermute_b32 v209, v220, v12
	s_waitcnt lgkmcnt(0)
	v_add_f32_e32 v124, v124, v202
	v_add_f32_e32 v108, v108, v203
	v_add_f32_e32 v92, v92, v204
	v_add_f32_e32 v76, v76, v205
	v_add_f32_e32 v60, v60, v206
	v_add_f32_e32 v44, v44, v207
	v_add_f32_e32 v28, v28, v208
	v_add_f32_e32 v12, v12, v209
	ds_bpermute_b32 v202, v221, v124
	ds_bpermute_b32 v203, v221, v108
	ds_bpermute_b32 v204, v221, v92
	ds_bpermute_b32 v205, v221, v76
	ds_bpermute_b32 v206, v221, v60
	ds_bpermute_b32 v207, v221, v44
	ds_bpermute_b32 v208, v221, v28
	ds_bpermute_b32 v209, v221, v12
	v_add_u32_e32 v220, s27, v152
	v_lshlrev_b32_e32 v220, 2, v220
	s_waitcnt lgkmcnt(0)
	v_add_f32_e32 v124, v124, v202
	v_add_f32_e32 v108, v108, v203
	v_add_f32_e32 v92, v92, v204
	v_add_f32_e32 v76, v76, v205
	v_add_f32_e32 v60, v60, v206
	v_add_f32_e32 v44, v44, v207
	v_add_f32_e32 v28, v28, v208
	v_add_f32_e32 v12, v12, v209
	s_and_saveexec_b64 s[38:39], s[2:3]
	global_atomic_add_f32 v220, v124, s[18:19] offset:0
	global_atomic_add_f32 v220, v108, s[18:19] offset:64
	global_atomic_add_f32 v220, v92, s[18:19] offset:128
	global_atomic_add_f32 v220, v76, s[18:19] offset:192
	global_atomic_add_f32 v220, v60, s[18:19] offset:512
	global_atomic_add_f32 v220, v44, s[18:19] offset:576
	global_atomic_add_f32 v220, v28, s[18:19] offset:640
	global_atomic_add_f32 v220, v12, s[18:19] offset:704
	s_mov_b64 exec, s[38:39]
	s_andn2_b64 vcc, exec, s[4:5]
	s_mov_b64 s[4:5], -1
	s_cbranch_vccnz .LBB0_1468
	s_andn2_b64 vcc, exec, s[0:1]
	s_cbranch_vccnz .LBB0_1467
	s_barrier
	s_branch .LBB0_1467

;     __device__ __forceinline__ void operator()(const gacc_t (&acc)[2][2][4][2], const Unit& u, int wr, int wc, int fr, int fq) const {
;     ...
;             for (int m = 0; m < 4; ++m) { const int row = u.pm * 256 + ai * 128 + wr * 64 + m * 16 + fr;
;                 const float* bp = row < ML ? baseL + (size_t)row * D : baseC + (size_t)(row - ML) * D;
;                 const int mb = row < ML ? (row >> 11) : 8; const float* gp = mod + mb * MODW + chunk * D; float* op = out + (size_t)row * D;
;                 float sq = 0.f;
; #pragma unroll
;                 for (int bj = 0; bj < 2; ++bj)
; #pragma unroll
;                     for (int n = 0; n < 2; ++n) { const int col = u.pn * 256 + bj * 128 + wc * 32 + n * 16 + 4 * fq;
;                         const f32x4 b = *(const f32x4*)(bp + col), g = *(const f32x4*)(gp + col); const gacc_t a = acc[ai][bj][m][n];
;                         f32x4 o; o.x = b.x + g.x * a[0]; o.y = b.y + g.y * a[1]; o.z = b.z + g.z * a[2]; o.w = b.w + g.w * a[3];
;                         *(f32x4*)(op + col) = o;
.LBB0_1683:
	s_lshl_b32 s24, s50, 8
	s_add_i32 s24, s24, s38
	s_lshr_b32 s20, s24, 11
	s_mul_i32 s20, s20, 0xc000
	s_cmpk_gt_i32 s24, 0x3fff
	s_cselect_b32 s20, 0x60000, s20
	s_cselect_b32 s22, s8, s6
	s_cselect_b32 s23, s9, s7
	v_lshl_or_b32 v132, s49, 8, v152
	v_lshlrev_b32_e32 v132, 2, v132
	v_add_u32_e32 v222, s20, v132
	v_add_u32_e32 v223, s16, v222
	v_add_u32_e32 v220, s24, v150
	v_lshl_add_u32 v219, v220, 13, v132
	s_cselect_b32 s20, 0x8000000, 0
	s_sub_u32 s22, s22, s20
	s_subb_u32 s23, s23, 0
	v_mov_b32_e32 v218, v219
	global_load_dwordx4 v[160:163], v223, s[10:11] offset:0
	global_load_dwordx4 v[164:167], v223, s[10:11] offset:64
	global_load_dwordx4 v[168:171], v223, s[10:11] offset:512
	global_load_dwordx4 v[172:175], v223, s[10:11] offset:576
	global_load_dwordx4 v[202:205], v218, s[22:23] offset:0
	global_load_dwordx4 v[206:209], v218, s[22:23] offset:64
	global_load_dwordx4 v[210:213], v218, s[22:23] offset:512
	global_load_dwordx4 v[214:217], v218, s[22:23] offset:576
	v_add_u32_e32 v218, 0x20000, v218
	global_load_dwordx4 v[142:145], v218, s[22:23] offset:0
	global_load_dwordx4 v[146:149], v218, s[22:23] offset:64
	global_load_dwordx4 v[176:179], v218, s[22:23] offset:512
	global_load_dwordx4 v[180:183], v218, s[22:23] offset:576
	v_add_u32_e32 v218, 0x20000, v218
	s_waitcnt vmcnt(4)
	v_pk_fma_f32 v[126:127], v[126:127], v[162:163], v[204:205]
	v_pk_fma_f32 v[124:125], v[124:125], v[160:161], v[202:203]
	global_store_dwordx4 v219, v[124:127], s[6:7] offset:0
	v_pk_fma_f32 v[122:123], v[122:123], v[166:167], v[208:209]
	v_pk_fma_f32 v[120:121], v[120:121], v[164:165], v[206:207]
	global_store_dwordx4 v219, v[120:123], s[6:7] offset:64
	v_pk_fma_f32 v[118:119], v[118:119], v[170:171], v[212:213]
	v_pk_fma_f32 v[116:117], v[116:117], v[168:169], v[210:211]
	global_store_dwordx4 v219, v[116:119], s[6:7] offset:512
	v_pk_fma_f32 v[114:115], v[114:115], v[174:175], v[216:217]
	v_pk_fma_f32 v[112:113], v[112:113], v[172:173], v[214:215]
	global_store_dwordx4 v219, v[112:115], s[6:7] offset:576
	global_load_dwordx4 v[202:205], v218, s[22:23] offset:0
	global_load_dwordx4 v[206:209], v218, s[22:23] offset:64
	global_load_dwordx4 v[210:213], v218, s[22:23] offset:512
	global_load_dwordx4 v[214:217], v218, s[22:23] offset:576
	v_add_u32_e32 v218, 0x20000, v218
	v_add_u32_e32 v219, 0x20000, v219
	s_waitcnt vmcnt(8)
	v_pk_fma_f32 v[110:111], v[110:111], v[162:163], v[144:145]
	v_pk_fma_f32 v[108:109], v[108:109], v[160:161], v[142:143]
	global_store_dwordx4 v219, v[108:111], s[6:7] offset:0
	v_pk_fma_f32 v[106:107], v[106:107], v[166:167], v[148:149]
	v_pk_fma_f32 v[104:105], v[104:105], v[164:165], v[146:147]
	global_store_dwordx4 v219, v[104:107], s[6:7] offset:64
	v_pk_fma_f32 v[102:103], v[102:103], v[170:171], v[178:179]
	v_pk_fma_f32 v[100:101], v[100:101], v[168:169], v[176:177]
	global_store_dwordx4 v219, v[100:103], s[6:7] offset:512
	v_pk_fma_f32 v[98:99], v[98:99], v[174:175], v[182:183]
	v_pk_fma_f32 v[96:97], v[96:97], v[172:173], v[180:181]
	global_store_dwordx4 v219, v[96:99], s[6:7] offset:576
	global_load_dwordx4 v[142:145], v218, s[22:23] offset:0
	global_load_dwordx4 v[146:149], v218, s[22:23] offset:64
	global_load_dwordx4 v[176:179], v218, s[22:23] offset:512
	global_load_dwordx4 v[180:183], v218, s[22:23] offset:576
	v_add_u32_e32 v218, 0xa0000, v218
	v_add_u32_e32 v219, 0x20000, v219
	s_waitcnt vmcnt(8)
	v_pk_fma_f32 v[94:95], v[94:95], v[162:163], v[204:205]
	v_pk_fma_f32 v[92:93], v[92:93], v[160:161], v[202:203]
	global_store_dwordx4 v219, v[92:95], s[6:7] offset:0
	v_pk_fma_f32 v[90:91], v[90:91], v[166:167], v[208:209]
	v_pk_fma_f32 v[88:89], v[88:89], v[164:165], v[206:207]
	global_store_dwordx4 v219, v[88:91], s[6:7] offset:64
	v_pk_fma_f32 v[86:87], v[86:87], v[170:171], v[212:213]
	v_pk_fma_f32 v[84:85], v[84:85], v[168:169], v[210:211]
	global_store_dwordx4 v219, v[84:87], s[6:7] offset:512
	v_pk_fma_f32 v[82:83], v[82:83], v[174:175], v[216:217]
	v_pk_fma_f32 v[80:81], v[80:81], v[172:173], v[214:215]
	global_store_dwordx4 v219, v[80:83], s[6:7] offset:576
	global_load_dwordx4 v[202:205], v218, s[22:23] offset:0
	global_load_dwordx4 v[206:209], v218, s[22:23] offset:64
	global_load_dwordx4 v[210:213], v218, s[22:23] offset:512
	global_load_dwordx4 v[214:217], v218, s[22:23] offset:576
	v_add_u32_e32 v218, 0x20000, v218
	v_add_u32_e32 v219, 0x20000, v219
	s_waitcnt vmcnt(8)
;     __device__ __forceinline__ void operator()(const gacc_t (&acc)[2][2][4][2], const Unit& u, int wr, int wc, int fr, int fq) const {
;     ...
;                     for (int n = 0; n < 2; ++n) { const int col = u.pn * 256 + bj * 128 + wc * 32 + n * 16 + 4 * fq;
;                         const f32x4 b = *(const f32x4*)(bp + col), g = *(const f32x4*)(gp + col); const gacc_t a = acc[ai][bj][m][n];
;                         f32x4 o; o.x = b.x + g.x * a[0]; o.y = b.y + g.y * a[1]; o.z = b.z + g.z * a[2]; o.w = b.w + g.w * a[3];
;                         *(f32x4*)(op + col) = o;
	v_pk_fma_f32 v[78:79], v[78:79], v[162:163], v[144:145]
	v_pk_fma_f32 v[76:77], v[76:77], v[160:161], v[142:143]
	global_store_dwordx4 v219, v[76:79], s[6:7] offset:0
	v_pk_fma_f32 v[74:75], v[74:75], v[166:167], v[148:149]
	v_pk_fma_f32 v[72:73], v[72:73], v[164:165], v[146:147]
	global_store_dwordx4 v219, v[72:75], s[6:7] offset:64
	v_pk_fma_f32 v[70:71], v[70:71], v[170:171], v[178:179]
	v_pk_fma_f32 v[68:69], v[68:69], v[168:169], v[176:177]
	global_store_dwordx4 v219, v[68:71], s[6:7] offset:512
	v_pk_fma_f32 v[66:67], v[66:67], v[174:175], v[182:183]
	v_pk_fma_f32 v[64:65], v[64:65], v[172:173], v[180:181]
	global_store_dwordx4 v219, v[64:67], s[6:7] offset:576
	global_load_dwordx4 v[142:145], v218, s[22:23] offset:0
	global_load_dwordx4 v[146:149], v218, s[22:23] offset:64
	global_load_dwordx4 v[176:179], v218, s[22:23] offset:512
	global_load_dwordx4 v[180:183], v218, s[22:23] offset:576
	v_add_u32_e32 v218, 0x20000, v218
	v_add_u32_e32 v219, 0xa0000, v219
	s_waitcnt vmcnt(8)
	v_pk_fma_f32 v[62:63], v[62:63], v[162:163], v[204:205]
	v_pk_fma_f32 v[60:61], v[60:61], v[160:161], v[202:203]
	global_store_dwordx4 v219, v[60:63], s[6:7] offset:0
	v_pk_fma_f32 v[58:59], v[58:59], v[166:167], v[208:209]
	v_pk_fma_f32 v[56:57], v[56:57], v[164:165], v[206:207]
	global_store_dwordx4 v219, v[56:59], s[6:7] offset:64
	v_pk_fma_f32 v[54:55], v[54:55], v[170:171], v[212:213]
	v_pk_fma_f32 v[52:53], v[52:53], v[168:169], v[210:211]
	global_store_dwordx4 v219, v[52:55], s[6:7] offset:512
	v_pk_fma_f32 v[50:51], v[50:51], v[174:175], v[216:217]
	v_pk_fma_f32 v[48:49], v[48:49], v[172:173], v[214:215]
	global_store_dwordx4 v219, v[48:51], s[6:7] offset:576
	global_load_dwordx4 v[202:205], v218, s[22:23] offset:0
	global_load_dwordx4 v[206:209], v218, s[22:23] offset:64
	global_load_dwordx4 v[210:213], v218, s[22:23] offset:512
	global_load_dwordx4 v[214:217], v218, s[22:23] offset:576
	v_add_u32_e32 v218, 0x20000, v218
	v_add_u32_e32 v219, 0x20000, v219
	s_waitcnt vmcnt(8)
	v_pk_fma_f32 v[46:47], v[46:47], v[162:163], v[144:145]
	v_pk_fma_f32 v[44:45], v[44:45], v[160:161], v[142:143]
	global_store_dwordx4 v219, v[44:47], s[6:7] offset:0
	v_pk_fma_f32 v[42:43], v[42:43], v[166:167], v[148:149]
	v_pk_fma_f32 v[40:41], v[40:41], v[164:165], v[146:147]
	global_store_dwordx4 v219, v[40:43], s[6:7] offset:64
	v_pk_fma_f32 v[38:39], v[38:39], v[170:171], v[178:179]
	v_pk_fma_f32 v[36:37], v[36:37], v[168:169], v[176:177]
	global_store_dwordx4 v219, v[36:39], s[6:7] offset:512
	v_pk_fma_f32 v[34:35], v[34:35], v[174:175], v[182:183]
	v_pk_fma_f32 v[32:33], v[32:33], v[172:173], v[180:181]
	global_store_dwordx4 v219, v[32:35], s[6:7] offset:576
	global_load_dwordx4 v[142:145], v218, s[22:23] offset:0
	global_load_dwordx4 v[146:149], v218, s[22:23] offset:64
	global_load_dwordx4 v[176:179], v218, s[22:23] offset:512
	global_load_dwordx4 v[180:183], v218, s[22:23] offset:576
	v_add_u32_e32 v219, 0x20000, v219
	s_waitcnt vmcnt(8)
	v_pk_fma_f32 v[30:31], v[30:31], v[162:163], v[204:205]
	v_pk_fma_f32 v[28:29], v[28:29], v[160:161], v[202:203]
	global_store_dwordx4 v219, v[28:31], s[6:7] offset:0
	v_pk_fma_f32 v[26:27], v[26:27], v[166:167], v[208:209]
	v_pk_fma_f32 v[24:25], v[24:25], v[164:165], v[206:207]
	global_store_dwordx4 v219, v[24:27], s[6:7] offset:64
	v_pk_fma_f32 v[22:23], v[22:23], v[170:171], v[212:213]
	v_pk_fma_f32 v[20:21], v[20:21], v[168:169], v[210:211]
	global_store_dwordx4 v219, v[20:23], s[6:7] offset:512
	v_pk_fma_f32 v[18:19], v[18:19], v[174:175], v[216:217]
	v_pk_fma_f32 v[16:17], v[16:17], v[172:173], v[214:215]
	global_store_dwordx4 v219, v[16:19], s[6:7] offset:576
	v_add_u32_e32 v219, 0x20000, v219
	s_waitcnt vmcnt(4)
	v_pk_fma_f32 v[14:15], v[14:15], v[162:163], v[144:145]
	v_pk_fma_f32 v[12:13], v[12:13], v[160:161], v[142:143]
	global_store_dwordx4 v219, v[12:15], s[6:7] offset:0
	v_pk_fma_f32 v[10:11], v[10:11], v[166:167], v[148:149]
	v_pk_fma_f32 v[8:9], v[8:9], v[164:165], v[146:147]
	global_store_dwordx4 v219, v[8:11], s[6:7] offset:64
	v_pk_fma_f32 v[6:7], v[6:7], v[170:171], v[178:179]
	v_pk_fma_f32 v[4:5], v[4:5], v[168:169], v[176:177]
	global_store_dwordx4 v219, v[4:7], s[6:7] offset:512
	v_pk_fma_f32 v[2:3], v[2:3], v[174:175], v[182:183]
	v_pk_fma_f32 v[0:1], v[0:1], v[172:173], v[180:181]
	global_store_dwordx4 v219, v[0:3], s[6:7] offset:576
	s_and_b64 vcc, exec, s[2:3]
	s_mov_b64 s[2:3], -1
	s_cbranch_vccnz .LBB0_1668
	s_andn2_b64 vcc, exec, s[0:1]
	s_cbranch_vccnz .LBB0_1667
	s_barrier
	s_branch .LBB0_1667
